# v26 + redundant back-to-back s_setprio 0/1 pairs inside K-loop MFMA segments deleted
# speedup vs baseline: 1.0023x; 1.0018x over previous
;     __device__ bool next(int i, Unit& u) const { const int L = i * G + c; if (L >= 33 * 16) return false; const int pnv = L & 15, pm = L >> 4; u.pm = (pnv >> 1) * 33 + pm; u.pn = pnv; return true; }
;     __device__ bool next(int i, Unit& u) const { const int L = i * G + c; if (L >= npn * nsl) return false; u.pm = 32; u.pn = L % npn; u.k0 = (L / npn) * 256; return true; }
; #define PG8_STAGE(bufoff, gbase, voff) do { _Pragma("unroll") for (int _i = 0; _i < 2; ++_i) \
;         __builtin_amdgcn_global_load_lds((const unsigned*)((const char*)(gbase) + (voff)[_i]), (PG8_LAS unsigned*)(lds + (bufoff) + ldsw + _i * 8192), 16, 0, 0); } while (0)
; #define PG8_LDA(dst, b, h) do { _Pragma("unroll") for (int m = 0; m < 4; ++m) _Pragma("unroll") for (int k = 0; k < 2; ++k) dst[m][k] = *(const PG8_LAS bf16x8*)(lds + PG8_SA(b, h) + aoff + m * 2048 + k * 1024); } while (0)
; #define PG8_WAIT_V(n) asm volatile("s_waitcnt vmcnt(" #n ")" ::: "memory")
; template <class Epi, class Sched, bool ALIGN_EPI = false, bool SP2 = false>
; __device__ __forceinline__ void gemm_phase(PG8_LAS unsigned char* lds, const Gemm g, const Sched& S, const Epi& E) {
;     ...
;         const bool has_next = S.next(ui + 1, nxt);
;         const char* nA = has_next ? (const char*)g.A + (size_t)nxt.pm * tstep + (size_t)nxt.k0 * 2 : cA; const char* nB = has_next ? (const char*)g.Bt + (size_t)nxt.pn * tstep + (size_t)nxt.k0 * 2 : cB;
;         for (int t = 0; t < nt; t += 2) {
;             const bool last = (t == nt - 2);
;             const char* a1 = cA + (size_t)(t + 1) * kstep;
;             const char* a2 = last ? nA : cA + (size_t)(t + 2) * kstep; const char* b2 = last ? nB : cB + (size_t)(t + 2) * kstep;
;             const char* a3 = a2 + kstep; const char* b3 = b2 + kstep;
;             if (last && has_next) S.a_ready(nxt);
;             if constexpr (SP2) {
;             PG8_LDB(B0, 0, 0); PG8_LDB(B1, 0, 1); PG8_SCHED; PG8_LDA(At, 0, 0); PG8_STAGE(PG8_SA(1, 1), a1 + hstep, voffA);
;             PG8_WAIT_V(8); PG8_WAIT_L(0); PG8_BAR; PG8_MMA(0, 0, At, B0); PG8_MMA(0, 1, At, B1); PG8_BAR; PG8_SCHED;
;             PG8_LDA(At, 0, 1); PG8_STAGE(PG8_SB(0, 0), b2, voffB); PG8_STAGE(PG8_SB(0, 1), b2 + hstep, voffB); PG8_STAGE(PG8_SA(0, 0), a2, voffA);
;             PG8_WAIT_V(8); PG8_WAIT_L(0); PG8_BAR; PG8_MMA(1, 0, At, B0); PG8_MMA(1, 1, At, B1); PG8_BAR; PG8_SCHED;
.LBB0_231:
	s_add_i32 s82, s54, 2
	s_add_u32 s83, s6, 0x80
	s_addc_u32 s55, s7, 0
	s_add_i32 s86, 0, 0x10000
	s_cmp_eq_u32 s71, s54
	s_cselect_b32 s55, s29, s55
	s_cselect_b32 s54, s28, s83
	s_cselect_b32 s85, s31, s59
	s_cselect_b32 s84, s30, s58
	s_add_i32 s83, 0, 0x14000
	v_add_u32_e32 v152, s86, v163
	v_add_u32_e32 v156, s83, v163
	ds_read_b128 v[140:143], v152
	ds_read_b128 v[144:147], v152 offset:1024
	ds_read_b128 v[148:151], v152 offset:2048
	ds_read_b128 v[152:155], v152 offset:3072
	ds_read_b128 v[166:169], v156
	ds_read_b128 v[170:173], v156 offset:1024
	ds_read_b128 v[174:177], v156 offset:2048
	ds_read_b128 v[194:197], v156 offset:3072
	v_lshl_add_u64 v[156:157], s[6:7], 0, v[136:137]
	s_add_i32 m0, s47, 0xc000
	ds_read_b128 v[198:201], v165
	ds_read_b128 v[202:205], v165 offset:1024
	ds_read_b128 v[206:209], v165 offset:2048
	ds_read_b128 v[210:213], v165 offset:3072
	ds_read_b128 v[214:217], v165 offset:4096
	ds_read_b128 v[234:237], v165 offset:5120
	ds_read_b128 v[238:241], v165 offset:6144
	ds_read_b128 v[242:245], v165 offset:7168
	global_load_lds_dwordx4 v[156:157], off
	v_lshl_add_u64 v[156:157], s[6:7], 0, v[138:139]
	s_add_i32 m0, s47, 0xe000
	s_nop 0
	global_load_lds_dwordx4 v[156:157], off
	s_waitcnt vmcnt(8)
	s_waitcnt lgkmcnt(0)
	s_barrier
	s_setprio 1
	s_waitcnt lgkmcnt(0)
	v_mfma_f32_16x16x32_bf16 v[122:125], v[140:143], v[198:201], v[122:125]
	v_mfma_f32_16x16x32_bf16 v[114:117], v[148:151], v[198:201], v[114:117]
	v_mfma_f32_16x16x32_bf16 v[106:109], v[140:143], v[206:209], v[106:109]
	v_mfma_f32_16x16x32_bf16 v[98:101], v[148:151], v[206:209], v[98:101]
	v_mfma_f32_16x16x32_bf16 v[90:93], v[140:143], v[214:217], v[90:93]
	v_mfma_f32_16x16x32_bf16 v[82:85], v[148:151], v[214:217], v[82:85]
	v_mfma_f32_16x16x32_bf16 v[74:77], v[140:143], v[238:241], v[74:77]
	v_mfma_f32_16x16x32_bf16 v[66:69], v[148:151], v[238:241], v[66:69]
	v_mfma_f32_16x16x32_bf16 v[122:125], v[144:147], v[202:205], v[122:125]
	v_mfma_f32_16x16x32_bf16 v[114:117], v[152:155], v[202:205], v[114:117]
	v_mfma_f32_16x16x32_bf16 v[106:109], v[144:147], v[210:213], v[106:109]
	v_mfma_f32_16x16x32_bf16 v[98:101], v[152:155], v[210:213], v[98:101]
	v_mfma_f32_16x16x32_bf16 v[90:93], v[144:147], v[234:237], v[90:93]
	v_mfma_f32_16x16x32_bf16 v[82:85], v[152:155], v[234:237], v[82:85]
	v_mfma_f32_16x16x32_bf16 v[74:77], v[144:147], v[242:245], v[74:77]
	v_mfma_f32_16x16x32_bf16 v[66:69], v[152:155], v[242:245], v[66:69]
	v_mfma_f32_16x16x32_bf16 v[126:129], v[166:169], v[198:201], v[126:129]
	v_mfma_f32_16x16x32_bf16 v[118:121], v[174:177], v[198:201], v[118:121]
	v_mfma_f32_16x16x32_bf16 v[110:113], v[166:169], v[206:209], v[110:113]
	v_mfma_f32_16x16x32_bf16 v[102:105], v[174:177], v[206:209], v[102:105]
	v_mfma_f32_16x16x32_bf16 v[94:97], v[166:169], v[214:217], v[94:97]
	v_mfma_f32_16x16x32_bf16 v[86:89], v[174:177], v[214:217], v[86:89]
	v_mfma_f32_16x16x32_bf16 v[78:81], v[166:169], v[238:241], v[78:81]
	v_mfma_f32_16x16x32_bf16 v[70:73], v[174:177], v[238:241], v[70:73]
	v_mfma_f32_16x16x32_bf16 v[126:129], v[170:173], v[202:205], v[126:129]
	v_mfma_f32_16x16x32_bf16 v[118:121], v[194:197], v[202:205], v[118:121]
	v_mfma_f32_16x16x32_bf16 v[110:113], v[170:173], v[210:213], v[110:113]
	v_mfma_f32_16x16x32_bf16 v[102:105], v[194:197], v[210:213], v[102:105]
	v_mfma_f32_16x16x32_bf16 v[94:97], v[170:173], v[234:237], v[94:97]
	v_mfma_f32_16x16x32_bf16 v[86:89], v[194:197], v[234:237], v[86:89]
	v_mfma_f32_16x16x32_bf16 v[78:81], v[170:173], v[242:245], v[78:81]
	v_mfma_f32_16x16x32_bf16 v[70:73], v[194:197], v[242:245], v[70:73]
	s_setprio 0
	s_barrier
	s_add_i32 s86, s86, s45
	v_lshl_add_u64 v[156:157], s[84:85], 0, v[0:1]
	s_mov_b32 m0, s86
	ds_read_b128 v[198:201], v165 offset:16384
	ds_read_b128 v[202:205], v165 offset:17408
	ds_read_b128 v[206:209], v165 offset:18432
	ds_read_b128 v[210:213], v165 offset:19456
	ds_read_b128 v[214:217], v165 offset:20480
	ds_read_b128 v[234:237], v165 offset:21504
	ds_read_b128 v[238:241], v165 offset:22528
	ds_read_b128 v[242:245], v165 offset:23552
	global_load_lds_dwordx4 v[156:157], off
	s_add_i32 m0, s86, 0x2000
	v_lshl_add_u64 v[246:247], s[84:85], 0, v[134:135]
	s_add_u32 s84, s84, s8
	s_addc_u32 s85, s85, s9
	s_add_i32 s83, s83, s45
	global_load_lds_dwordx4 v[246:247], off
	v_lshl_add_u64 v[248:249], s[84:85], 0, v[0:1]
	s_mov_b32 m0, s83
	v_lshl_add_u64 v[250:251], s[84:85], 0, v[134:135]
	global_load_lds_dwordx4 v[248:249], off
	s_add_i32 m0, s83, 0x2000
	v_lshl_add_u64 v[252:253], s[54:55], 0, v[130:131]
	global_load_lds_dwordx4 v[250:251], off
	s_mov_b32 m0, s47
	v_lshl_add_u64 v[232:233], s[54:55], 0, v[132:133]
	global_load_lds_dwordx4 v[252:253], off
	s_mov_b32 m0, s56
	s_nop 0
	global_load_lds_dwordx4 v[232:233], off
	s_waitcnt vmcnt(8)
	s_waitcnt lgkmcnt(0)
	s_barrier
; #define PG8_STAGE(bufoff, gbase, voff) do { _Pragma("unroll") for (int _i = 0; _i < 2; ++_i) \
;         __builtin_amdgcn_global_load_lds((const unsigned*)((const char*)(gbase) + (voff)[_i]), (PG8_LAS unsigned*)(lds + (bufoff) + ldsw + _i * 8192), 16, 0, 0); } while (0)
; #define PG8_LDA(dst, b, h) do { _Pragma("unroll") for (int m = 0; m < 4; ++m) _Pragma("unroll") for (int k = 0; k < 2; ++k) dst[m][k] = *(const PG8_LAS bf16x8*)(lds + PG8_SA(b, h) + aoff + m * 2048 + k * 1024); } while (0)
; #define PG8_LDB(dst, b, h) do { _Pragma("unroll") for (int n = 0; n < 2; ++n) _Pragma("unroll") for (int k = 0; k < 2; ++k) dst[n][k] = *(const PG8_LAS bf16x8*)(lds + PG8_SB(b, h) + boff + n * 2048 + k * 1024); } while (0)
; #define PG8_MMA(ai, bj, At, Bt) do { __builtin_amdgcn_s_setprio(1); _Pragma("unroll") for (int m = 0; m < 4; ++m) _Pragma("unroll") for (int n = 0; n < 2; ++n) _Pragma("unroll") for (int k = 0; k < 2; ++k) \
;         acc[ai][bj][m][n] = __builtin_amdgcn_mfma_f32_16x16x32_bf16(Bt[n][k], At[m][k], acc[ai][bj][m][n], 0, 0, 0); __builtin_amdgcn_s_setprio(0); } while (0)
; #define PG8_WAIT_V(n) asm volatile("s_waitcnt vmcnt(" #n ")" ::: "memory")
; #define PG8_WAIT_L(n) asm volatile("s_waitcnt lgkmcnt(" #n ")" ::: "memory")
; #define PG8_BAR __builtin_amdgcn_s_barrier()
; #define PG8_SCHED __builtin_amdgcn_sched_barrier(0)
; template <class Epi, class Sched, bool ALIGN_EPI = false, bool SP2 = false>
; __device__ __forceinline__ void gemm_phase(PG8_LAS unsigned char* lds, const Gemm g, const Sched& S, const Epi& E) {
;     ...
;             PG8_WAIT_V(8); PG8_WAIT_L(0); PG8_BAR; PG8_MMA(1, 0, At, B0); PG8_MMA(1, 1, At, B1); PG8_BAR; PG8_SCHED;
;             PG8_LDB(B0, 1, 0); PG8_LDB(B1, 1, 1); PG8_SCHED; PG8_LDA(At, 1, 0); PG8_STAGE(PG8_SA(0, 1), a2 + hstep, voffA);
;             PG8_WAIT_V(8); PG8_WAIT_L(0); PG8_BAR; PG8_MMA(0, 0, At, B0); PG8_MMA(0, 1, At, B1); PG8_BAR; PG8_SCHED;
	s_setprio 1
	s_waitcnt lgkmcnt(0)
	v_mfma_f32_16x16x32_bf16 v[58:61], v[140:143], v[198:201], v[58:61]
	v_mfma_f32_16x16x32_bf16 v[50:53], v[148:151], v[198:201], v[50:53]
	v_mfma_f32_16x16x32_bf16 v[42:45], v[140:143], v[206:209], v[42:45]
	v_mfma_f32_16x16x32_bf16 v[34:37], v[148:151], v[206:209], v[34:37]
	v_mfma_f32_16x16x32_bf16 v[26:29], v[140:143], v[214:217], v[26:29]
	v_mfma_f32_16x16x32_bf16 v[18:21], v[148:151], v[214:217], v[18:21]
	v_mfma_f32_16x16x32_bf16 v[10:13], v[140:143], v[238:241], v[10:13]
	v_mfma_f32_16x16x32_bf16 v[6:9], v[148:151], v[238:241], v[6:9]
	v_mfma_f32_16x16x32_bf16 v[58:61], v[144:147], v[202:205], v[58:61]
	v_mfma_f32_16x16x32_bf16 v[50:53], v[152:155], v[202:205], v[50:53]
	v_mfma_f32_16x16x32_bf16 v[42:45], v[144:147], v[210:213], v[42:45]
	v_mfma_f32_16x16x32_bf16 v[34:37], v[152:155], v[210:213], v[34:37]
	v_mfma_f32_16x16x32_bf16 v[26:29], v[144:147], v[234:237], v[26:29]
	v_mfma_f32_16x16x32_bf16 v[18:21], v[152:155], v[234:237], v[18:21]
	v_mfma_f32_16x16x32_bf16 v[10:13], v[144:147], v[242:245], v[10:13]
	v_mfma_f32_16x16x32_bf16 v[6:9], v[152:155], v[242:245], v[6:9]
	v_mfma_f32_16x16x32_bf16 v[62:65], v[166:169], v[198:201], v[62:65]
	v_mfma_f32_16x16x32_bf16 v[54:57], v[174:177], v[198:201], v[54:57]
	v_mfma_f32_16x16x32_bf16 v[46:49], v[166:169], v[206:209], v[46:49]
	v_mfma_f32_16x16x32_bf16 v[38:41], v[174:177], v[206:209], v[38:41]
	v_mfma_f32_16x16x32_bf16 v[30:33], v[166:169], v[214:217], v[30:33]
	v_mfma_f32_16x16x32_bf16 v[22:25], v[174:177], v[214:217], v[22:25]
	v_mfma_f32_16x16x32_bf16 v[14:17], v[166:169], v[238:241], v[14:17]
	v_mfma_f32_16x16x32_bf16 v[2:5], v[174:177], v[238:241], v[2:5]
	v_mfma_f32_16x16x32_bf16 v[62:65], v[170:173], v[202:205], v[62:65]
	v_mfma_f32_16x16x32_bf16 v[54:57], v[194:197], v[202:205], v[54:57]
	v_mfma_f32_16x16x32_bf16 v[46:49], v[170:173], v[210:213], v[46:49]
	v_mfma_f32_16x16x32_bf16 v[38:41], v[194:197], v[210:213], v[38:41]
	v_mfma_f32_16x16x32_bf16 v[30:33], v[170:173], v[234:237], v[30:33]
	v_mfma_f32_16x16x32_bf16 v[22:25], v[194:197], v[234:237], v[22:25]
	v_mfma_f32_16x16x32_bf16 v[14:17], v[170:173], v[242:245], v[14:17]
	v_mfma_f32_16x16x32_bf16 v[2:5], v[194:197], v[242:245], v[2:5]
	s_setprio 0
	s_barrier
	s_add_i32 s83, 0, 0x18000
	s_add_i32 s84, 0, 0x1c000
	v_add_u32_e32 v152, s83, v163
	v_add_u32_e32 v158, s84, v163
	ds_read_b128 v[140:143], v152
	ds_read_b128 v[144:147], v152 offset:1024
	ds_read_b128 v[148:151], v152 offset:2048
	ds_read_b128 v[152:155], v152 offset:3072
	ds_read_b128 v[166:169], v158
	ds_read_b128 v[170:173], v158 offset:1024
	ds_read_b128 v[174:177], v158 offset:2048
	ds_read_b128 v[194:197], v158 offset:3072
	s_add_u32 s54, s54, s8
	s_addc_u32 s55, s55, s9
	s_mov_b32 m0, s57
	v_lshl_add_u64 v[222:223], s[54:55], 0, v[130:131]
	ds_read_b128 v[198:201], v165 offset:32768
	ds_read_b128 v[202:205], v165 offset:33792
	ds_read_b128 v[206:209], v165 offset:34816
	ds_read_b128 v[210:213], v165 offset:35840
	ds_read_b128 v[214:217], v165 offset:36864
	ds_read_b128 v[234:237], v165 offset:37888
	ds_read_b128 v[238:241], v165 offset:38912
	ds_read_b128 v[242:245], v165 offset:39936
	global_load_lds_dwordx4 v[222:223], off
	v_lshl_add_u64 v[222:223], s[54:55], 0, v[132:133]
	s_mov_b32 m0, s66
	s_nop 0
	global_load_lds_dwordx4 v[222:223], off
	s_waitcnt vmcnt(8)
	s_waitcnt lgkmcnt(0)
	s_barrier
	s_setprio 1
	s_waitcnt lgkmcnt(0)
	v_mfma_f32_16x16x32_bf16 v[122:125], v[140:143], v[198:201], v[122:125]
	v_mfma_f32_16x16x32_bf16 v[114:117], v[148:151], v[198:201], v[114:117]
	v_mfma_f32_16x16x32_bf16 v[106:109], v[140:143], v[206:209], v[106:109]
	v_mfma_f32_16x16x32_bf16 v[98:101], v[148:151], v[206:209], v[98:101]
	v_mfma_f32_16x16x32_bf16 v[90:93], v[140:143], v[214:217], v[90:93]
	v_mfma_f32_16x16x32_bf16 v[82:85], v[148:151], v[214:217], v[82:85]
	v_mfma_f32_16x16x32_bf16 v[74:77], v[140:143], v[238:241], v[74:77]
	v_mfma_f32_16x16x32_bf16 v[66:69], v[148:151], v[238:241], v[66:69]
	v_mfma_f32_16x16x32_bf16 v[122:125], v[144:147], v[202:205], v[122:125]
	v_mfma_f32_16x16x32_bf16 v[114:117], v[152:155], v[202:205], v[114:117]
	v_mfma_f32_16x16x32_bf16 v[106:109], v[144:147], v[210:213], v[106:109]
	v_mfma_f32_16x16x32_bf16 v[98:101], v[152:155], v[210:213], v[98:101]
	v_mfma_f32_16x16x32_bf16 v[90:93], v[144:147], v[234:237], v[90:93]
	v_mfma_f32_16x16x32_bf16 v[82:85], v[152:155], v[234:237], v[82:85]
	v_mfma_f32_16x16x32_bf16 v[74:77], v[144:147], v[242:245], v[74:77]
	v_mfma_f32_16x16x32_bf16 v[66:69], v[152:155], v[242:245], v[66:69]
	v_mfma_f32_16x16x32_bf16 v[126:129], v[166:169], v[198:201], v[126:129]
	v_mfma_f32_16x16x32_bf16 v[118:121], v[174:177], v[198:201], v[118:121]
	v_mfma_f32_16x16x32_bf16 v[110:113], v[166:169], v[206:209], v[110:113]
	v_mfma_f32_16x16x32_bf16 v[102:105], v[174:177], v[206:209], v[102:105]
	v_mfma_f32_16x16x32_bf16 v[94:97], v[166:169], v[214:217], v[94:97]
	v_mfma_f32_16x16x32_bf16 v[86:89], v[174:177], v[214:217], v[86:89]
	v_mfma_f32_16x16x32_bf16 v[78:81], v[166:169], v[238:241], v[78:81]
	v_mfma_f32_16x16x32_bf16 v[70:73], v[174:177], v[238:241], v[70:73]
	v_mfma_f32_16x16x32_bf16 v[126:129], v[170:173], v[202:205], v[126:129]
	v_mfma_f32_16x16x32_bf16 v[118:121], v[194:197], v[202:205], v[118:121]
	v_mfma_f32_16x16x32_bf16 v[110:113], v[170:173], v[210:213], v[110:113]
	v_mfma_f32_16x16x32_bf16 v[102:105], v[194:197], v[210:213], v[102:105]
	v_mfma_f32_16x16x32_bf16 v[94:97], v[170:173], v[234:237], v[94:97]
	v_mfma_f32_16x16x32_bf16 v[86:89], v[194:197], v[234:237], v[86:89]
	v_mfma_f32_16x16x32_bf16 v[78:81], v[170:173], v[242:245], v[78:81]
	v_mfma_f32_16x16x32_bf16 v[70:73], v[194:197], v[242:245], v[70:73]
	s_setprio 0
	s_barrier
; #define PG8_STAGE(bufoff, gbase, voff) do { _Pragma("unroll") for (int _i = 0; _i < 2; ++_i) \
;         __builtin_amdgcn_global_load_lds((const unsigned*)((const char*)(gbase) + (voff)[_i]), (PG8_LAS unsigned*)(lds + (bufoff) + ldsw + _i * 8192), 16, 0, 0); } while (0)
; #define PG8_LDA(dst, b, h) do { _Pragma("unroll") for (int m = 0; m < 4; ++m) _Pragma("unroll") for (int k = 0; k < 2; ++k) dst[m][k] = *(const PG8_LAS bf16x8*)(lds + PG8_SA(b, h) + aoff + m * 2048 + k * 1024); } while (0)
; #define PG8_MMA(ai, bj, At, Bt) do { __builtin_amdgcn_s_setprio(1); _Pragma("unroll") for (int m = 0; m < 4; ++m) _Pragma("unroll") for (int n = 0; n < 2; ++n) _Pragma("unroll") for (int k = 0; k < 2; ++k) \
;         acc[ai][bj][m][n] = __builtin_amdgcn_mfma_f32_16x16x32_bf16(Bt[n][k], At[m][k], acc[ai][bj][m][n], 0, 0, 0); __builtin_amdgcn_s_setprio(0); } while (0)
; #define PG8_WAIT_V(n) asm volatile("s_waitcnt vmcnt(" #n ")" ::: "memory")
; #define PG8_WAIT_L(n) asm volatile("s_waitcnt lgkmcnt(" #n ")" ::: "memory")
; #define PG8_BAR __builtin_amdgcn_s_barrier()
; #define PG8_SCHED __builtin_amdgcn_sched_barrier(0)
; template <class Epi, class Sched, bool ALIGN_EPI = false, bool SP2 = false>
; __device__ __forceinline__ void gemm_phase(PG8_LAS unsigned char* lds, const Gemm g, const Sched& S, const Epi& E) {
;     ...
;         for (int t = 0; t < nt; t += 2) {
;             const bool last = (t == nt - 2);
;             const char* a1 = cA + (size_t)(t + 1) * kstep;
;             const char* a2 = last ? nA : cA + (size_t)(t + 2) * kstep; const char* b2 = last ? nB : cB + (size_t)(t + 2) * kstep;
;     ...
;             PG8_LDA(At, 1, 1); PG8_STAGE(PG8_SB(1, 0), b3, voffB); PG8_STAGE(PG8_SB(1, 1), b3 + hstep, voffB); PG8_STAGE(PG8_SA(1, 0), a3, voffA);
;             PG8_WAIT_V(8); PG8_WAIT_L(0); PG8_BAR; PG8_MMA(1, 0, At, B0); PG8_MMA(1, 1, At, B1); PG8_BAR; PG8_SCHED;
	s_add_i32 s54, s83, s45
	v_lshl_add_u64 v[156:157], v[156:157], 0, s[52:53]
	s_mov_b32 m0, s54
	ds_read_b128 v[198:201], v165 offset:49152
	ds_read_b128 v[202:205], v165 offset:50176
	ds_read_b128 v[206:209], v165 offset:51200
	ds_read_b128 v[210:213], v165 offset:52224
	ds_read_b128 v[214:217], v165 offset:53248
	ds_read_b128 v[234:237], v165 offset:54272
	ds_read_b128 v[238:241], v165 offset:55296
	ds_read_b128 v[242:245], v165 offset:56320
	global_load_lds_dwordx4 v[156:157], off
	v_lshl_add_u64 v[156:157], v[246:247], 0, s[52:53]
	s_add_i32 m0, s54, 0x2000
	s_add_i32 s54, s84, s45
	global_load_lds_dwordx4 v[156:157], off
	v_lshl_add_u64 v[156:157], v[248:249], 0, s[52:53]
	s_mov_b32 m0, s54
	s_nop 0
	global_load_lds_dwordx4 v[156:157], off
	v_lshl_add_u64 v[156:157], v[250:251], 0, s[52:53]
	s_add_i32 m0, s54, 0x2000
	s_nop 0
	global_load_lds_dwordx4 v[156:157], off
	v_lshl_add_u64 v[156:157], v[252:253], 0, s[52:53]
	s_mov_b32 m0, s67
	s_nop 0
	global_load_lds_dwordx4 v[156:157], off
	v_lshl_add_u64 v[156:157], v[232:233], 0, s[52:53]
	s_mov_b32 m0, s68
	s_nop 0
	global_load_lds_dwordx4 v[156:157], off
	s_waitcnt vmcnt(8)
	s_waitcnt lgkmcnt(0)
	s_barrier
	s_setprio 1
	s_waitcnt lgkmcnt(0)
	v_mfma_f32_16x16x32_bf16 v[58:61], v[140:143], v[198:201], v[58:61]
	v_mfma_f32_16x16x32_bf16 v[50:53], v[148:151], v[198:201], v[50:53]
	v_mfma_f32_16x16x32_bf16 v[42:45], v[140:143], v[206:209], v[42:45]
	v_mfma_f32_16x16x32_bf16 v[34:37], v[148:151], v[206:209], v[34:37]
	v_mfma_f32_16x16x32_bf16 v[26:29], v[140:143], v[214:217], v[26:29]
	v_mfma_f32_16x16x32_bf16 v[18:21], v[148:151], v[214:217], v[18:21]
	v_mfma_f32_16x16x32_bf16 v[10:13], v[140:143], v[238:241], v[10:13]
	v_mfma_f32_16x16x32_bf16 v[6:9], v[148:151], v[238:241], v[6:9]
	v_mfma_f32_16x16x32_bf16 v[58:61], v[144:147], v[202:205], v[58:61]
	v_mfma_f32_16x16x32_bf16 v[50:53], v[152:155], v[202:205], v[50:53]
	v_mfma_f32_16x16x32_bf16 v[42:45], v[144:147], v[210:213], v[42:45]
	v_mfma_f32_16x16x32_bf16 v[34:37], v[152:155], v[210:213], v[34:37]
	v_mfma_f32_16x16x32_bf16 v[26:29], v[144:147], v[234:237], v[26:29]
	v_mfma_f32_16x16x32_bf16 v[18:21], v[152:155], v[234:237], v[18:21]
	v_mfma_f32_16x16x32_bf16 v[10:13], v[144:147], v[242:245], v[10:13]
	v_mfma_f32_16x16x32_bf16 v[6:9], v[152:155], v[242:245], v[6:9]
	v_mfma_f32_16x16x32_bf16 v[62:65], v[166:169], v[198:201], v[62:65]
	v_mfma_f32_16x16x32_bf16 v[54:57], v[174:177], v[198:201], v[54:57]
	v_mfma_f32_16x16x32_bf16 v[46:49], v[166:169], v[206:209], v[46:49]
	v_mfma_f32_16x16x32_bf16 v[38:41], v[174:177], v[206:209], v[38:41]
	v_mfma_f32_16x16x32_bf16 v[30:33], v[166:169], v[214:217], v[30:33]
	v_mfma_f32_16x16x32_bf16 v[22:25], v[174:177], v[214:217], v[22:25]
	v_mfma_f32_16x16x32_bf16 v[14:17], v[166:169], v[238:241], v[14:17]
	v_mfma_f32_16x16x32_bf16 v[2:5], v[174:177], v[238:241], v[2:5]
	v_mfma_f32_16x16x32_bf16 v[62:65], v[170:173], v[202:205], v[62:65]
	v_mfma_f32_16x16x32_bf16 v[54:57], v[194:197], v[202:205], v[54:57]
	v_mfma_f32_16x16x32_bf16 v[46:49], v[170:173], v[210:213], v[46:49]
	v_mfma_f32_16x16x32_bf16 v[38:41], v[194:197], v[210:213], v[38:41]
	v_mfma_f32_16x16x32_bf16 v[30:33], v[170:173], v[234:237], v[30:33]
	v_mfma_f32_16x16x32_bf16 v[22:25], v[194:197], v[234:237], v[22:25]
	v_mfma_f32_16x16x32_bf16 v[14:17], v[170:173], v[242:245], v[14:17]
	v_mfma_f32_16x16x32_bf16 v[2:5], v[194:197], v[242:245], v[2:5]
	s_setprio 0
	s_barrier
	s_add_u32 s6, s6, 0x100
	s_addc_u32 s7, s7, 0
	s_add_u32 s58, s58, 0x100
	s_addc_u32 s59, s59, 0
	s_cmp_ge_i32 s82, s69
	s_mov_b32 s54, s82
	s_cbranch_scc0 .LBB0_231

;     __device__ bool next(int i, Unit& u) const { const int L = i * G + c; if (L >= 33 * 16) return false; const int pnv = L & 15, pm = L >> 4; u.pm = (pnv >> 1) * 33 + pm; u.pn = pnv; return true; }
;     __device__ bool next(int i, Unit& u) const { const int L = i * G + c; if (L >= npn * nsl) return false; u.pm = 32; u.pn = L % npn; u.k0 = (L / npn) * 256; return true; }
; #define PG8_STAGE(bufoff, gbase, voff) do { _Pragma("unroll") for (int _i = 0; _i < 2; ++_i) \
;         __builtin_amdgcn_global_load_lds((const unsigned*)((const char*)(gbase) + (voff)[_i]), (PG8_LAS unsigned*)(lds + (bufoff) + ldsw + _i * 8192), 16, 0, 0); } while (0)
; #define PG8_LDA(dst, b, h) do { _Pragma("unroll") for (int m = 0; m < 4; ++m) _Pragma("unroll") for (int k = 0; k < 2; ++k) dst[m][k] = *(const PG8_LAS bf16x8*)(lds + PG8_SA(b, h) + aoff + m * 2048 + k * 1024); } while (0)
; #define PG8_WAIT_V(n) asm volatile("s_waitcnt vmcnt(" #n ")" ::: "memory")
; template <class Epi, class Sched, bool ALIGN_EPI = false, bool SP2 = false>
; __device__ __forceinline__ void gemm_phase(PG8_LAS unsigned char* lds, const Gemm g, const Sched& S, const Epi& E) {
;     ...
;         const bool has_next = S.next(ui + 1, nxt);
;         const char* nA = has_next ? (const char*)g.A + (size_t)nxt.pm * tstep + (size_t)nxt.k0 * 2 : cA; const char* nB = has_next ? (const char*)g.Bt + (size_t)nxt.pn * tstep + (size_t)nxt.k0 * 2 : cB;
;         for (int t = 0; t < nt; t += 2) {
;             const bool last = (t == nt - 2);
;             const char* a1 = cA + (size_t)(t + 1) * kstep;
;             const char* a2 = last ? nA : cA + (size_t)(t + 2) * kstep; const char* b2 = last ? nB : cB + (size_t)(t + 2) * kstep;
;             const char* a3 = a2 + kstep; const char* b3 = b2 + kstep;
;             if (last && has_next) S.a_ready(nxt);
;             if constexpr (SP2) {
;             PG8_LDB(B0, 0, 0); PG8_LDB(B1, 0, 1); PG8_SCHED; PG8_LDA(At, 0, 0); PG8_STAGE(PG8_SA(1, 1), a1 + hstep, voffA);
;             PG8_WAIT_V(8); PG8_WAIT_L(0); PG8_BAR; PG8_MMA(0, 0, At, B0); PG8_MMA(0, 1, At, B1); PG8_BAR; PG8_SCHED;
;             PG8_LDA(At, 0, 1); PG8_STAGE(PG8_SB(0, 0), b2, voffB); PG8_STAGE(PG8_SB(0, 1), b2 + hstep, voffB); PG8_STAGE(PG8_SA(0, 0), a2, voffA);
;             PG8_WAIT_V(8); PG8_WAIT_L(0); PG8_BAR; PG8_MMA(1, 0, At, B0); PG8_MMA(1, 1, At, B1); PG8_BAR; PG8_SCHED;
.LBB0_342:
	s_add_i32 s87, s30, 2
	s_add_u32 s90, s6, 0x80
	s_addc_u32 s31, s7, 0
	s_add_i32 s92, 0, 0x10000
	s_cmp_eq_u32 s75, s30
	s_cselect_b32 s31, s23, s31
	s_cselect_b32 s30, s22, s90
	s_cselect_b32 s91, s29, s55
	s_cselect_b32 s90, s28, s54
	s_add_i32 s93, 0, 0x14000
	v_add_u32_e32 v152, s92, v234
	v_add_u32_e32 v168, s93, v234
	ds_read_b128 v[140:143], v152
	ds_read_b128 v[144:147], v152 offset:1024
	ds_read_b128 v[148:151], v152 offset:2048
	ds_read_b128 v[152:155], v152 offset:3072
	ds_read_b128 v[156:159], v168
	ds_read_b128 v[160:163], v168 offset:1024
	ds_read_b128 v[164:167], v168 offset:2048
	ds_read_b128 v[168:171], v168 offset:3072
	v_lshl_add_u64 v[176:177], s[6:7], 0, v[136:137]
	s_add_i32 m0, s56, 0xc000
	ds_read_b128 v[172:175], v235
	ds_read_b128 v[194:197], v235 offset:1024
	ds_read_b128 v[198:201], v235 offset:2048
	ds_read_b128 v[202:205], v235 offset:3072
	ds_read_b128 v[206:209], v235 offset:4096
	ds_read_b128 v[210:213], v235 offset:5120
	ds_read_b128 v[214:217], v235 offset:6144
	ds_read_b128 v[236:239], v235 offset:7168
	global_load_lds_dwordx4 v[176:177], off
	v_lshl_add_u64 v[176:177], s[6:7], 0, v[138:139]
	s_add_i32 m0, s56, 0xe000
	s_nop 0
	global_load_lds_dwordx4 v[176:177], off
	s_waitcnt vmcnt(8)
	s_waitcnt lgkmcnt(0)
	s_barrier
	s_setprio 1
	s_waitcnt lgkmcnt(0)
	v_mfma_f32_16x16x32_bf16 v[126:129], v[140:143], v[172:175], v[126:129]
	v_mfma_f32_16x16x32_bf16 v[122:125], v[148:151], v[172:175], v[122:125]
	v_mfma_f32_16x16x32_bf16 v[118:121], v[140:143], v[198:201], v[118:121]
	v_mfma_f32_16x16x32_bf16 v[114:117], v[148:151], v[198:201], v[114:117]
	v_mfma_f32_16x16x32_bf16 v[106:109], v[140:143], v[206:209], v[106:109]
	v_mfma_f32_16x16x32_bf16 v[98:101], v[148:151], v[206:209], v[98:101]
	v_mfma_f32_16x16x32_bf16 v[90:93], v[140:143], v[214:217], v[90:93]
	v_mfma_f32_16x16x32_bf16 v[82:85], v[148:151], v[214:217], v[82:85]
	v_mfma_f32_16x16x32_bf16 v[126:129], v[144:147], v[194:197], v[126:129]
	v_mfma_f32_16x16x32_bf16 v[122:125], v[152:155], v[194:197], v[122:125]
	v_mfma_f32_16x16x32_bf16 v[118:121], v[144:147], v[202:205], v[118:121]
	v_mfma_f32_16x16x32_bf16 v[114:117], v[152:155], v[202:205], v[114:117]
	v_mfma_f32_16x16x32_bf16 v[106:109], v[144:147], v[210:213], v[106:109]
	v_mfma_f32_16x16x32_bf16 v[98:101], v[152:155], v[210:213], v[98:101]
	v_mfma_f32_16x16x32_bf16 v[90:93], v[144:147], v[236:239], v[90:93]
	v_mfma_f32_16x16x32_bf16 v[82:85], v[152:155], v[236:239], v[82:85]
	v_mfma_f32_16x16x32_bf16 v[110:113], v[156:159], v[172:175], v[110:113]
	v_mfma_f32_16x16x32_bf16 v[102:105], v[164:167], v[172:175], v[102:105]
	v_mfma_f32_16x16x32_bf16 v[94:97], v[156:159], v[198:201], v[94:97]
	v_mfma_f32_16x16x32_bf16 v[86:89], v[164:167], v[198:201], v[86:89]
	v_mfma_f32_16x16x32_bf16 v[78:81], v[156:159], v[206:209], v[78:81]
	v_mfma_f32_16x16x32_bf16 v[74:77], v[164:167], v[206:209], v[74:77]
	v_mfma_f32_16x16x32_bf16 v[70:73], v[156:159], v[214:217], v[70:73]
	v_mfma_f32_16x16x32_bf16 v[66:69], v[164:167], v[214:217], v[66:69]
	v_mfma_f32_16x16x32_bf16 v[110:113], v[160:163], v[194:197], v[110:113]
	v_mfma_f32_16x16x32_bf16 v[102:105], v[168:171], v[194:197], v[102:105]
	v_mfma_f32_16x16x32_bf16 v[94:97], v[160:163], v[202:205], v[94:97]
	v_mfma_f32_16x16x32_bf16 v[86:89], v[168:171], v[202:205], v[86:89]
	v_mfma_f32_16x16x32_bf16 v[78:81], v[160:163], v[210:213], v[78:81]
	v_mfma_f32_16x16x32_bf16 v[74:77], v[168:171], v[210:213], v[74:77]
	v_mfma_f32_16x16x32_bf16 v[70:73], v[160:163], v[236:239], v[70:73]
	v_mfma_f32_16x16x32_bf16 v[66:69], v[168:171], v[236:239], v[66:69]
	s_setprio 0
	s_barrier
	s_add_i32 s92, s92, s47
	v_lshl_add_u64 v[176:177], s[90:91], 0, v[0:1]
	s_mov_b32 m0, s92
	ds_read_b128 v[172:175], v235 offset:16384
	ds_read_b128 v[194:197], v235 offset:17408
	ds_read_b128 v[198:201], v235 offset:18432
	ds_read_b128 v[202:205], v235 offset:19456
	ds_read_b128 v[206:209], v235 offset:20480
	ds_read_b128 v[210:213], v235 offset:21504
	ds_read_b128 v[214:217], v235 offset:22528
	ds_read_b128 v[236:239], v235 offset:23552
	global_load_lds_dwordx4 v[176:177], off
	s_add_i32 m0, s92, 0x2000
	v_lshl_add_u64 v[222:223], s[90:91], 0, v[134:135]
	s_add_u32 s90, s90, s8
	s_addc_u32 s91, s91, s9
	s_add_i32 s92, s93, s47
	global_load_lds_dwordx4 v[222:223], off
	v_lshl_add_u64 v[240:241], s[90:91], 0, v[0:1]
	s_mov_b32 m0, s92
	v_lshl_add_u64 v[242:243], s[90:91], 0, v[134:135]
	global_load_lds_dwordx4 v[240:241], off
	s_add_i32 m0, s92, 0x2000
	v_lshl_add_u64 v[244:245], s[30:31], 0, v[130:131]
	global_load_lds_dwordx4 v[242:243], off
	s_mov_b32 m0, s56
	v_lshl_add_u64 v[246:247], s[30:31], 0, v[132:133]
	global_load_lds_dwordx4 v[244:245], off
	s_mov_b32 m0, s57
	s_nop 0
	global_load_lds_dwordx4 v[246:247], off
	s_waitcnt vmcnt(8)
	s_waitcnt lgkmcnt(0)
	s_barrier
; #define PG8_STAGE(bufoff, gbase, voff) do { _Pragma("unroll") for (int _i = 0; _i < 2; ++_i) \
;         __builtin_amdgcn_global_load_lds((const unsigned*)((const char*)(gbase) + (voff)[_i]), (PG8_LAS unsigned*)(lds + (bufoff) + ldsw + _i * 8192), 16, 0, 0); } while (0)
; #define PG8_LDA(dst, b, h) do { _Pragma("unroll") for (int m = 0; m < 4; ++m) _Pragma("unroll") for (int k = 0; k < 2; ++k) dst[m][k] = *(const PG8_LAS bf16x8*)(lds + PG8_SA(b, h) + aoff + m * 2048 + k * 1024); } while (0)
; #define PG8_LDB(dst, b, h) do { _Pragma("unroll") for (int n = 0; n < 2; ++n) _Pragma("unroll") for (int k = 0; k < 2; ++k) dst[n][k] = *(const PG8_LAS bf16x8*)(lds + PG8_SB(b, h) + boff + n * 2048 + k * 1024); } while (0)
; #define PG8_MMA(ai, bj, At, Bt) do { __builtin_amdgcn_s_setprio(1); _Pragma("unroll") for (int m = 0; m < 4; ++m) _Pragma("unroll") for (int n = 0; n < 2; ++n) _Pragma("unroll") for (int k = 0; k < 2; ++k) \
;         acc[ai][bj][m][n] = __builtin_amdgcn_mfma_f32_16x16x32_bf16(Bt[n][k], At[m][k], acc[ai][bj][m][n], 0, 0, 0); __builtin_amdgcn_s_setprio(0); } while (0)
; #define PG8_WAIT_V(n) asm volatile("s_waitcnt vmcnt(" #n ")" ::: "memory")
; #define PG8_WAIT_L(n) asm volatile("s_waitcnt lgkmcnt(" #n ")" ::: "memory")
; #define PG8_BAR __builtin_amdgcn_s_barrier()
; #define PG8_SCHED __builtin_amdgcn_sched_barrier(0)
; template <class Epi, class Sched, bool ALIGN_EPI = false, bool SP2 = false>
; __device__ __forceinline__ void gemm_phase(PG8_LAS unsigned char* lds, const Gemm g, const Sched& S, const Epi& E) {
;     ...
;             PG8_WAIT_V(8); PG8_WAIT_L(0); PG8_BAR; PG8_MMA(1, 0, At, B0); PG8_MMA(1, 1, At, B1); PG8_BAR; PG8_SCHED;
;             PG8_LDB(B0, 1, 0); PG8_LDB(B1, 1, 1); PG8_SCHED; PG8_LDA(At, 1, 0); PG8_STAGE(PG8_SA(0, 1), a2 + hstep, voffA);
;             PG8_WAIT_V(8); PG8_WAIT_L(0); PG8_BAR; PG8_MMA(0, 0, At, B0); PG8_MMA(0, 1, At, B1); PG8_BAR; PG8_SCHED;
	s_setprio 1
	s_waitcnt lgkmcnt(0)
	v_mfma_f32_16x16x32_bf16 v[62:65], v[140:143], v[172:175], v[62:65]
	v_mfma_f32_16x16x32_bf16 v[58:61], v[148:151], v[172:175], v[58:61]
	v_mfma_f32_16x16x32_bf16 v[54:57], v[140:143], v[198:201], v[54:57]
	v_mfma_f32_16x16x32_bf16 v[50:53], v[148:151], v[198:201], v[50:53]
	v_mfma_f32_16x16x32_bf16 v[42:45], v[140:143], v[206:209], v[42:45]
	v_mfma_f32_16x16x32_bf16 v[34:37], v[148:151], v[206:209], v[34:37]
	v_mfma_f32_16x16x32_bf16 v[26:29], v[140:143], v[214:217], v[26:29]
	v_mfma_f32_16x16x32_bf16 v[18:21], v[148:151], v[214:217], v[18:21]
	v_mfma_f32_16x16x32_bf16 v[62:65], v[144:147], v[194:197], v[62:65]
	v_mfma_f32_16x16x32_bf16 v[58:61], v[152:155], v[194:197], v[58:61]
	v_mfma_f32_16x16x32_bf16 v[54:57], v[144:147], v[202:205], v[54:57]
	v_mfma_f32_16x16x32_bf16 v[50:53], v[152:155], v[202:205], v[50:53]
	v_mfma_f32_16x16x32_bf16 v[42:45], v[144:147], v[210:213], v[42:45]
	v_mfma_f32_16x16x32_bf16 v[34:37], v[152:155], v[210:213], v[34:37]
	v_mfma_f32_16x16x32_bf16 v[26:29], v[144:147], v[236:239], v[26:29]
	v_mfma_f32_16x16x32_bf16 v[18:21], v[152:155], v[236:239], v[18:21]
	v_mfma_f32_16x16x32_bf16 v[46:49], v[156:159], v[172:175], v[46:49]
	v_mfma_f32_16x16x32_bf16 v[38:41], v[164:167], v[172:175], v[38:41]
	v_mfma_f32_16x16x32_bf16 v[30:33], v[156:159], v[198:201], v[30:33]
	v_mfma_f32_16x16x32_bf16 v[22:25], v[164:167], v[198:201], v[22:25]
	v_mfma_f32_16x16x32_bf16 v[14:17], v[156:159], v[206:209], v[14:17]
	v_mfma_f32_16x16x32_bf16 v[10:13], v[164:167], v[206:209], v[10:13]
	v_mfma_f32_16x16x32_bf16 v[6:9], v[156:159], v[214:217], v[6:9]
	v_mfma_f32_16x16x32_bf16 v[2:5], v[164:167], v[214:217], v[2:5]
	v_mfma_f32_16x16x32_bf16 v[46:49], v[160:163], v[194:197], v[46:49]
	v_mfma_f32_16x16x32_bf16 v[38:41], v[168:171], v[194:197], v[38:41]
	v_mfma_f32_16x16x32_bf16 v[30:33], v[160:163], v[202:205], v[30:33]
	v_mfma_f32_16x16x32_bf16 v[22:25], v[168:171], v[202:205], v[22:25]
	v_mfma_f32_16x16x32_bf16 v[14:17], v[160:163], v[210:213], v[14:17]
	v_mfma_f32_16x16x32_bf16 v[10:13], v[168:171], v[210:213], v[10:13]
	v_mfma_f32_16x16x32_bf16 v[6:9], v[160:163], v[236:239], v[6:9]
	v_mfma_f32_16x16x32_bf16 v[2:5], v[168:171], v[236:239], v[2:5]
	s_setprio 0
	s_barrier
	s_add_i32 s90, 0, 0x18000
	s_add_i32 s91, 0, 0x1c000
	v_add_u32_e32 v152, s90, v234
	v_add_u32_e32 v168, s91, v234
	ds_read_b128 v[140:143], v152
	ds_read_b128 v[144:147], v152 offset:1024
	ds_read_b128 v[148:151], v152 offset:2048
	ds_read_b128 v[152:155], v152 offset:3072
	ds_read_b128 v[156:159], v168
	ds_read_b128 v[160:163], v168 offset:1024
	ds_read_b128 v[164:167], v168 offset:2048
	ds_read_b128 v[168:171], v168 offset:3072
	s_add_u32 s30, s30, s8
	s_addc_u32 s31, s31, s9
	s_mov_b32 m0, s58
	v_lshl_add_u64 v[248:249], s[30:31], 0, v[130:131]
	ds_read_b128 v[172:175], v235 offset:32768
	ds_read_b128 v[194:197], v235 offset:33792
	ds_read_b128 v[198:201], v235 offset:34816
	ds_read_b128 v[202:205], v235 offset:35840
	ds_read_b128 v[206:209], v235 offset:36864
	ds_read_b128 v[210:213], v235 offset:37888
	ds_read_b128 v[214:217], v235 offset:38912
	ds_read_b128 v[236:239], v235 offset:39936
	global_load_lds_dwordx4 v[248:249], off
	v_lshl_add_u64 v[248:249], s[30:31], 0, v[132:133]
	s_mov_b32 m0, s59
	s_nop 0
	global_load_lds_dwordx4 v[248:249], off
	s_waitcnt vmcnt(8)
	s_waitcnt lgkmcnt(0)
	s_barrier
	s_setprio 1
	s_waitcnt lgkmcnt(0)
	v_mfma_f32_16x16x32_bf16 v[126:129], v[140:143], v[172:175], v[126:129]
	v_mfma_f32_16x16x32_bf16 v[122:125], v[148:151], v[172:175], v[122:125]
	v_mfma_f32_16x16x32_bf16 v[118:121], v[140:143], v[198:201], v[118:121]
	v_mfma_f32_16x16x32_bf16 v[114:117], v[148:151], v[198:201], v[114:117]
	v_mfma_f32_16x16x32_bf16 v[106:109], v[140:143], v[206:209], v[106:109]
	v_mfma_f32_16x16x32_bf16 v[98:101], v[148:151], v[206:209], v[98:101]
	v_mfma_f32_16x16x32_bf16 v[90:93], v[140:143], v[214:217], v[90:93]
	v_mfma_f32_16x16x32_bf16 v[82:85], v[148:151], v[214:217], v[82:85]
	v_mfma_f32_16x16x32_bf16 v[126:129], v[144:147], v[194:197], v[126:129]
	v_mfma_f32_16x16x32_bf16 v[122:125], v[152:155], v[194:197], v[122:125]
	v_mfma_f32_16x16x32_bf16 v[118:121], v[144:147], v[202:205], v[118:121]
	v_mfma_f32_16x16x32_bf16 v[114:117], v[152:155], v[202:205], v[114:117]
	v_mfma_f32_16x16x32_bf16 v[106:109], v[144:147], v[210:213], v[106:109]
	v_mfma_f32_16x16x32_bf16 v[98:101], v[152:155], v[210:213], v[98:101]
	v_mfma_f32_16x16x32_bf16 v[90:93], v[144:147], v[236:239], v[90:93]
	v_mfma_f32_16x16x32_bf16 v[82:85], v[152:155], v[236:239], v[82:85]
	v_mfma_f32_16x16x32_bf16 v[110:113], v[156:159], v[172:175], v[110:113]
	v_mfma_f32_16x16x32_bf16 v[102:105], v[164:167], v[172:175], v[102:105]
	v_mfma_f32_16x16x32_bf16 v[94:97], v[156:159], v[198:201], v[94:97]
	v_mfma_f32_16x16x32_bf16 v[86:89], v[164:167], v[198:201], v[86:89]
	v_mfma_f32_16x16x32_bf16 v[78:81], v[156:159], v[206:209], v[78:81]
	v_mfma_f32_16x16x32_bf16 v[74:77], v[164:167], v[206:209], v[74:77]
	v_mfma_f32_16x16x32_bf16 v[70:73], v[156:159], v[214:217], v[70:73]
	v_mfma_f32_16x16x32_bf16 v[66:69], v[164:167], v[214:217], v[66:69]
	v_mfma_f32_16x16x32_bf16 v[110:113], v[160:163], v[194:197], v[110:113]
	v_mfma_f32_16x16x32_bf16 v[102:105], v[168:171], v[194:197], v[102:105]
	v_mfma_f32_16x16x32_bf16 v[94:97], v[160:163], v[202:205], v[94:97]
	v_mfma_f32_16x16x32_bf16 v[86:89], v[168:171], v[202:205], v[86:89]
	v_mfma_f32_16x16x32_bf16 v[78:81], v[160:163], v[210:213], v[78:81]
	v_mfma_f32_16x16x32_bf16 v[74:77], v[168:171], v[210:213], v[74:77]
	v_mfma_f32_16x16x32_bf16 v[70:73], v[160:163], v[236:239], v[70:73]
	v_mfma_f32_16x16x32_bf16 v[66:69], v[168:171], v[236:239], v[66:69]
	s_setprio 0
	s_barrier
; #define PG8_STAGE(bufoff, gbase, voff) do { _Pragma("unroll") for (int _i = 0; _i < 2; ++_i) \
;         __builtin_amdgcn_global_load_lds((const unsigned*)((const char*)(gbase) + (voff)[_i]), (PG8_LAS unsigned*)(lds + (bufoff) + ldsw + _i * 8192), 16, 0, 0); } while (0)
; #define PG8_LDA(dst, b, h) do { _Pragma("unroll") for (int m = 0; m < 4; ++m) _Pragma("unroll") for (int k = 0; k < 2; ++k) dst[m][k] = *(const PG8_LAS bf16x8*)(lds + PG8_SA(b, h) + aoff + m * 2048 + k * 1024); } while (0)
; #define PG8_MMA(ai, bj, At, Bt) do { __builtin_amdgcn_s_setprio(1); _Pragma("unroll") for (int m = 0; m < 4; ++m) _Pragma("unroll") for (int n = 0; n < 2; ++n) _Pragma("unroll") for (int k = 0; k < 2; ++k) \
;         acc[ai][bj][m][n] = __builtin_amdgcn_mfma_f32_16x16x32_bf16(Bt[n][k], At[m][k], acc[ai][bj][m][n], 0, 0, 0); __builtin_amdgcn_s_setprio(0); } while (0)
; #define PG8_WAIT_V(n) asm volatile("s_waitcnt vmcnt(" #n ")" ::: "memory")
; #define PG8_WAIT_L(n) asm volatile("s_waitcnt lgkmcnt(" #n ")" ::: "memory")
; #define PG8_BAR __builtin_amdgcn_s_barrier()
; #define PG8_SCHED __builtin_amdgcn_sched_barrier(0)
; template <class Epi, class Sched, bool ALIGN_EPI = false, bool SP2 = false>
; __device__ __forceinline__ void gemm_phase(PG8_LAS unsigned char* lds, const Gemm g, const Sched& S, const Epi& E) {
;     ...
;             PG8_LDA(At, 1, 1); PG8_STAGE(PG8_SB(1, 0), b3, voffB); PG8_STAGE(PG8_SB(1, 1), b3 + hstep, voffB); PG8_STAGE(PG8_SA(1, 0), a3, voffA);
;             PG8_WAIT_V(8); PG8_WAIT_L(0); PG8_BAR; PG8_MMA(1, 0, At, B0); PG8_MMA(1, 1, At, B1); PG8_BAR; PG8_SCHED;
	s_add_i32 s30, s90, s47
	v_lshl_add_u64 v[176:177], v[176:177], 0, s[52:53]
	s_mov_b32 m0, s30
	ds_read_b128 v[172:175], v235 offset:49152
	ds_read_b128 v[194:197], v235 offset:50176
	ds_read_b128 v[198:201], v235 offset:51200
	ds_read_b128 v[202:205], v235 offset:52224
	ds_read_b128 v[206:209], v235 offset:53248
	ds_read_b128 v[210:213], v235 offset:54272
	ds_read_b128 v[214:217], v235 offset:55296
	ds_read_b128 v[236:239], v235 offset:56320
	global_load_lds_dwordx4 v[176:177], off
	v_lshl_add_u64 v[176:177], v[222:223], 0, s[52:53]
	s_add_i32 m0, s30, 0x2000
	s_add_i32 s30, s91, s47
	global_load_lds_dwordx4 v[176:177], off
	v_lshl_add_u64 v[176:177], v[240:241], 0, s[52:53]
	s_mov_b32 m0, s30
	s_nop 0
	global_load_lds_dwordx4 v[176:177], off
	v_lshl_add_u64 v[176:177], v[242:243], 0, s[52:53]
	s_add_i32 m0, s30, 0x2000
	s_nop 0
	global_load_lds_dwordx4 v[176:177], off
	v_lshl_add_u64 v[176:177], v[244:245], 0, s[52:53]
	s_mov_b32 m0, s68
	s_nop 0
	global_load_lds_dwordx4 v[176:177], off
	v_lshl_add_u64 v[176:177], v[246:247], 0, s[52:53]
	s_mov_b32 m0, s69
	s_nop 0
	global_load_lds_dwordx4 v[176:177], off
	s_waitcnt vmcnt(8)
	s_waitcnt lgkmcnt(0)
	s_barrier
	s_setprio 1
	s_waitcnt lgkmcnt(0)
	v_mfma_f32_16x16x32_bf16 v[62:65], v[140:143], v[172:175], v[62:65]
	v_mfma_f32_16x16x32_bf16 v[58:61], v[148:151], v[172:175], v[58:61]
	v_mfma_f32_16x16x32_bf16 v[54:57], v[140:143], v[198:201], v[54:57]
	v_mfma_f32_16x16x32_bf16 v[50:53], v[148:151], v[198:201], v[50:53]
	v_mfma_f32_16x16x32_bf16 v[42:45], v[140:143], v[206:209], v[42:45]
	v_mfma_f32_16x16x32_bf16 v[34:37], v[148:151], v[206:209], v[34:37]
	v_mfma_f32_16x16x32_bf16 v[26:29], v[140:143], v[214:217], v[26:29]
	v_mfma_f32_16x16x32_bf16 v[18:21], v[148:151], v[214:217], v[18:21]
	v_mfma_f32_16x16x32_bf16 v[62:65], v[144:147], v[194:197], v[62:65]
	v_mfma_f32_16x16x32_bf16 v[58:61], v[152:155], v[194:197], v[58:61]
	v_mfma_f32_16x16x32_bf16 v[54:57], v[144:147], v[202:205], v[54:57]
	v_mfma_f32_16x16x32_bf16 v[50:53], v[152:155], v[202:205], v[50:53]
	v_mfma_f32_16x16x32_bf16 v[42:45], v[144:147], v[210:213], v[42:45]
	v_mfma_f32_16x16x32_bf16 v[34:37], v[152:155], v[210:213], v[34:37]
	v_mfma_f32_16x16x32_bf16 v[26:29], v[144:147], v[236:239], v[26:29]
	v_mfma_f32_16x16x32_bf16 v[18:21], v[152:155], v[236:239], v[18:21]
	v_mfma_f32_16x16x32_bf16 v[46:49], v[156:159], v[172:175], v[46:49]
	v_mfma_f32_16x16x32_bf16 v[38:41], v[164:167], v[172:175], v[38:41]
	v_mfma_f32_16x16x32_bf16 v[30:33], v[156:159], v[198:201], v[30:33]
	v_mfma_f32_16x16x32_bf16 v[22:25], v[164:167], v[198:201], v[22:25]
	v_mfma_f32_16x16x32_bf16 v[14:17], v[156:159], v[206:209], v[14:17]
	v_mfma_f32_16x16x32_bf16 v[10:13], v[164:167], v[206:209], v[10:13]
	v_mfma_f32_16x16x32_bf16 v[6:9], v[156:159], v[214:217], v[6:9]
	v_mfma_f32_16x16x32_bf16 v[2:5], v[164:167], v[214:217], v[2:5]
	v_mfma_f32_16x16x32_bf16 v[46:49], v[160:163], v[194:197], v[46:49]
	v_mfma_f32_16x16x32_bf16 v[38:41], v[168:171], v[194:197], v[38:41]
	v_mfma_f32_16x16x32_bf16 v[30:33], v[160:163], v[202:205], v[30:33]
	v_mfma_f32_16x16x32_bf16 v[22:25], v[168:171], v[202:205], v[22:25]
	v_mfma_f32_16x16x32_bf16 v[14:17], v[160:163], v[210:213], v[14:17]
	v_mfma_f32_16x16x32_bf16 v[10:13], v[168:171], v[210:213], v[10:13]
	v_mfma_f32_16x16x32_bf16 v[6:9], v[160:163], v[236:239], v[6:9]
	v_mfma_f32_16x16x32_bf16 v[2:5], v[168:171], v[236:239], v[2:5]
	s_setprio 0
	s_barrier
	s_add_u32 s6, s6, 0x100
	s_addc_u32 s7, s7, 0
	s_add_u32 s54, s54, 0x100
	s_addc_u32 s55, s55, 0
	s_cmp_ge_i32 s87, s71
	s_mov_b32 s30, s87
	s_cbranch_scc0 .LBB0_342
;     __device__ __forceinline__ void operator()(const f32x4 (&acc)[2][2][4][2], const Unit& u, int wr, int wc, int fr, int fq) const {
;     ...
;                     const f32x4 a0 = xa[m][bj][0] + acc[ai][bj][m][0] * scale, a1 = xa[m][bj][1] + acc[ai][bj][m][1] * scale;
	v_pk_mul_f32 v[202:203], v[128:129], 0.5 op_sel_hi:[1,0]
	v_pk_mul_f32 v[204:205], v[126:127], 0.5 op_sel_hi:[1,0]
	v_pk_mul_f32 v[206:207], v[124:125], 0.5 op_sel_hi:[1,0]
	v_pk_mul_f32 v[208:209], v[122:123], 0.5 op_sel_hi:[1,0]
	v_pk_mul_f32 v[210:211], v[112:113], 0.5 op_sel_hi:[1,0]
	v_pk_mul_f32 v[212:213], v[110:111], 0.5 op_sel_hi:[1,0]
	v_pk_mul_f32 v[214:215], v[104:105], 0.5 op_sel_hi:[1,0]
	v_pk_mul_f32 v[216:217], v[102:103], 0.5 op_sel_hi:[1,0]
	v_pk_mul_f32 v[196:197], v[120:121], 0.5 op_sel_hi:[1,0]
	v_pk_mul_f32 v[194:195], v[118:119], 0.5 op_sel_hi:[1,0]
	v_pk_mul_f32 v[176:177], v[116:117], 0.5 op_sel_hi:[1,0]
	v_pk_mul_f32 v[174:175], v[114:115], 0.5 op_sel_hi:[1,0]
	v_pk_mul_f32 v[172:173], v[96:97], 0.5 op_sel_hi:[1,0]
	v_pk_mul_f32 v[170:171], v[94:95], 0.5 op_sel_hi:[1,0]
	v_pk_mul_f32 v[168:169], v[88:89], 0.5 op_sel_hi:[1,0]
	v_pk_mul_f32 v[166:167], v[86:87], 0.5 op_sel_hi:[1,0]
	v_pk_mul_f32 v[164:165], v[108:109], 0.5 op_sel_hi:[1,0]
	v_pk_mul_f32 v[162:163], v[106:107], 0.5 op_sel_hi:[1,0]
	v_pk_mul_f32 v[160:161], v[100:101], 0.5 op_sel_hi:[1,0]
	v_pk_mul_f32 v[158:159], v[98:99], 0.5 op_sel_hi:[1,0]
	v_pk_mul_f32 v[156:157], v[80:81], 0.5 op_sel_hi:[1,0]
	v_pk_mul_f32 v[154:155], v[78:79], 0.5 op_sel_hi:[1,0]
	v_pk_mul_f32 v[152:153], v[76:77], 0.5 op_sel_hi:[1,0]
	v_pk_mul_f32 v[150:151], v[74:75], 0.5 op_sel_hi:[1,0]
	v_pk_mul_f32 v[148:149], v[92:93], 0.5 op_sel_hi:[1,0]
	v_pk_mul_f32 v[146:147], v[90:91], 0.5 op_sel_hi:[1,0]
	v_pk_mul_f32 v[144:145], v[84:85], 0.5 op_sel_hi:[1,0]
	v_pk_mul_f32 v[142:143], v[82:83], 0.5 op_sel_hi:[1,0]
	v_pk_mul_f32 v[140:141], v[72:73], 0.5 op_sel_hi:[1,0]
	v_pk_mul_f32 v[128:129], v[70:71], 0.5 op_sel_hi:[1,0]
	v_pk_mul_f32 v[126:127], v[68:69], 0.5 op_sel_hi:[1,0]
	v_pk_mul_f32 v[124:125], v[66:67], 0.5 op_sel_hi:[1,0]
	v_pk_mul_f32 v[116:117], v[64:65], 0.5 op_sel_hi:[1,0]
	v_pk_mul_f32 v[118:119], v[62:63], 0.5 op_sel_hi:[1,0]
	v_pk_mul_f32 v[120:121], v[60:61], 0.5 op_sel_hi:[1,0]
	v_pk_mul_f32 v[122:123], v[58:59], 0.5 op_sel_hi:[1,0]
	v_pk_mul_f32 v[114:115], v[48:49], 0.5 op_sel_hi:[1,0]
	v_pk_mul_f32 v[112:113], v[46:47], 0.5 op_sel_hi:[1,0]
	v_pk_mul_f32 v[110:111], v[40:41], 0.5 op_sel_hi:[1,0]
	v_pk_mul_f32 v[108:109], v[38:39], 0.5 op_sel_hi:[1,0]
	v_pk_mul_f32 v[104:105], v[56:57], 0.5 op_sel_hi:[1,0]
	v_pk_mul_f32 v[102:103], v[54:55], 0.5 op_sel_hi:[1,0]
	v_pk_mul_f32 v[100:101], v[52:53], 0.5 op_sel_hi:[1,0]
	v_pk_mul_f32 v[98:99], v[50:51], 0.5 op_sel_hi:[1,0]
	v_pk_mul_f32 v[96:97], v[32:33], 0.5 op_sel_hi:[1,0]
	v_pk_mul_f32 v[94:95], v[30:31], 0.5 op_sel_hi:[1,0]
	v_pk_mul_f32 v[92:93], v[24:25], 0.5 op_sel_hi:[1,0]
	v_pk_mul_f32 v[90:91], v[22:23], 0.5 op_sel_hi:[1,0]
	v_pk_mul_f32 v[88:89], v[44:45], 0.5 op_sel_hi:[1,0]
	v_pk_mul_f32 v[86:87], v[42:43], 0.5 op_sel_hi:[1,0]
	v_pk_mul_f32 v[84:85], v[36:37], 0.5 op_sel_hi:[1,0]
	v_pk_mul_f32 v[82:83], v[34:35], 0.5 op_sel_hi:[1,0]
	v_pk_mul_f32 v[80:81], v[16:17], 0.5 op_sel_hi:[1,0]
	v_pk_mul_f32 v[78:79], v[14:15], 0.5 op_sel_hi:[1,0]
	v_pk_mul_f32 v[76:77], v[12:13], 0.5 op_sel_hi:[1,0]
	v_pk_mul_f32 v[74:75], v[10:11], 0.5 op_sel_hi:[1,0]
	v_pk_mul_f32 v[72:73], v[28:29], 0.5 op_sel_hi:[1,0]
	v_pk_mul_f32 v[70:71], v[26:27], 0.5 op_sel_hi:[1,0]
	v_pk_mul_f32 v[68:69], v[20:21], 0.5 op_sel_hi:[1,0]
	v_pk_mul_f32 v[66:67], v[18:19], 0.5 op_sel_hi:[1,0]
	v_pk_mul_f32 v[64:65], v[8:9], 0.5 op_sel_hi:[1,0]
	v_pk_mul_f32 v[62:63], v[6:7], 0.5 op_sel_hi:[1,0]
	v_pk_mul_f32 v[60:61], v[4:5], 0.5 op_sel_hi:[1,0]
	v_pk_mul_f32 v[58:59], v[2:3], 0.5 op_sel_hi:[1,0]

;     __device__ bool next(int i, Unit& u) const { const int L = i * G + c; if (L >= 33 * 16) return false; const int pnv = L & 15, pm = L >> 4; u.pm = (pnv >> 1) * 33 + pm; u.pn = pnv; return true; }
;     __device__ bool next(int i, Unit& u) const { const int L = i * G + c; if (L >= npn * nsl) return false; u.pm = 32; u.pn = L % npn; u.k0 = (L / npn) * 256; return true; }
; #define PG8_STAGE(bufoff, gbase, voff) do { _Pragma("unroll") for (int _i = 0; _i < 2; ++_i) \
;         __builtin_amdgcn_global_load_lds((const unsigned*)((const char*)(gbase) + (voff)[_i]), (PG8_LAS unsigned*)(lds + (bufoff) + ldsw + _i * 8192), 16, 0, 0); } while (0)
; #define PG8_LDA(dst, b, h) do { _Pragma("unroll") for (int m = 0; m < 4; ++m) _Pragma("unroll") for (int k = 0; k < 2; ++k) dst[m][k] = *(const PG8_LAS bf16x8*)(lds + PG8_SA(b, h) + aoff + m * 2048 + k * 1024); } while (0)
; #define PG8_WAIT_V(n) asm volatile("s_waitcnt vmcnt(" #n ")" ::: "memory")
; template <class Epi, class Sched, bool ALIGN_EPI = false, bool SP2 = false>
; __device__ __forceinline__ void gemm_phase(PG8_LAS unsigned char* lds, const Gemm g, const Sched& S, const Epi& E) {
;     ...
;         const bool has_next = S.next(ui + 1, nxt);
;         const char* nA = has_next ? (const char*)g.A + (size_t)nxt.pm * tstep + (size_t)nxt.k0 * 2 : cA; const char* nB = has_next ? (const char*)g.Bt + (size_t)nxt.pn * tstep + (size_t)nxt.k0 * 2 : cB;
;         for (int t = 0; t < nt; t += 2) {
;             const bool last = (t == nt - 2);
;             const char* a1 = cA + (size_t)(t + 1) * kstep;
;             const char* a2 = last ? nA : cA + (size_t)(t + 2) * kstep; const char* b2 = last ? nB : cB + (size_t)(t + 2) * kstep;
;             const char* a3 = a2 + kstep; const char* b3 = b2 + kstep;
;             if (last && has_next) S.a_ready(nxt);
;             if constexpr (SP2) {
;             PG8_LDB(B0, 0, 0); PG8_LDB(B1, 0, 1); PG8_SCHED; PG8_LDA(At, 0, 0); PG8_STAGE(PG8_SA(1, 1), a1 + hstep, voffA);
;             PG8_WAIT_V(8); PG8_WAIT_L(0); PG8_BAR; PG8_MMA(0, 0, At, B0); PG8_MMA(0, 1, At, B1); PG8_BAR; PG8_SCHED;
;             PG8_LDA(At, 0, 1); PG8_STAGE(PG8_SB(0, 0), b2, voffB); PG8_STAGE(PG8_SB(0, 1), b2 + hstep, voffB); PG8_STAGE(PG8_SA(0, 0), a2, voffA);
;             PG8_WAIT_V(8); PG8_WAIT_L(0); PG8_BAR; PG8_MMA(1, 0, At, B0); PG8_MMA(1, 1, At, B1); PG8_BAR; PG8_SCHED;
.LBB0_378:
	s_add_i32 s78, s54, 2
	s_add_u32 s79, s30, 0x80
	s_addc_u32 s55, s31, 0
	s_add_i32 s81, 0, 0x10000
	s_cmp_eq_u32 s70, s54
	s_cselect_b32 s55, s21, s55
	s_cselect_b32 s54, s58, s79
	s_cselect_b32 s83, s23, s76
	s_cselect_b32 s82, s22, s59
	s_add_i32 s79, 0, 0x14000
	v_add_u32_e32 v92, s81, v78
	v_add_u32_e32 v108, s79, v78
	ds_read_b128 v[80:83], v92
	ds_read_b128 v[84:87], v92 offset:1024
	ds_read_b128 v[88:91], v92 offset:2048
	ds_read_b128 v[92:95], v92 offset:3072
	ds_read_b128 v[96:99], v108
	ds_read_b128 v[100:103], v108 offset:1024
	ds_read_b128 v[104:107], v108 offset:2048
	ds_read_b128 v[108:111], v108 offset:3072
	v_lshl_add_u64 v[144:145], s[30:31], 0, v[72:73]
	s_add_i32 m0, s13, 0xc000
	ds_read_b128 v[112:115], v79
	ds_read_b128 v[116:119], v79 offset:1024
	ds_read_b128 v[120:123], v79 offset:2048
	ds_read_b128 v[124:127], v79 offset:3072
	ds_read_b128 v[128:131], v79 offset:4096
	ds_read_b128 v[132:135], v79 offset:5120
	ds_read_b128 v[136:139], v79 offset:6144
	ds_read_b128 v[140:143], v79 offset:7168
	global_load_lds_dwordx4 v[144:145], off
	v_lshl_add_u64 v[144:145], s[30:31], 0, v[74:75]
	s_add_i32 m0, s13, 0xe000
	s_nop 0
	global_load_lds_dwordx4 v[144:145], off
	s_waitcnt vmcnt(8)
	s_waitcnt lgkmcnt(0)
	s_barrier
	s_setprio 1
	s_waitcnt lgkmcnt(0)
	v_mfma_f32_16x16x32_bf16 v[62:65], v[80:83], v[112:115], v[62:65]
	v_mfma_f32_16x16x32_bf16 v[58:61], v[88:91], v[112:115], v[58:61]
	v_mfma_f32_16x16x32_bf16 v[46:49], v[80:83], v[120:123], v[46:49]
	v_mfma_f32_16x16x32_bf16 v[42:45], v[88:91], v[120:123], v[42:45]
	v_mfma_f32_16x16x32_bf16 v[30:33], v[80:83], v[128:131], v[30:33]
	v_mfma_f32_16x16x32_bf16 v[26:29], v[88:91], v[128:131], v[26:29]
	v_mfma_f32_16x16x32_bf16 v[14:17], v[80:83], v[136:139], v[14:17]
	v_mfma_f32_16x16x32_bf16 v[10:13], v[88:91], v[136:139], v[10:13]
	v_mfma_f32_16x16x32_bf16 v[62:65], v[84:87], v[116:119], v[62:65]
	v_mfma_f32_16x16x32_bf16 v[58:61], v[92:95], v[116:119], v[58:61]
	v_mfma_f32_16x16x32_bf16 v[46:49], v[84:87], v[124:127], v[46:49]
	v_mfma_f32_16x16x32_bf16 v[42:45], v[92:95], v[124:127], v[42:45]
	v_mfma_f32_16x16x32_bf16 v[30:33], v[84:87], v[132:135], v[30:33]
	v_mfma_f32_16x16x32_bf16 v[26:29], v[92:95], v[132:135], v[26:29]
	v_mfma_f32_16x16x32_bf16 v[14:17], v[84:87], v[140:143], v[14:17]
	v_mfma_f32_16x16x32_bf16 v[10:13], v[92:95], v[140:143], v[10:13]
	v_mfma_f32_16x16x32_bf16 v[54:57], v[96:99], v[112:115], v[54:57]
	v_mfma_f32_16x16x32_bf16 v[50:53], v[104:107], v[112:115], v[50:53]
	v_mfma_f32_16x16x32_bf16 v[38:41], v[96:99], v[120:123], v[38:41]
	v_mfma_f32_16x16x32_bf16 v[34:37], v[104:107], v[120:123], v[34:37]
	v_mfma_f32_16x16x32_bf16 v[22:25], v[96:99], v[128:131], v[22:25]
	v_mfma_f32_16x16x32_bf16 v[18:21], v[104:107], v[128:131], v[18:21]
	v_mfma_f32_16x16x32_bf16 v[6:9], v[96:99], v[136:139], v[6:9]
	v_mfma_f32_16x16x32_bf16 v[2:5], v[104:107], v[136:139], v[2:5]
	v_mfma_f32_16x16x32_bf16 v[54:57], v[100:103], v[116:119], v[54:57]
	v_mfma_f32_16x16x32_bf16 v[50:53], v[108:111], v[116:119], v[50:53]
	v_mfma_f32_16x16x32_bf16 v[38:41], v[100:103], v[124:127], v[38:41]
	v_mfma_f32_16x16x32_bf16 v[34:37], v[108:111], v[124:127], v[34:37]
	v_mfma_f32_16x16x32_bf16 v[22:25], v[100:103], v[132:135], v[22:25]
	v_mfma_f32_16x16x32_bf16 v[18:21], v[108:111], v[132:135], v[18:21]
	v_mfma_f32_16x16x32_bf16 v[6:9], v[100:103], v[140:143], v[6:9]
	v_mfma_f32_16x16x32_bf16 v[2:5], v[108:111], v[140:143], v[2:5]
	s_setprio 0
	s_barrier
	s_add_i32 s81, s81, s35
	v_lshl_add_u64 v[144:145], s[82:83], 0, v[0:1]
	s_mov_b32 m0, s81
	v_lshl_add_u64 v[146:147], s[82:83], 0, v[66:67]
	global_load_lds_dwordx4 v[144:145], off
	s_add_i32 m0, s81, 0x2000
	s_add_u32 s82, s82, s6
	s_addc_u32 s83, s83, s7
	s_add_i32 s79, s79, s35
	global_load_lds_dwordx4 v[146:147], off
	v_lshl_add_u64 v[148:149], s[82:83], 0, v[0:1]
	s_mov_b32 m0, s79
	v_lshl_add_u64 v[150:151], s[82:83], 0, v[66:67]
	global_load_lds_dwordx4 v[148:149], off
	s_add_i32 m0, s79, 0x2000
	v_lshl_add_u64 v[152:153], s[54:55], 0, v[70:71]
	global_load_lds_dwordx4 v[150:151], off
	s_mov_b32 m0, s13
	v_lshl_add_u64 v[154:155], s[54:55], 0, v[68:69]
	global_load_lds_dwordx4 v[152:153], off
	s_mov_b32 m0, s45
	s_nop 0
	global_load_lds_dwordx4 v[154:155], off
	s_waitcnt vmcnt(8)
	s_waitcnt lgkmcnt(0)
	s_barrier
	s_setprio 1
	s_setprio 0
	s_setprio 1
	s_setprio 0
	s_barrier
; #define PG8_STAGE(bufoff, gbase, voff) do { _Pragma("unroll") for (int _i = 0; _i < 2; ++_i) \
;         __builtin_amdgcn_global_load_lds((const unsigned*)((const char*)(gbase) + (voff)[_i]), (PG8_LAS unsigned*)(lds + (bufoff) + ldsw + _i * 8192), 16, 0, 0); } while (0)
; #define PG8_LDA(dst, b, h) do { _Pragma("unroll") for (int m = 0; m < 4; ++m) _Pragma("unroll") for (int k = 0; k < 2; ++k) dst[m][k] = *(const PG8_LAS bf16x8*)(lds + PG8_SA(b, h) + aoff + m * 2048 + k * 1024); } while (0)
; #define PG8_LDB(dst, b, h) do { _Pragma("unroll") for (int n = 0; n < 2; ++n) _Pragma("unroll") for (int k = 0; k < 2; ++k) dst[n][k] = *(const PG8_LAS bf16x8*)(lds + PG8_SB(b, h) + boff + n * 2048 + k * 1024); } while (0)
; #define PG8_MMA(ai, bj, At, Bt) do { __builtin_amdgcn_s_setprio(1); _Pragma("unroll") for (int m = 0; m < 4; ++m) _Pragma("unroll") for (int n = 0; n < 2; ++n) _Pragma("unroll") for (int k = 0; k < 2; ++k) \
;         acc[ai][bj][m][n] = __builtin_amdgcn_mfma_f32_16x16x32_bf16(Bt[n][k], At[m][k], acc[ai][bj][m][n], 0, 0, 0); __builtin_amdgcn_s_setprio(0); } while (0)
; #define PG8_WAIT_V(n) asm volatile("s_waitcnt vmcnt(" #n ")" ::: "memory")
; #define PG8_WAIT_L(n) asm volatile("s_waitcnt lgkmcnt(" #n ")" ::: "memory")
; #define PG8_BAR __builtin_amdgcn_s_barrier()
; #define PG8_SCHED __builtin_amdgcn_sched_barrier(0)
; template <class Epi, class Sched, bool ALIGN_EPI = false, bool SP2 = false>
; __device__ __forceinline__ void gemm_phase(PG8_LAS unsigned char* lds, const Gemm g, const Sched& S, const Epi& E) {
;     ...
;             PG8_LDB(B0, 1, 0); PG8_LDB(B1, 1, 1); PG8_SCHED; PG8_LDA(At, 1, 0); PG8_STAGE(PG8_SA(0, 1), a2 + hstep, voffA);
;             PG8_WAIT_V(8); PG8_WAIT_L(0); PG8_BAR; PG8_MMA(0, 0, At, B0); PG8_MMA(0, 1, At, B1); PG8_BAR; PG8_SCHED;
;             PG8_LDA(At, 1, 1); PG8_STAGE(PG8_SB(1, 0), b3, voffB); PG8_STAGE(PG8_SB(1, 1), b3 + hstep, voffB); PG8_STAGE(PG8_SA(1, 0), a3, voffA);
;             PG8_WAIT_V(8); PG8_WAIT_L(0); PG8_BAR; PG8_MMA(1, 0, At, B0); PG8_MMA(1, 1, At, B1); PG8_BAR; PG8_SCHED;
	s_add_i32 s79, 0, 0x18000
	s_add_i32 s81, 0, 0x1c000
	v_add_u32_e32 v92, s79, v78
	v_add_u32_e32 v108, s81, v78
	ds_read_b128 v[80:83], v92
	ds_read_b128 v[84:87], v92 offset:1024
	ds_read_b128 v[88:91], v92 offset:2048
	ds_read_b128 v[92:95], v92 offset:3072
	ds_read_b128 v[96:99], v108
	ds_read_b128 v[100:103], v108 offset:1024
	ds_read_b128 v[104:107], v108 offset:2048
	ds_read_b128 v[108:111], v108 offset:3072
	s_add_u32 s54, s54, s6
	s_addc_u32 s55, s55, s7
	s_mov_b32 m0, s47
	v_lshl_add_u64 v[156:157], s[54:55], 0, v[70:71]
	ds_read_b128 v[112:115], v79 offset:32768
	ds_read_b128 v[116:119], v79 offset:33792
	ds_read_b128 v[120:123], v79 offset:34816
	ds_read_b128 v[124:127], v79 offset:35840
	ds_read_b128 v[128:131], v79 offset:36864
	ds_read_b128 v[132:135], v79 offset:37888
	ds_read_b128 v[136:139], v79 offset:38912
	ds_read_b128 v[140:143], v79 offset:39936
	global_load_lds_dwordx4 v[156:157], off
	v_lshl_add_u64 v[156:157], s[54:55], 0, v[68:69]
	s_mov_b32 m0, s56
	s_nop 0
	global_load_lds_dwordx4 v[156:157], off
	s_waitcnt vmcnt(8)
	s_waitcnt lgkmcnt(0)
	s_barrier
	s_setprio 1
	s_waitcnt lgkmcnt(0)
	v_mfma_f32_16x16x32_bf16 v[62:65], v[80:83], v[112:115], v[62:65]
	v_mfma_f32_16x16x32_bf16 v[58:61], v[88:91], v[112:115], v[58:61]
	v_mfma_f32_16x16x32_bf16 v[46:49], v[80:83], v[120:123], v[46:49]
	v_mfma_f32_16x16x32_bf16 v[42:45], v[88:91], v[120:123], v[42:45]
	v_mfma_f32_16x16x32_bf16 v[30:33], v[80:83], v[128:131], v[30:33]
	v_mfma_f32_16x16x32_bf16 v[26:29], v[88:91], v[128:131], v[26:29]
	v_mfma_f32_16x16x32_bf16 v[14:17], v[80:83], v[136:139], v[14:17]
	v_mfma_f32_16x16x32_bf16 v[10:13], v[88:91], v[136:139], v[10:13]
	v_mfma_f32_16x16x32_bf16 v[62:65], v[84:87], v[116:119], v[62:65]
	v_mfma_f32_16x16x32_bf16 v[58:61], v[92:95], v[116:119], v[58:61]
	v_mfma_f32_16x16x32_bf16 v[46:49], v[84:87], v[124:127], v[46:49]
	v_mfma_f32_16x16x32_bf16 v[42:45], v[92:95], v[124:127], v[42:45]
	v_mfma_f32_16x16x32_bf16 v[30:33], v[84:87], v[132:135], v[30:33]
	v_mfma_f32_16x16x32_bf16 v[26:29], v[92:95], v[132:135], v[26:29]
	v_mfma_f32_16x16x32_bf16 v[14:17], v[84:87], v[140:143], v[14:17]
	v_mfma_f32_16x16x32_bf16 v[10:13], v[92:95], v[140:143], v[10:13]
	v_mfma_f32_16x16x32_bf16 v[54:57], v[96:99], v[112:115], v[54:57]
	v_mfma_f32_16x16x32_bf16 v[50:53], v[104:107], v[112:115], v[50:53]
	v_mfma_f32_16x16x32_bf16 v[38:41], v[96:99], v[120:123], v[38:41]
	v_mfma_f32_16x16x32_bf16 v[34:37], v[104:107], v[120:123], v[34:37]
	v_mfma_f32_16x16x32_bf16 v[22:25], v[96:99], v[128:131], v[22:25]
	v_mfma_f32_16x16x32_bf16 v[18:21], v[104:107], v[128:131], v[18:21]
	v_mfma_f32_16x16x32_bf16 v[6:9], v[96:99], v[136:139], v[6:9]
	v_mfma_f32_16x16x32_bf16 v[2:5], v[104:107], v[136:139], v[2:5]
	v_mfma_f32_16x16x32_bf16 v[54:57], v[100:103], v[116:119], v[54:57]
	v_mfma_f32_16x16x32_bf16 v[50:53], v[108:111], v[116:119], v[50:53]
	v_mfma_f32_16x16x32_bf16 v[38:41], v[100:103], v[124:127], v[38:41]
	v_mfma_f32_16x16x32_bf16 v[34:37], v[108:111], v[124:127], v[34:37]
	v_mfma_f32_16x16x32_bf16 v[22:25], v[100:103], v[132:135], v[22:25]
	v_mfma_f32_16x16x32_bf16 v[18:21], v[108:111], v[132:135], v[18:21]
	v_mfma_f32_16x16x32_bf16 v[6:9], v[100:103], v[140:143], v[6:9]
	v_mfma_f32_16x16x32_bf16 v[2:5], v[108:111], v[140:143], v[2:5]
	s_setprio 0
	s_barrier
	s_add_i32 s54, s79, s35
	v_lshl_add_u64 v[80:81], v[144:145], 0, s[52:53]
	s_mov_b32 m0, s54
	s_nop 0
	global_load_lds_dwordx4 v[80:81], off
	v_lshl_add_u64 v[80:81], v[146:147], 0, s[52:53]
	s_add_i32 m0, s54, 0x2000
	s_add_i32 s54, s81, s35
	global_load_lds_dwordx4 v[80:81], off
	v_lshl_add_u64 v[80:81], v[148:149], 0, s[52:53]
	s_mov_b32 m0, s54
	s_nop 0
	global_load_lds_dwordx4 v[80:81], off
	v_lshl_add_u64 v[80:81], v[150:151], 0, s[52:53]
	s_add_i32 m0, s54, 0x2000
	s_nop 0
	global_load_lds_dwordx4 v[80:81], off
	v_lshl_add_u64 v[80:81], v[152:153], 0, s[52:53]
	s_mov_b32 m0, s66
	s_nop 0
	global_load_lds_dwordx4 v[80:81], off
	v_lshl_add_u64 v[80:81], v[154:155], 0, s[52:53]
	s_mov_b32 m0, s67
	s_nop 0
	global_load_lds_dwordx4 v[80:81], off
	s_waitcnt vmcnt(8)
	s_waitcnt lgkmcnt(0)
	s_barrier
	s_setprio 1
	s_setprio 0
	s_setprio 1
	s_setprio 0
	s_barrier
	s_add_u32 s30, s30, 0x100
	s_addc_u32 s31, s31, 0
	s_add_u32 s59, s59, 0x100
	s_addc_u32 s76, s76, 0
	s_cmp_ge_i32 s78, s68
	s_mov_b32 s54, s78
	s_cbranch_scc0 .LBB0_378

;     __device__ bool next(int i, Unit& u) const { const int L = i * G + c; if (L >= 33 * 16) return false; const int pnv = L & 15, pm = L >> 4; u.pm = (pnv >> 1) * 33 + pm; u.pn = pnv; return true; }
;     __device__ bool next(int i, Unit& u) const { const int L = i * G + c; if (L >= npn * nsl) return false; u.pm = 32; u.pn = L % npn; u.k0 = (L / npn) * 256; return true; }
; #define PG8_STAGE(bufoff, gbase, voff) do { _Pragma("unroll") for (int _i = 0; _i < 2; ++_i) \
;         __builtin_amdgcn_global_load_lds((const unsigned*)((const char*)(gbase) + (voff)[_i]), (PG8_LAS unsigned*)(lds + (bufoff) + ldsw + _i * 8192), 16, 0, 0); } while (0)
; #define PG8_LDA(dst, b, h) do { _Pragma("unroll") for (int m = 0; m < 4; ++m) _Pragma("unroll") for (int k = 0; k < 2; ++k) dst[m][k] = *(const PG8_LAS bf16x8*)(lds + PG8_SA(b, h) + aoff + m * 2048 + k * 1024); } while (0)
; #define PG8_WAIT_V(n) asm volatile("s_waitcnt vmcnt(" #n ")" ::: "memory")
; template <class Epi, class Sched, bool ALIGN_EPI = false, bool SP2 = false>
; __device__ __forceinline__ void gemm_phase(PG8_LAS unsigned char* lds, const Gemm g, const Sched& S, const Epi& E) {
;     ...
;         const bool has_next = S.next(ui + 1, nxt);
;         const char* nA = has_next ? (const char*)g.A + (size_t)nxt.pm * tstep + (size_t)nxt.k0 * 2 : cA; const char* nB = has_next ? (const char*)g.Bt + (size_t)nxt.pn * tstep + (size_t)nxt.k0 * 2 : cB;
;         for (int t = 0; t < nt; t += 2) {
;             const bool last = (t == nt - 2);
;             const char* a1 = cA + (size_t)(t + 1) * kstep;
;             const char* a2 = last ? nA : cA + (size_t)(t + 2) * kstep; const char* b2 = last ? nB : cB + (size_t)(t + 2) * kstep;
;             const char* a3 = a2 + kstep; const char* b3 = b2 + kstep;
;             if (last && has_next) S.a_ready(nxt);
;             if constexpr (SP2) {
;             PG8_LDB(B0, 0, 0); PG8_LDB(B1, 0, 1); PG8_SCHED; PG8_LDA(At, 0, 0); PG8_STAGE(PG8_SA(1, 1), a1 + hstep, voffA);
;             PG8_WAIT_V(8); PG8_WAIT_L(0); PG8_BAR; PG8_MMA(0, 0, At, B0); PG8_MMA(0, 1, At, B1); PG8_BAR; PG8_SCHED;
;             PG8_LDA(At, 0, 1); PG8_STAGE(PG8_SB(0, 0), b2, voffB); PG8_STAGE(PG8_SB(0, 1), b2 + hstep, voffB); PG8_STAGE(PG8_SA(0, 0), a2, voffA);
;             PG8_WAIT_V(8); PG8_WAIT_L(0); PG8_BAR; PG8_MMA(1, 0, At, B0); PG8_MMA(1, 1, At, B1); PG8_BAR; PG8_SCHED;
.LBB0_522:
	s_add_i32 s58, s8, 2
	s_add_u32 s59, s6, 0x80
	s_addc_u32 s9, s7, 0
	s_add_i32 s71, 0, 0x10000
	s_cmp_eq_u32 s67, s8
	s_cselect_b32 s9, s97, s9
	s_cselect_b32 s8, s96, s59
	s_cselect_b32 s69, s55, s11
	s_cselect_b32 s68, s54, s10
	s_add_i32 s59, 0, 0x14000
	v_add_u32_e32 v152, s71, v195
	v_add_u32_e32 v168, s59, v195
	ds_read_b128 v[140:143], v152
	ds_read_b128 v[144:147], v152 offset:1024
	ds_read_b128 v[148:151], v152 offset:2048
	ds_read_b128 v[152:155], v152 offset:3072
	ds_read_b128 v[156:159], v168
	ds_read_b128 v[160:163], v168 offset:1024
	ds_read_b128 v[164:167], v168 offset:2048
	ds_read_b128 v[168:171], v168 offset:3072
	v_lshl_add_u64 v[176:177], s[6:7], 0, v[136:137]
	s_add_i32 m0, s79, 0xc000
	ds_read_b128 v[172:175], v196
	ds_read_b128 v[198:201], v196 offset:1024
	ds_read_b128 v[202:205], v196 offset:2048
	ds_read_b128 v[206:209], v196 offset:3072
	ds_read_b128 v[210:213], v196 offset:4096
	ds_read_b128 v[214:217], v196 offset:5120
	ds_read_b128 v[234:237], v196 offset:6144
	ds_read_b128 v[238:241], v196 offset:7168
	global_load_lds_dwordx4 v[176:177], off
	v_lshl_add_u64 v[176:177], s[6:7], 0, v[138:139]
	s_add_i32 m0, s79, 0xe000
	s_nop 0
	global_load_lds_dwordx4 v[176:177], off
	s_waitcnt vmcnt(8)
	s_waitcnt lgkmcnt(0)
	s_barrier
	s_setprio 1
	s_waitcnt lgkmcnt(0)
	v_mfma_f32_16x16x32_bf16 v[126:129], v[140:143], v[172:175], v[126:129]
	v_mfma_f32_16x16x32_bf16 v[122:125], v[148:151], v[172:175], v[122:125]
	v_mfma_f32_16x16x32_bf16 v[110:113], v[140:143], v[202:205], v[110:113]
	v_mfma_f32_16x16x32_bf16 v[106:109], v[148:151], v[202:205], v[106:109]
	v_mfma_f32_16x16x32_bf16 v[94:97], v[140:143], v[210:213], v[94:97]
	v_mfma_f32_16x16x32_bf16 v[90:93], v[148:151], v[210:213], v[90:93]
	v_mfma_f32_16x16x32_bf16 v[78:81], v[140:143], v[234:237], v[78:81]
	v_mfma_f32_16x16x32_bf16 v[74:77], v[148:151], v[234:237], v[74:77]
	v_mfma_f32_16x16x32_bf16 v[126:129], v[144:147], v[198:201], v[126:129]
	v_mfma_f32_16x16x32_bf16 v[122:125], v[152:155], v[198:201], v[122:125]
	v_mfma_f32_16x16x32_bf16 v[110:113], v[144:147], v[206:209], v[110:113]
	v_mfma_f32_16x16x32_bf16 v[106:109], v[152:155], v[206:209], v[106:109]
	v_mfma_f32_16x16x32_bf16 v[94:97], v[144:147], v[214:217], v[94:97]
	v_mfma_f32_16x16x32_bf16 v[90:93], v[152:155], v[214:217], v[90:93]
	v_mfma_f32_16x16x32_bf16 v[78:81], v[144:147], v[238:241], v[78:81]
	v_mfma_f32_16x16x32_bf16 v[74:77], v[152:155], v[238:241], v[74:77]
	v_mfma_f32_16x16x32_bf16 v[118:121], v[156:159], v[172:175], v[118:121]
	v_mfma_f32_16x16x32_bf16 v[114:117], v[164:167], v[172:175], v[114:117]
	v_mfma_f32_16x16x32_bf16 v[102:105], v[156:159], v[202:205], v[102:105]
	v_mfma_f32_16x16x32_bf16 v[98:101], v[164:167], v[202:205], v[98:101]
	v_mfma_f32_16x16x32_bf16 v[86:89], v[156:159], v[210:213], v[86:89]
	v_mfma_f32_16x16x32_bf16 v[82:85], v[164:167], v[210:213], v[82:85]
	v_mfma_f32_16x16x32_bf16 v[70:73], v[156:159], v[234:237], v[70:73]
	v_mfma_f32_16x16x32_bf16 v[66:69], v[164:167], v[234:237], v[66:69]
	v_mfma_f32_16x16x32_bf16 v[118:121], v[160:163], v[198:201], v[118:121]
	v_mfma_f32_16x16x32_bf16 v[114:117], v[168:171], v[198:201], v[114:117]
	v_mfma_f32_16x16x32_bf16 v[102:105], v[160:163], v[206:209], v[102:105]
	v_mfma_f32_16x16x32_bf16 v[98:101], v[168:171], v[206:209], v[98:101]
	v_mfma_f32_16x16x32_bf16 v[86:89], v[160:163], v[214:217], v[86:89]
	v_mfma_f32_16x16x32_bf16 v[82:85], v[168:171], v[214:217], v[82:85]
	v_mfma_f32_16x16x32_bf16 v[70:73], v[160:163], v[238:241], v[70:73]
	v_mfma_f32_16x16x32_bf16 v[66:69], v[168:171], v[238:241], v[66:69]
	s_setprio 0
	s_barrier
	s_add_i32 s71, s71, s78
	v_lshl_add_u64 v[176:177], s[68:69], 0, v[0:1]
	s_mov_b32 m0, s71
	ds_read_b128 v[172:175], v196 offset:16384
	ds_read_b128 v[198:201], v196 offset:17408
	ds_read_b128 v[202:205], v196 offset:18432
	ds_read_b128 v[206:209], v196 offset:19456
	ds_read_b128 v[210:213], v196 offset:20480
	ds_read_b128 v[214:217], v196 offset:21504
	ds_read_b128 v[234:237], v196 offset:22528
	ds_read_b128 v[238:241], v196 offset:23552
	global_load_lds_dwordx4 v[176:177], off
	s_add_i32 m0, s71, 0x2000
	v_lshl_add_u64 v[222:223], s[68:69], 0, v[134:135]
	s_add_u32 s68, s68, s12
	s_addc_u32 s69, s69, s13
	s_add_i32 s59, s59, s78
	global_load_lds_dwordx4 v[222:223], off
	v_lshl_add_u64 v[232:233], s[68:69], 0, v[0:1]
	s_mov_b32 m0, s59
	v_lshl_add_u64 v[242:243], s[68:69], 0, v[134:135]
	global_load_lds_dwordx4 v[232:233], off
	s_add_i32 m0, s59, 0x2000
	v_lshl_add_u64 v[244:245], s[8:9], 0, v[130:131]
	global_load_lds_dwordx4 v[242:243], off
	s_mov_b32 m0, s79
	v_lshl_add_u64 v[246:247], s[8:9], 0, v[132:133]
	global_load_lds_dwordx4 v[244:245], off
	s_mov_b32 m0, s82
	s_nop 0
	global_load_lds_dwordx4 v[246:247], off
	s_waitcnt vmcnt(8)
	s_waitcnt lgkmcnt(0)
	s_barrier
; #define PG8_STAGE(bufoff, gbase, voff) do { _Pragma("unroll") for (int _i = 0; _i < 2; ++_i) \
;         __builtin_amdgcn_global_load_lds((const unsigned*)((const char*)(gbase) + (voff)[_i]), (PG8_LAS unsigned*)(lds + (bufoff) + ldsw + _i * 8192), 16, 0, 0); } while (0)
; #define PG8_LDA(dst, b, h) do { _Pragma("unroll") for (int m = 0; m < 4; ++m) _Pragma("unroll") for (int k = 0; k < 2; ++k) dst[m][k] = *(const PG8_LAS bf16x8*)(lds + PG8_SA(b, h) + aoff + m * 2048 + k * 1024); } while (0)
; #define PG8_LDB(dst, b, h) do { _Pragma("unroll") for (int n = 0; n < 2; ++n) _Pragma("unroll") for (int k = 0; k < 2; ++k) dst[n][k] = *(const PG8_LAS bf16x8*)(lds + PG8_SB(b, h) + boff + n * 2048 + k * 1024); } while (0)
; #define PG8_MMA(ai, bj, At, Bt) do { __builtin_amdgcn_s_setprio(1); _Pragma("unroll") for (int m = 0; m < 4; ++m) _Pragma("unroll") for (int n = 0; n < 2; ++n) _Pragma("unroll") for (int k = 0; k < 2; ++k) \
;         acc[ai][bj][m][n] = __builtin_amdgcn_mfma_f32_16x16x32_bf16(Bt[n][k], At[m][k], acc[ai][bj][m][n], 0, 0, 0); __builtin_amdgcn_s_setprio(0); } while (0)
; #define PG8_WAIT_V(n) asm volatile("s_waitcnt vmcnt(" #n ")" ::: "memory")
; #define PG8_WAIT_L(n) asm volatile("s_waitcnt lgkmcnt(" #n ")" ::: "memory")
; #define PG8_BAR __builtin_amdgcn_s_barrier()
; #define PG8_SCHED __builtin_amdgcn_sched_barrier(0)
; template <class Epi, class Sched, bool ALIGN_EPI = false, bool SP2 = false>
; __device__ __forceinline__ void gemm_phase(PG8_LAS unsigned char* lds, const Gemm g, const Sched& S, const Epi& E) {
;     ...
;             PG8_WAIT_V(8); PG8_WAIT_L(0); PG8_BAR; PG8_MMA(1, 0, At, B0); PG8_MMA(1, 1, At, B1); PG8_BAR; PG8_SCHED;
;             PG8_LDB(B0, 1, 0); PG8_LDB(B1, 1, 1); PG8_SCHED; PG8_LDA(At, 1, 0); PG8_STAGE(PG8_SA(0, 1), a2 + hstep, voffA);
;             PG8_WAIT_V(8); PG8_WAIT_L(0); PG8_BAR; PG8_MMA(0, 0, At, B0); PG8_MMA(0, 1, At, B1); PG8_BAR; PG8_SCHED;
	s_setprio 1
	s_waitcnt lgkmcnt(0)
	v_mfma_f32_16x16x32_bf16 v[62:65], v[140:143], v[172:175], v[62:65]
	v_mfma_f32_16x16x32_bf16 v[58:61], v[148:151], v[172:175], v[58:61]
	v_mfma_f32_16x16x32_bf16 v[46:49], v[140:143], v[202:205], v[46:49]
	v_mfma_f32_16x16x32_bf16 v[42:45], v[148:151], v[202:205], v[42:45]
	v_mfma_f32_16x16x32_bf16 v[30:33], v[140:143], v[210:213], v[30:33]
	v_mfma_f32_16x16x32_bf16 v[26:29], v[148:151], v[210:213], v[26:29]
	v_mfma_f32_16x16x32_bf16 v[14:17], v[140:143], v[234:237], v[14:17]
	v_mfma_f32_16x16x32_bf16 v[10:13], v[148:151], v[234:237], v[10:13]
	v_mfma_f32_16x16x32_bf16 v[62:65], v[144:147], v[198:201], v[62:65]
	v_mfma_f32_16x16x32_bf16 v[58:61], v[152:155], v[198:201], v[58:61]
	v_mfma_f32_16x16x32_bf16 v[46:49], v[144:147], v[206:209], v[46:49]
	v_mfma_f32_16x16x32_bf16 v[42:45], v[152:155], v[206:209], v[42:45]
	v_mfma_f32_16x16x32_bf16 v[30:33], v[144:147], v[214:217], v[30:33]
	v_mfma_f32_16x16x32_bf16 v[26:29], v[152:155], v[214:217], v[26:29]
	v_mfma_f32_16x16x32_bf16 v[14:17], v[144:147], v[238:241], v[14:17]
	v_mfma_f32_16x16x32_bf16 v[10:13], v[152:155], v[238:241], v[10:13]
	v_mfma_f32_16x16x32_bf16 v[54:57], v[156:159], v[172:175], v[54:57]
	v_mfma_f32_16x16x32_bf16 v[50:53], v[164:167], v[172:175], v[50:53]
	v_mfma_f32_16x16x32_bf16 v[38:41], v[156:159], v[202:205], v[38:41]
	v_mfma_f32_16x16x32_bf16 v[34:37], v[164:167], v[202:205], v[34:37]
	v_mfma_f32_16x16x32_bf16 v[22:25], v[156:159], v[210:213], v[22:25]
	v_mfma_f32_16x16x32_bf16 v[18:21], v[164:167], v[210:213], v[18:21]
	v_mfma_f32_16x16x32_bf16 v[6:9], v[156:159], v[234:237], v[6:9]
	v_mfma_f32_16x16x32_bf16 v[2:5], v[164:167], v[234:237], v[2:5]
	v_mfma_f32_16x16x32_bf16 v[54:57], v[160:163], v[198:201], v[54:57]
	v_mfma_f32_16x16x32_bf16 v[50:53], v[168:171], v[198:201], v[50:53]
	v_mfma_f32_16x16x32_bf16 v[38:41], v[160:163], v[206:209], v[38:41]
	v_mfma_f32_16x16x32_bf16 v[34:37], v[168:171], v[206:209], v[34:37]
	v_mfma_f32_16x16x32_bf16 v[22:25], v[160:163], v[214:217], v[22:25]
	v_mfma_f32_16x16x32_bf16 v[18:21], v[168:171], v[214:217], v[18:21]
	v_mfma_f32_16x16x32_bf16 v[6:9], v[160:163], v[238:241], v[6:9]
	v_mfma_f32_16x16x32_bf16 v[2:5], v[168:171], v[238:241], v[2:5]
	s_setprio 0
	s_barrier
	s_add_i32 s59, 0, 0x18000
	s_add_i32 s68, 0, 0x1c000
	v_add_u32_e32 v152, s59, v195
	v_add_u32_e32 v168, s68, v195
	ds_read_b128 v[140:143], v152
	ds_read_b128 v[144:147], v152 offset:1024
	ds_read_b128 v[148:151], v152 offset:2048
	ds_read_b128 v[152:155], v152 offset:3072
	ds_read_b128 v[156:159], v168
	ds_read_b128 v[160:163], v168 offset:1024
	ds_read_b128 v[164:167], v168 offset:2048
	ds_read_b128 v[168:171], v168 offset:3072
	s_add_u32 s8, s8, s12
	s_addc_u32 s9, s9, s13
	s_mov_b32 m0, s83
	v_lshl_add_u64 v[248:249], s[8:9], 0, v[130:131]
	ds_read_b128 v[172:175], v196 offset:32768
	ds_read_b128 v[198:201], v196 offset:33792
	ds_read_b128 v[202:205], v196 offset:34816
	ds_read_b128 v[206:209], v196 offset:35840
	ds_read_b128 v[210:213], v196 offset:36864
	ds_read_b128 v[214:217], v196 offset:37888
	ds_read_b128 v[234:237], v196 offset:38912
	ds_read_b128 v[238:241], v196 offset:39936
	global_load_lds_dwordx4 v[248:249], off
	v_lshl_add_u64 v[248:249], s[8:9], 0, v[132:133]
	s_mov_b32 m0, s84
	s_nop 0
	global_load_lds_dwordx4 v[248:249], off
	s_waitcnt vmcnt(8)
	s_waitcnt lgkmcnt(0)
	s_barrier
	s_setprio 1
	s_waitcnt lgkmcnt(0)
	v_mfma_f32_16x16x32_bf16 v[126:129], v[140:143], v[172:175], v[126:129]
	v_mfma_f32_16x16x32_bf16 v[122:125], v[148:151], v[172:175], v[122:125]
	v_mfma_f32_16x16x32_bf16 v[110:113], v[140:143], v[202:205], v[110:113]
	v_mfma_f32_16x16x32_bf16 v[106:109], v[148:151], v[202:205], v[106:109]
	v_mfma_f32_16x16x32_bf16 v[94:97], v[140:143], v[210:213], v[94:97]
	v_mfma_f32_16x16x32_bf16 v[90:93], v[148:151], v[210:213], v[90:93]
	v_mfma_f32_16x16x32_bf16 v[78:81], v[140:143], v[234:237], v[78:81]
	v_mfma_f32_16x16x32_bf16 v[74:77], v[148:151], v[234:237], v[74:77]
	v_mfma_f32_16x16x32_bf16 v[126:129], v[144:147], v[198:201], v[126:129]
	v_mfma_f32_16x16x32_bf16 v[122:125], v[152:155], v[198:201], v[122:125]
	v_mfma_f32_16x16x32_bf16 v[110:113], v[144:147], v[206:209], v[110:113]
	v_mfma_f32_16x16x32_bf16 v[106:109], v[152:155], v[206:209], v[106:109]
	v_mfma_f32_16x16x32_bf16 v[94:97], v[144:147], v[214:217], v[94:97]
	v_mfma_f32_16x16x32_bf16 v[90:93], v[152:155], v[214:217], v[90:93]
	v_mfma_f32_16x16x32_bf16 v[78:81], v[144:147], v[238:241], v[78:81]
	v_mfma_f32_16x16x32_bf16 v[74:77], v[152:155], v[238:241], v[74:77]
	v_mfma_f32_16x16x32_bf16 v[118:121], v[156:159], v[172:175], v[118:121]
	v_mfma_f32_16x16x32_bf16 v[114:117], v[164:167], v[172:175], v[114:117]
	v_mfma_f32_16x16x32_bf16 v[102:105], v[156:159], v[202:205], v[102:105]
	v_mfma_f32_16x16x32_bf16 v[98:101], v[164:167], v[202:205], v[98:101]
	v_mfma_f32_16x16x32_bf16 v[86:89], v[156:159], v[210:213], v[86:89]
	v_mfma_f32_16x16x32_bf16 v[82:85], v[164:167], v[210:213], v[82:85]
	v_mfma_f32_16x16x32_bf16 v[70:73], v[156:159], v[234:237], v[70:73]
	v_mfma_f32_16x16x32_bf16 v[66:69], v[164:167], v[234:237], v[66:69]
	v_mfma_f32_16x16x32_bf16 v[118:121], v[160:163], v[198:201], v[118:121]
	v_mfma_f32_16x16x32_bf16 v[114:117], v[168:171], v[198:201], v[114:117]
	v_mfma_f32_16x16x32_bf16 v[102:105], v[160:163], v[206:209], v[102:105]
	v_mfma_f32_16x16x32_bf16 v[98:101], v[168:171], v[206:209], v[98:101]
	v_mfma_f32_16x16x32_bf16 v[86:89], v[160:163], v[214:217], v[86:89]
	v_mfma_f32_16x16x32_bf16 v[82:85], v[168:171], v[214:217], v[82:85]
	v_mfma_f32_16x16x32_bf16 v[70:73], v[160:163], v[238:241], v[70:73]
	v_mfma_f32_16x16x32_bf16 v[66:69], v[168:171], v[238:241], v[66:69]
	s_setprio 0
	s_barrier
; #define PG8_STAGE(bufoff, gbase, voff) do { _Pragma("unroll") for (int _i = 0; _i < 2; ++_i) \
;         __builtin_amdgcn_global_load_lds((const unsigned*)((const char*)(gbase) + (voff)[_i]), (PG8_LAS unsigned*)(lds + (bufoff) + ldsw + _i * 8192), 16, 0, 0); } while (0)
; #define PG8_LDA(dst, b, h) do { _Pragma("unroll") for (int m = 0; m < 4; ++m) _Pragma("unroll") for (int k = 0; k < 2; ++k) dst[m][k] = *(const PG8_LAS bf16x8*)(lds + PG8_SA(b, h) + aoff + m * 2048 + k * 1024); } while (0)
; #define PG8_MMA(ai, bj, At, Bt) do { __builtin_amdgcn_s_setprio(1); _Pragma("unroll") for (int m = 0; m < 4; ++m) _Pragma("unroll") for (int n = 0; n < 2; ++n) _Pragma("unroll") for (int k = 0; k < 2; ++k) \
;         acc[ai][bj][m][n] = __builtin_amdgcn_mfma_f32_16x16x32_bf16(Bt[n][k], At[m][k], acc[ai][bj][m][n], 0, 0, 0); __builtin_amdgcn_s_setprio(0); } while (0)
; #define PG8_WAIT_V(n) asm volatile("s_waitcnt vmcnt(" #n ")" ::: "memory")
; #define PG8_WAIT_L(n) asm volatile("s_waitcnt lgkmcnt(" #n ")" ::: "memory")
; #define PG8_BAR __builtin_amdgcn_s_barrier()
; #define PG8_SCHED __builtin_amdgcn_sched_barrier(0)
; template <class Epi, class Sched, bool ALIGN_EPI = false, bool SP2 = false>
; __device__ __forceinline__ void gemm_phase(PG8_LAS unsigned char* lds, const Gemm g, const Sched& S, const Epi& E) {
;     ...
;             PG8_LDA(At, 1, 1); PG8_STAGE(PG8_SB(1, 0), b3, voffB); PG8_STAGE(PG8_SB(1, 1), b3 + hstep, voffB); PG8_STAGE(PG8_SA(1, 0), a3, voffA);
;             PG8_WAIT_V(8); PG8_WAIT_L(0); PG8_BAR; PG8_MMA(1, 0, At, B0); PG8_MMA(1, 1, At, B1); PG8_BAR; PG8_SCHED;
	s_add_i32 s8, s59, s78
	v_lshl_add_u64 v[176:177], v[176:177], 0, s[52:53]
	s_mov_b32 m0, s8
	ds_read_b128 v[172:175], v196 offset:49152
	ds_read_b128 v[198:201], v196 offset:50176
	ds_read_b128 v[202:205], v196 offset:51200
	ds_read_b128 v[206:209], v196 offset:52224
	ds_read_b128 v[210:213], v196 offset:53248
	ds_read_b128 v[214:217], v196 offset:54272
	ds_read_b128 v[234:237], v196 offset:55296
	ds_read_b128 v[238:241], v196 offset:56320
	global_load_lds_dwordx4 v[176:177], off
	v_lshl_add_u64 v[176:177], v[222:223], 0, s[52:53]
	s_add_i32 m0, s8, 0x2000
	s_add_i32 s8, s68, s78
	global_load_lds_dwordx4 v[176:177], off
	v_lshl_add_u64 v[176:177], v[232:233], 0, s[52:53]
	s_mov_b32 m0, s8
	s_nop 0
	global_load_lds_dwordx4 v[176:177], off
	v_lshl_add_u64 v[176:177], v[242:243], 0, s[52:53]
	s_add_i32 m0, s8, 0x2000
	s_nop 0
	global_load_lds_dwordx4 v[176:177], off
	v_lshl_add_u64 v[176:177], v[244:245], 0, s[52:53]
	s_mov_b32 m0, s91
	s_nop 0
	global_load_lds_dwordx4 v[176:177], off
	v_lshl_add_u64 v[176:177], v[246:247], 0, s[52:53]
	s_mov_b32 m0, s35
	s_nop 0
	global_load_lds_dwordx4 v[176:177], off
	s_waitcnt vmcnt(8)
	s_waitcnt lgkmcnt(0)
	s_barrier
	s_setprio 1
	s_waitcnt lgkmcnt(0)
	v_mfma_f32_16x16x32_bf16 v[62:65], v[140:143], v[172:175], v[62:65]
	v_mfma_f32_16x16x32_bf16 v[58:61], v[148:151], v[172:175], v[58:61]
	v_mfma_f32_16x16x32_bf16 v[46:49], v[140:143], v[202:205], v[46:49]
	v_mfma_f32_16x16x32_bf16 v[42:45], v[148:151], v[202:205], v[42:45]
	v_mfma_f32_16x16x32_bf16 v[30:33], v[140:143], v[210:213], v[30:33]
	v_mfma_f32_16x16x32_bf16 v[26:29], v[148:151], v[210:213], v[26:29]
	v_mfma_f32_16x16x32_bf16 v[14:17], v[140:143], v[234:237], v[14:17]
	v_mfma_f32_16x16x32_bf16 v[10:13], v[148:151], v[234:237], v[10:13]
	v_mfma_f32_16x16x32_bf16 v[62:65], v[144:147], v[198:201], v[62:65]
	v_mfma_f32_16x16x32_bf16 v[58:61], v[152:155], v[198:201], v[58:61]
	v_mfma_f32_16x16x32_bf16 v[46:49], v[144:147], v[206:209], v[46:49]
	v_mfma_f32_16x16x32_bf16 v[42:45], v[152:155], v[206:209], v[42:45]
	v_mfma_f32_16x16x32_bf16 v[30:33], v[144:147], v[214:217], v[30:33]
	v_mfma_f32_16x16x32_bf16 v[26:29], v[152:155], v[214:217], v[26:29]
	v_mfma_f32_16x16x32_bf16 v[14:17], v[144:147], v[238:241], v[14:17]
	v_mfma_f32_16x16x32_bf16 v[10:13], v[152:155], v[238:241], v[10:13]
	v_mfma_f32_16x16x32_bf16 v[54:57], v[156:159], v[172:175], v[54:57]
	v_mfma_f32_16x16x32_bf16 v[50:53], v[164:167], v[172:175], v[50:53]
	v_mfma_f32_16x16x32_bf16 v[38:41], v[156:159], v[202:205], v[38:41]
	v_mfma_f32_16x16x32_bf16 v[34:37], v[164:167], v[202:205], v[34:37]
	v_mfma_f32_16x16x32_bf16 v[22:25], v[156:159], v[210:213], v[22:25]
	v_mfma_f32_16x16x32_bf16 v[18:21], v[164:167], v[210:213], v[18:21]
	v_mfma_f32_16x16x32_bf16 v[6:9], v[156:159], v[234:237], v[6:9]
	v_mfma_f32_16x16x32_bf16 v[2:5], v[164:167], v[234:237], v[2:5]
	v_mfma_f32_16x16x32_bf16 v[54:57], v[160:163], v[198:201], v[54:57]
	v_mfma_f32_16x16x32_bf16 v[50:53], v[168:171], v[198:201], v[50:53]
	v_mfma_f32_16x16x32_bf16 v[38:41], v[160:163], v[206:209], v[38:41]
	v_mfma_f32_16x16x32_bf16 v[34:37], v[168:171], v[206:209], v[34:37]
	v_mfma_f32_16x16x32_bf16 v[22:25], v[160:163], v[214:217], v[22:25]
	v_mfma_f32_16x16x32_bf16 v[18:21], v[168:171], v[214:217], v[18:21]
	v_mfma_f32_16x16x32_bf16 v[6:9], v[160:163], v[238:241], v[6:9]
	v_mfma_f32_16x16x32_bf16 v[2:5], v[168:171], v[238:241], v[2:5]
	s_setprio 0
	s_barrier
	s_add_u32 s6, s6, 0x100
	s_addc_u32 s7, s7, 0
	s_add_u32 s10, s10, 0x100
	s_addc_u32 s11, s11, 0
	s_cmp_ge_i32 s58, s2
	s_mov_b32 s8, s58
	s_cbranch_scc0 .LBB0_522

;     __device__ bool next(int i, Unit& u) const { const int L = i * G + c; if (L >= 33 * 16) return false; const int pnv = L & 15, pm = L >> 4; u.pm = (pnv >> 1) * 33 + pm; u.pn = pnv; return true; }
;     __device__ bool next(int i, Unit& u) const { const int L = i * G + c; if (L >= npn * nsl) return false; u.pm = 32; u.pn = L % npn; u.k0 = (L / npn) * 256; return true; }
; #define PG8_STAGE(bufoff, gbase, voff) do { _Pragma("unroll") for (int _i = 0; _i < 2; ++_i) \
;         __builtin_amdgcn_global_load_lds((const unsigned*)((const char*)(gbase) + (voff)[_i]), (PG8_LAS unsigned*)(lds + (bufoff) + ldsw + _i * 8192), 16, 0, 0); } while (0)
; #define PG8_LDA(dst, b, h) do { _Pragma("unroll") for (int m = 0; m < 4; ++m) _Pragma("unroll") for (int k = 0; k < 2; ++k) dst[m][k] = *(const PG8_LAS bf16x8*)(lds + PG8_SA(b, h) + aoff + m * 2048 + k * 1024); } while (0)
; #define PG8_LDB(dst, b, h) do { _Pragma("unroll") for (int n = 0; n < 2; ++n) _Pragma("unroll") for (int k = 0; k < 2; ++k) dst[n][k] = *(const PG8_LAS bf16x8*)(lds + PG8_SB(b, h) + boff + n * 2048 + k * 1024); } while (0)
; template <class Epi, class Sched, bool ALIGN_EPI = false, bool SP2 = false>
; __device__ __forceinline__ void gemm_phase(PG8_LAS unsigned char* lds, const Gemm g, const Sched& S, const Epi& E) {
;     ...
;         const bool has_next = S.next(ui + 1, nxt);
;         const char* nA = has_next ? (const char*)g.A + (size_t)nxt.pm * tstep + (size_t)nxt.k0 * 2 : cA; const char* nB = has_next ? (const char*)g.Bt + (size_t)nxt.pn * tstep + (size_t)nxt.k0 * 2 : cB;
;         for (int t = 0; t < nt; t += 2) {
;             const bool last = (t == nt - 2);
;             const char* a1 = cA + (size_t)(t + 1) * kstep;
;             const char* a2 = last ? nA : cA + (size_t)(t + 2) * kstep; const char* b2 = last ? nB : cB + (size_t)(t + 2) * kstep;
;             const char* a3 = a2 + kstep; const char* b3 = b2 + kstep;
;             if (last && has_next) S.a_ready(nxt);
;             if constexpr (SP2) {
;             PG8_LDB(B0, 0, 0); PG8_LDB(B1, 0, 1); PG8_SCHED; PG8_LDA(At, 0, 0); PG8_STAGE(PG8_SA(1, 1), a1 + hstep, voffA);
;             PG8_WAIT_V(8); PG8_WAIT_L(0); PG8_BAR; PG8_MMA(0, 0, At, B0); PG8_MMA(0, 1, At, B1); PG8_BAR; PG8_SCHED;
;             PG8_LDA(At, 0, 1); PG8_STAGE(PG8_SB(0, 0), b2, voffB); PG8_STAGE(PG8_SB(0, 1), b2 + hstep, voffB); PG8_STAGE(PG8_SA(0, 0), a2, voffA);
.LBB0_1051:
	s_add_i32 s85, s30, 2
	s_add_u32 s86, s6, 0x80
	s_addc_u32 s31, s7, 0
	s_add_i32 s90, 0, 0x10000
	s_cmp_eq_u32 s71, s30
	s_cselect_b32 s31, s23, s31
	s_cselect_b32 s30, s22, s86
	s_cselect_b32 s87, s29, s55
	s_cselect_b32 s86, s28, s54
	s_add_i32 s91, 0, 0x14000
	v_add_u32_e32 v142, s90, v217
	v_add_u32_e32 v158, s91, v217
	ds_read_b128 v[130:133], v142
	ds_read_b128 v[134:137], v142 offset:1024
	ds_read_b128 v[138:141], v142 offset:2048
	ds_read_b128 v[142:145], v142 offset:3072
	ds_read_b128 v[146:149], v158
	ds_read_b128 v[150:153], v158 offset:1024
	ds_read_b128 v[154:157], v158 offset:2048
	ds_read_b128 v[158:161], v158 offset:3072
	v_lshl_add_u64 v[222:223], s[6:7], 0, v[200:201]
	s_add_i32 m0, s45, 0xc000
	ds_read_b128 v[162:165], v233
	ds_read_b128 v[166:169], v233 offset:1024
	ds_read_b128 v[170:173], v233 offset:2048
	ds_read_b128 v[174:177], v233 offset:3072
	ds_read_b128 v[204:207], v233 offset:4096
	ds_read_b128 v[208:211], v233 offset:5120
	ds_read_b128 v[212:215], v233 offset:6144
	ds_read_b128 v[234:237], v233 offset:7168
	global_load_lds_dwordx4 v[222:223], off
	v_lshl_add_u64 v[222:223], s[6:7], 0, v[202:203]
	s_add_i32 m0, s45, 0xe000
	s_nop 0
	global_load_lds_dwordx4 v[222:223], off
	s_waitcnt vmcnt(8)
	s_waitcnt lgkmcnt(0)
	s_barrier
	s_setprio 1
	s_waitcnt lgkmcnt(0)
	v_mfma_f32_16x16x32_bf16 v[122:125], v[130:133], v[162:165], v[122:125]
	v_mfma_f32_16x16x32_bf16 v[126:129], v[138:141], v[162:165], v[126:129]
	v_mfma_f32_16x16x32_bf16 v[110:113], v[130:133], v[170:173], v[110:113]
	v_mfma_f32_16x16x32_bf16 v[106:109], v[138:141], v[170:173], v[106:109]
	v_mfma_f32_16x16x32_bf16 v[94:97], v[130:133], v[204:207], v[94:97]
	v_mfma_f32_16x16x32_bf16 v[90:93], v[138:141], v[204:207], v[90:93]
	v_mfma_f32_16x16x32_bf16 v[78:81], v[130:133], v[212:215], v[78:81]
	v_mfma_f32_16x16x32_bf16 v[74:77], v[138:141], v[212:215], v[74:77]
	v_mfma_f32_16x16x32_bf16 v[122:125], v[134:137], v[166:169], v[122:125]
	v_mfma_f32_16x16x32_bf16 v[126:129], v[142:145], v[166:169], v[126:129]
	v_mfma_f32_16x16x32_bf16 v[110:113], v[134:137], v[174:177], v[110:113]
	v_mfma_f32_16x16x32_bf16 v[106:109], v[142:145], v[174:177], v[106:109]
	v_mfma_f32_16x16x32_bf16 v[94:97], v[134:137], v[208:211], v[94:97]
	v_mfma_f32_16x16x32_bf16 v[90:93], v[142:145], v[208:211], v[90:93]
	v_mfma_f32_16x16x32_bf16 v[78:81], v[134:137], v[234:237], v[78:81]
	v_mfma_f32_16x16x32_bf16 v[74:77], v[142:145], v[234:237], v[74:77]
	v_mfma_f32_16x16x32_bf16 v[118:121], v[146:149], v[162:165], v[118:121]
	v_mfma_f32_16x16x32_bf16 v[114:117], v[154:157], v[162:165], v[114:117]
	v_mfma_f32_16x16x32_bf16 v[102:105], v[146:149], v[170:173], v[102:105]
	v_mfma_f32_16x16x32_bf16 v[98:101], v[154:157], v[170:173], v[98:101]
	v_mfma_f32_16x16x32_bf16 v[86:89], v[146:149], v[204:207], v[86:89]
	v_mfma_f32_16x16x32_bf16 v[82:85], v[154:157], v[204:207], v[82:85]
	v_mfma_f32_16x16x32_bf16 v[70:73], v[146:149], v[212:215], v[70:73]
	v_mfma_f32_16x16x32_bf16 v[66:69], v[154:157], v[212:215], v[66:69]
	v_mfma_f32_16x16x32_bf16 v[118:121], v[150:153], v[166:169], v[118:121]
	v_mfma_f32_16x16x32_bf16 v[114:117], v[158:161], v[166:169], v[114:117]
	v_mfma_f32_16x16x32_bf16 v[102:105], v[150:153], v[174:177], v[102:105]
	v_mfma_f32_16x16x32_bf16 v[98:101], v[158:161], v[174:177], v[98:101]
	v_mfma_f32_16x16x32_bf16 v[86:89], v[150:153], v[208:211], v[86:89]
	v_mfma_f32_16x16x32_bf16 v[82:85], v[158:161], v[208:211], v[82:85]
	v_mfma_f32_16x16x32_bf16 v[70:73], v[150:153], v[234:237], v[70:73]
	v_mfma_f32_16x16x32_bf16 v[66:69], v[158:161], v[234:237], v[66:69]
	s_setprio 0
	s_barrier
	s_add_i32 s90, s90, s40
	v_lshl_add_u64 v[222:223], s[86:87], 0, v[0:1]
	s_mov_b32 m0, s90
	ds_read_b128 v[162:165], v233 offset:16384
	ds_read_b128 v[166:169], v233 offset:17408
	ds_read_b128 v[170:173], v233 offset:18432
	ds_read_b128 v[174:177], v233 offset:19456
	ds_read_b128 v[204:207], v233 offset:20480
	ds_read_b128 v[208:211], v233 offset:21504
	ds_read_b128 v[212:215], v233 offset:22528
	ds_read_b128 v[234:237], v233 offset:23552
	global_load_lds_dwordx4 v[222:223], off
	s_add_i32 m0, s90, 0x2000
	v_lshl_add_u64 v[238:239], s[86:87], 0, v[198:199]
	s_add_u32 s86, s86, s8
	s_addc_u32 s87, s87, s9
	s_add_i32 s90, s91, s40
	global_load_lds_dwordx4 v[238:239], off
	v_lshl_add_u64 v[240:241], s[86:87], 0, v[0:1]
	s_mov_b32 m0, s90
	v_lshl_add_u64 v[242:243], s[86:87], 0, v[198:199]
	global_load_lds_dwordx4 v[240:241], off
	s_add_i32 m0, s90, 0x2000
	v_lshl_add_u64 v[244:245], s[30:31], 0, v[194:195]
	global_load_lds_dwordx4 v[242:243], off
	s_mov_b32 m0, s45
	v_lshl_add_u64 v[246:247], s[30:31], 0, v[196:197]
	global_load_lds_dwordx4 v[244:245], off
	s_mov_b32 m0, s47
	s_nop 0
	global_load_lds_dwordx4 v[246:247], off
	s_waitcnt vmcnt(8)
	s_waitcnt lgkmcnt(0)
	s_barrier
; #define PG8_STAGE(bufoff, gbase, voff) do { _Pragma("unroll") for (int _i = 0; _i < 2; ++_i) \
;         __builtin_amdgcn_global_load_lds((const unsigned*)((const char*)(gbase) + (voff)[_i]), (PG8_LAS unsigned*)(lds + (bufoff) + ldsw + _i * 8192), 16, 0, 0); } while (0)
; #define PG8_LDA(dst, b, h) do { _Pragma("unroll") for (int m = 0; m < 4; ++m) _Pragma("unroll") for (int k = 0; k < 2; ++k) dst[m][k] = *(const PG8_LAS bf16x8*)(lds + PG8_SA(b, h) + aoff + m * 2048 + k * 1024); } while (0)
; #define PG8_LDB(dst, b, h) do { _Pragma("unroll") for (int n = 0; n < 2; ++n) _Pragma("unroll") for (int k = 0; k < 2; ++k) dst[n][k] = *(const PG8_LAS bf16x8*)(lds + PG8_SB(b, h) + boff + n * 2048 + k * 1024); } while (0)
; #define PG8_MMA(ai, bj, At, Bt) do { __builtin_amdgcn_s_setprio(1); _Pragma("unroll") for (int m = 0; m < 4; ++m) _Pragma("unroll") for (int n = 0; n < 2; ++n) _Pragma("unroll") for (int k = 0; k < 2; ++k) \
;         acc[ai][bj][m][n] = __builtin_amdgcn_mfma_f32_16x16x32_bf16(Bt[n][k], At[m][k], acc[ai][bj][m][n], 0, 0, 0); __builtin_amdgcn_s_setprio(0); } while (0)
; #define PG8_WAIT_V(n) asm volatile("s_waitcnt vmcnt(" #n ")" ::: "memory")
; #define PG8_WAIT_L(n) asm volatile("s_waitcnt lgkmcnt(" #n ")" ::: "memory")
; #define PG8_BAR __builtin_amdgcn_s_barrier()
; #define PG8_SCHED __builtin_amdgcn_sched_barrier(0)
; template <class Epi, class Sched, bool ALIGN_EPI = false, bool SP2 = false>
; __device__ __forceinline__ void gemm_phase(PG8_LAS unsigned char* lds, const Gemm g, const Sched& S, const Epi& E) {
;     ...
;             PG8_WAIT_V(8); PG8_WAIT_L(0); PG8_BAR; PG8_MMA(1, 0, At, B0); PG8_MMA(1, 1, At, B1); PG8_BAR; PG8_SCHED;
;             PG8_LDB(B0, 1, 0); PG8_LDB(B1, 1, 1); PG8_SCHED; PG8_LDA(At, 1, 0); PG8_STAGE(PG8_SA(0, 1), a2 + hstep, voffA);
;             PG8_WAIT_V(8); PG8_WAIT_L(0); PG8_BAR; PG8_MMA(0, 0, At, B0); PG8_MMA(0, 1, At, B1); PG8_BAR; PG8_SCHED;
	s_setprio 1
	s_waitcnt lgkmcnt(0)
	v_mfma_f32_16x16x32_bf16 v[62:65], v[130:133], v[162:165], v[62:65]
	v_mfma_f32_16x16x32_bf16 v[58:61], v[138:141], v[162:165], v[58:61]
	v_mfma_f32_16x16x32_bf16 v[46:49], v[130:133], v[170:173], v[46:49]
	v_mfma_f32_16x16x32_bf16 v[42:45], v[138:141], v[170:173], v[42:45]
	v_mfma_f32_16x16x32_bf16 v[30:33], v[130:133], v[204:207], v[30:33]
	v_mfma_f32_16x16x32_bf16 v[26:29], v[138:141], v[204:207], v[26:29]
	v_mfma_f32_16x16x32_bf16 v[14:17], v[130:133], v[212:215], v[14:17]
	v_mfma_f32_16x16x32_bf16 v[10:13], v[138:141], v[212:215], v[10:13]
	v_mfma_f32_16x16x32_bf16 v[62:65], v[134:137], v[166:169], v[62:65]
	v_mfma_f32_16x16x32_bf16 v[58:61], v[142:145], v[166:169], v[58:61]
	v_mfma_f32_16x16x32_bf16 v[46:49], v[134:137], v[174:177], v[46:49]
	v_mfma_f32_16x16x32_bf16 v[42:45], v[142:145], v[174:177], v[42:45]
	v_mfma_f32_16x16x32_bf16 v[30:33], v[134:137], v[208:211], v[30:33]
	v_mfma_f32_16x16x32_bf16 v[26:29], v[142:145], v[208:211], v[26:29]
	v_mfma_f32_16x16x32_bf16 v[14:17], v[134:137], v[234:237], v[14:17]
	v_mfma_f32_16x16x32_bf16 v[10:13], v[142:145], v[234:237], v[10:13]
	v_mfma_f32_16x16x32_bf16 v[54:57], v[146:149], v[162:165], v[54:57]
	v_mfma_f32_16x16x32_bf16 v[50:53], v[154:157], v[162:165], v[50:53]
	v_mfma_f32_16x16x32_bf16 v[38:41], v[146:149], v[170:173], v[38:41]
	v_mfma_f32_16x16x32_bf16 v[34:37], v[154:157], v[170:173], v[34:37]
	v_mfma_f32_16x16x32_bf16 v[22:25], v[146:149], v[204:207], v[22:25]
	v_mfma_f32_16x16x32_bf16 v[18:21], v[154:157], v[204:207], v[18:21]
	v_mfma_f32_16x16x32_bf16 v[6:9], v[146:149], v[212:215], v[6:9]
	v_mfma_f32_16x16x32_bf16 v[2:5], v[154:157], v[212:215], v[2:5]
	v_mfma_f32_16x16x32_bf16 v[54:57], v[150:153], v[166:169], v[54:57]
	v_mfma_f32_16x16x32_bf16 v[50:53], v[158:161], v[166:169], v[50:53]
	v_mfma_f32_16x16x32_bf16 v[38:41], v[150:153], v[174:177], v[38:41]
	v_mfma_f32_16x16x32_bf16 v[34:37], v[158:161], v[174:177], v[34:37]
	v_mfma_f32_16x16x32_bf16 v[22:25], v[150:153], v[208:211], v[22:25]
	v_mfma_f32_16x16x32_bf16 v[18:21], v[158:161], v[208:211], v[18:21]
	v_mfma_f32_16x16x32_bf16 v[6:9], v[150:153], v[234:237], v[6:9]
	v_mfma_f32_16x16x32_bf16 v[2:5], v[158:161], v[234:237], v[2:5]
	s_setprio 0
	s_barrier
	s_add_i32 s86, 0, 0x18000
	s_add_i32 s87, 0, 0x1c000
	v_add_u32_e32 v142, s86, v217
	v_add_u32_e32 v158, s87, v217
	ds_read_b128 v[130:133], v142
	ds_read_b128 v[134:137], v142 offset:1024
	ds_read_b128 v[138:141], v142 offset:2048
	ds_read_b128 v[142:145], v142 offset:3072
	ds_read_b128 v[146:149], v158
	ds_read_b128 v[150:153], v158 offset:1024
	ds_read_b128 v[154:157], v158 offset:2048
	ds_read_b128 v[158:161], v158 offset:3072
	s_add_u32 s30, s30, s8
	s_addc_u32 s31, s31, s9
	s_mov_b32 m0, s56
	v_lshl_add_u64 v[248:249], s[30:31], 0, v[194:195]
	ds_read_b128 v[162:165], v233 offset:32768
	ds_read_b128 v[166:169], v233 offset:33792
	ds_read_b128 v[170:173], v233 offset:34816
	ds_read_b128 v[174:177], v233 offset:35840
	ds_read_b128 v[204:207], v233 offset:36864
	ds_read_b128 v[208:211], v233 offset:37888
	ds_read_b128 v[212:215], v233 offset:38912
	ds_read_b128 v[234:237], v233 offset:39936
	global_load_lds_dwordx4 v[248:249], off
	v_lshl_add_u64 v[248:249], s[30:31], 0, v[196:197]
	s_mov_b32 m0, s57
	s_nop 0
	global_load_lds_dwordx4 v[248:249], off
	s_waitcnt vmcnt(8)
	s_waitcnt lgkmcnt(0)
	s_barrier
	s_setprio 1
	s_waitcnt lgkmcnt(0)
	v_mfma_f32_16x16x32_bf16 v[122:125], v[130:133], v[162:165], v[122:125]
	v_mfma_f32_16x16x32_bf16 v[126:129], v[138:141], v[162:165], v[126:129]
	v_mfma_f32_16x16x32_bf16 v[110:113], v[130:133], v[170:173], v[110:113]
	v_mfma_f32_16x16x32_bf16 v[106:109], v[138:141], v[170:173], v[106:109]
	v_mfma_f32_16x16x32_bf16 v[94:97], v[130:133], v[204:207], v[94:97]
	v_mfma_f32_16x16x32_bf16 v[90:93], v[138:141], v[204:207], v[90:93]
	v_mfma_f32_16x16x32_bf16 v[78:81], v[130:133], v[212:215], v[78:81]
	v_mfma_f32_16x16x32_bf16 v[74:77], v[138:141], v[212:215], v[74:77]
	v_mfma_f32_16x16x32_bf16 v[122:125], v[134:137], v[166:169], v[122:125]
	v_mfma_f32_16x16x32_bf16 v[126:129], v[142:145], v[166:169], v[126:129]
	v_mfma_f32_16x16x32_bf16 v[110:113], v[134:137], v[174:177], v[110:113]
	v_mfma_f32_16x16x32_bf16 v[106:109], v[142:145], v[174:177], v[106:109]
	v_mfma_f32_16x16x32_bf16 v[94:97], v[134:137], v[208:211], v[94:97]
	v_mfma_f32_16x16x32_bf16 v[90:93], v[142:145], v[208:211], v[90:93]
	v_mfma_f32_16x16x32_bf16 v[78:81], v[134:137], v[234:237], v[78:81]
	v_mfma_f32_16x16x32_bf16 v[74:77], v[142:145], v[234:237], v[74:77]
	v_mfma_f32_16x16x32_bf16 v[118:121], v[146:149], v[162:165], v[118:121]
	v_mfma_f32_16x16x32_bf16 v[114:117], v[154:157], v[162:165], v[114:117]
	v_mfma_f32_16x16x32_bf16 v[102:105], v[146:149], v[170:173], v[102:105]
	v_mfma_f32_16x16x32_bf16 v[98:101], v[154:157], v[170:173], v[98:101]
	v_mfma_f32_16x16x32_bf16 v[86:89], v[146:149], v[204:207], v[86:89]
	v_mfma_f32_16x16x32_bf16 v[82:85], v[154:157], v[204:207], v[82:85]
	v_mfma_f32_16x16x32_bf16 v[70:73], v[146:149], v[212:215], v[70:73]
	v_mfma_f32_16x16x32_bf16 v[66:69], v[154:157], v[212:215], v[66:69]
	v_mfma_f32_16x16x32_bf16 v[118:121], v[150:153], v[166:169], v[118:121]
	v_mfma_f32_16x16x32_bf16 v[114:117], v[158:161], v[166:169], v[114:117]
	v_mfma_f32_16x16x32_bf16 v[102:105], v[150:153], v[174:177], v[102:105]
	v_mfma_f32_16x16x32_bf16 v[98:101], v[158:161], v[174:177], v[98:101]
	v_mfma_f32_16x16x32_bf16 v[86:89], v[150:153], v[208:211], v[86:89]
	v_mfma_f32_16x16x32_bf16 v[82:85], v[158:161], v[208:211], v[82:85]
	v_mfma_f32_16x16x32_bf16 v[70:73], v[150:153], v[234:237], v[70:73]
	v_mfma_f32_16x16x32_bf16 v[66:69], v[158:161], v[234:237], v[66:69]
	s_setprio 0
	s_barrier
; #define PG8_STAGE(bufoff, gbase, voff) do { _Pragma("unroll") for (int _i = 0; _i < 2; ++_i) \
;         __builtin_amdgcn_global_load_lds((const unsigned*)((const char*)(gbase) + (voff)[_i]), (PG8_LAS unsigned*)(lds + (bufoff) + ldsw + _i * 8192), 16, 0, 0); } while (0)
; #define PG8_LDA(dst, b, h) do { _Pragma("unroll") for (int m = 0; m < 4; ++m) _Pragma("unroll") for (int k = 0; k < 2; ++k) dst[m][k] = *(const PG8_LAS bf16x8*)(lds + PG8_SA(b, h) + aoff + m * 2048 + k * 1024); } while (0)
; #define PG8_MMA(ai, bj, At, Bt) do { __builtin_amdgcn_s_setprio(1); _Pragma("unroll") for (int m = 0; m < 4; ++m) _Pragma("unroll") for (int n = 0; n < 2; ++n) _Pragma("unroll") for (int k = 0; k < 2; ++k) \
;         acc[ai][bj][m][n] = __builtin_amdgcn_mfma_f32_16x16x32_bf16(Bt[n][k], At[m][k], acc[ai][bj][m][n], 0, 0, 0); __builtin_amdgcn_s_setprio(0); } while (0)
; #define PG8_WAIT_V(n) asm volatile("s_waitcnt vmcnt(" #n ")" ::: "memory")
; #define PG8_WAIT_L(n) asm volatile("s_waitcnt lgkmcnt(" #n ")" ::: "memory")
; #define PG8_BAR __builtin_amdgcn_s_barrier()
; #define PG8_SCHED __builtin_amdgcn_sched_barrier(0)
; template <class Epi, class Sched, bool ALIGN_EPI = false, bool SP2 = false>
; __device__ __forceinline__ void gemm_phase(PG8_LAS unsigned char* lds, const Gemm g, const Sched& S, const Epi& E) {
;     ...
;         for (int t = 0; t < nt; t += 2) {
;     ...
;             PG8_LDA(At, 1, 1); PG8_STAGE(PG8_SB(1, 0), b3, voffB); PG8_STAGE(PG8_SB(1, 1), b3 + hstep, voffB); PG8_STAGE(PG8_SA(1, 0), a3, voffA);
;             PG8_WAIT_V(8); PG8_WAIT_L(0); PG8_BAR; PG8_MMA(1, 0, At, B0); PG8_MMA(1, 1, At, B1); PG8_BAR; PG8_SCHED;
	s_add_i32 s30, s86, s40
	v_lshl_add_u64 v[222:223], v[222:223], 0, s[52:53]
	s_mov_b32 m0, s30
	ds_read_b128 v[162:165], v233 offset:49152
	ds_read_b128 v[166:169], v233 offset:50176
	ds_read_b128 v[170:173], v233 offset:51200
	ds_read_b128 v[174:177], v233 offset:52224
	ds_read_b128 v[204:207], v233 offset:53248
	ds_read_b128 v[208:211], v233 offset:54272
	ds_read_b128 v[212:215], v233 offset:55296
	ds_read_b128 v[234:237], v233 offset:56320
	global_load_lds_dwordx4 v[222:223], off
	v_lshl_add_u64 v[222:223], v[238:239], 0, s[52:53]
	s_add_i32 m0, s30, 0x2000
	s_add_i32 s30, s87, s40
	global_load_lds_dwordx4 v[222:223], off
	v_lshl_add_u64 v[222:223], v[240:241], 0, s[52:53]
	s_mov_b32 m0, s30
	s_nop 0
	global_load_lds_dwordx4 v[222:223], off
	v_lshl_add_u64 v[222:223], v[242:243], 0, s[52:53]
	s_add_i32 m0, s30, 0x2000
	s_nop 0
	global_load_lds_dwordx4 v[222:223], off
	v_lshl_add_u64 v[222:223], v[244:245], 0, s[52:53]
	s_mov_b32 m0, s66
	s_nop 0
	global_load_lds_dwordx4 v[222:223], off
	v_lshl_add_u64 v[222:223], v[246:247], 0, s[52:53]
	s_mov_b32 m0, s67
	s_nop 0
	global_load_lds_dwordx4 v[222:223], off
	s_waitcnt vmcnt(8)
	s_waitcnt lgkmcnt(0)
	s_barrier
	s_setprio 1
	s_waitcnt lgkmcnt(0)
	v_mfma_f32_16x16x32_bf16 v[62:65], v[130:133], v[162:165], v[62:65]
	v_mfma_f32_16x16x32_bf16 v[58:61], v[138:141], v[162:165], v[58:61]
	v_mfma_f32_16x16x32_bf16 v[46:49], v[130:133], v[170:173], v[46:49]
	v_mfma_f32_16x16x32_bf16 v[42:45], v[138:141], v[170:173], v[42:45]
	v_mfma_f32_16x16x32_bf16 v[30:33], v[130:133], v[204:207], v[30:33]
	v_mfma_f32_16x16x32_bf16 v[26:29], v[138:141], v[204:207], v[26:29]
	v_mfma_f32_16x16x32_bf16 v[14:17], v[130:133], v[212:215], v[14:17]
	v_mfma_f32_16x16x32_bf16 v[10:13], v[138:141], v[212:215], v[10:13]
	v_mfma_f32_16x16x32_bf16 v[62:65], v[134:137], v[166:169], v[62:65]
	v_mfma_f32_16x16x32_bf16 v[58:61], v[142:145], v[166:169], v[58:61]
	v_mfma_f32_16x16x32_bf16 v[46:49], v[134:137], v[174:177], v[46:49]
	v_mfma_f32_16x16x32_bf16 v[42:45], v[142:145], v[174:177], v[42:45]
	v_mfma_f32_16x16x32_bf16 v[30:33], v[134:137], v[208:211], v[30:33]
	v_mfma_f32_16x16x32_bf16 v[26:29], v[142:145], v[208:211], v[26:29]
	v_mfma_f32_16x16x32_bf16 v[14:17], v[134:137], v[234:237], v[14:17]
	v_mfma_f32_16x16x32_bf16 v[10:13], v[142:145], v[234:237], v[10:13]
	v_mfma_f32_16x16x32_bf16 v[54:57], v[146:149], v[162:165], v[54:57]
	v_mfma_f32_16x16x32_bf16 v[50:53], v[154:157], v[162:165], v[50:53]
	v_mfma_f32_16x16x32_bf16 v[38:41], v[146:149], v[170:173], v[38:41]
	v_mfma_f32_16x16x32_bf16 v[34:37], v[154:157], v[170:173], v[34:37]
	v_mfma_f32_16x16x32_bf16 v[22:25], v[146:149], v[204:207], v[22:25]
	v_mfma_f32_16x16x32_bf16 v[18:21], v[154:157], v[204:207], v[18:21]
	v_mfma_f32_16x16x32_bf16 v[6:9], v[146:149], v[212:215], v[6:9]
	v_mfma_f32_16x16x32_bf16 v[2:5], v[154:157], v[212:215], v[2:5]
	v_mfma_f32_16x16x32_bf16 v[54:57], v[150:153], v[166:169], v[54:57]
	v_mfma_f32_16x16x32_bf16 v[50:53], v[158:161], v[166:169], v[50:53]
	v_mfma_f32_16x16x32_bf16 v[38:41], v[150:153], v[174:177], v[38:41]
	v_mfma_f32_16x16x32_bf16 v[34:37], v[158:161], v[174:177], v[34:37]
	v_mfma_f32_16x16x32_bf16 v[22:25], v[150:153], v[208:211], v[22:25]
	v_mfma_f32_16x16x32_bf16 v[18:21], v[158:161], v[208:211], v[18:21]
	v_mfma_f32_16x16x32_bf16 v[6:9], v[150:153], v[234:237], v[6:9]
	v_mfma_f32_16x16x32_bf16 v[2:5], v[158:161], v[234:237], v[2:5]
	s_setprio 0
	s_barrier
	s_add_u32 s6, s6, 0x100
	s_addc_u32 s7, s7, 0
	s_add_u32 s54, s54, 0x100
	s_addc_u32 s55, s55, 0
	s_cmp_ge_i32 s85, s69
	s_mov_b32 s30, s85
	s_cbranch_scc0 .LBB0_1051

;     __device__ bool next(int i, Unit& u) const { const int L = i * G + c; if (L >= 33 * 16) return false; const int pnv = L & 15, pm = L >> 4; u.pm = (pnv >> 1) * 33 + pm; u.pn = pnv; return true; }
;     __device__ bool next(int i, Unit& u) const { const int L = i * G + c; if (L >= npn * nsl) return false; u.pm = 32; u.pn = L % npn; u.k0 = (L / npn) * 256; return true; }
; #define PG8_STAGE(bufoff, gbase, voff) do { _Pragma("unroll") for (int _i = 0; _i < 2; ++_i) \
;         __builtin_amdgcn_global_load_lds((const unsigned*)((const char*)(gbase) + (voff)[_i]), (PG8_LAS unsigned*)(lds + (bufoff) + ldsw + _i * 8192), 16, 0, 0); } while (0)
; #define PG8_LDA(dst, b, h) do { _Pragma("unroll") for (int m = 0; m < 4; ++m) _Pragma("unroll") for (int k = 0; k < 2; ++k) dst[m][k] = *(const PG8_LAS bf16x8*)(lds + PG8_SA(b, h) + aoff + m * 2048 + k * 1024); } while (0)
; #define PG8_LDB(dst, b, h) do { _Pragma("unroll") for (int n = 0; n < 2; ++n) _Pragma("unroll") for (int k = 0; k < 2; ++k) dst[n][k] = *(const PG8_LAS bf16x8*)(lds + PG8_SB(b, h) + boff + n * 2048 + k * 1024); } while (0)
; template <class Epi, class Sched, bool ALIGN_EPI = false, bool SP2 = false>
; __device__ __forceinline__ void gemm_phase(PG8_LAS unsigned char* lds, const Gemm g, const Sched& S, const Epi& E) {
;     ...
;         const bool has_next = S.next(ui + 1, nxt);
;         const char* nA = has_next ? (const char*)g.A + (size_t)nxt.pm * tstep + (size_t)nxt.k0 * 2 : cA; const char* nB = has_next ? (const char*)g.Bt + (size_t)nxt.pn * tstep + (size_t)nxt.k0 * 2 : cB;
;         for (int t = 0; t < nt; t += 2) {
;             const bool last = (t == nt - 2);
;             const char* a1 = cA + (size_t)(t + 1) * kstep;
;             const char* a2 = last ? nA : cA + (size_t)(t + 2) * kstep; const char* b2 = last ? nB : cB + (size_t)(t + 2) * kstep;
;             const char* a3 = a2 + kstep; const char* b3 = b2 + kstep;
;             if (last && has_next) S.a_ready(nxt);
;             if constexpr (SP2) {
;             PG8_LDB(B0, 0, 0); PG8_LDB(B1, 0, 1); PG8_SCHED; PG8_LDA(At, 0, 0); PG8_STAGE(PG8_SA(1, 1), a1 + hstep, voffA);
;             PG8_WAIT_V(8); PG8_WAIT_L(0); PG8_BAR; PG8_MMA(0, 0, At, B0); PG8_MMA(0, 1, At, B1); PG8_BAR; PG8_SCHED;
;             PG8_LDA(At, 0, 1); PG8_STAGE(PG8_SB(0, 0), b2, voffB); PG8_STAGE(PG8_SB(0, 1), b2 + hstep, voffB); PG8_STAGE(PG8_SA(0, 0), a2, voffA);
.LBB0_1231:
	s_add_i32 s56, s48, 2
	s_add_u32 s54, s6, 0x80
	s_addc_u32 s55, s7, 0
	s_add_i32 s57, 0, 0x10000
	s_cmp_eq_u32 s86, s48
	s_cselect_b32 s55, s31, s55
	s_cselect_b32 s54, s30, s54
	s_cselect_b32 s59, s93, s45
	s_cselect_b32 s58, s92, s35
	s_add_i32 s48, 0, 0x14000
	v_add_u32_e32 v152, s57, v195
	v_add_u32_e32 v168, s48, v195
	ds_read_b128 v[140:143], v152
	ds_read_b128 v[144:147], v152 offset:1024
	ds_read_b128 v[148:151], v152 offset:2048
	ds_read_b128 v[152:155], v152 offset:3072
	ds_read_b128 v[156:159], v168
	ds_read_b128 v[160:163], v168 offset:1024
	ds_read_b128 v[164:167], v168 offset:2048
	ds_read_b128 v[168:171], v168 offset:3072
	v_lshl_add_u64 v[176:177], s[6:7], 0, v[136:137]
	s_add_i32 m0, s70, 0xc000
	ds_read_b128 v[172:175], v196
	ds_read_b128 v[198:201], v196 offset:1024
	ds_read_b128 v[202:205], v196 offset:2048
	ds_read_b128 v[206:209], v196 offset:3072
	ds_read_b128 v[210:213], v196 offset:4096
	ds_read_b128 v[214:217], v196 offset:5120
	ds_read_b128 v[234:237], v196 offset:6144
	ds_read_b128 v[238:241], v196 offset:7168
	global_load_lds_dwordx4 v[176:177], off
	v_lshl_add_u64 v[176:177], s[6:7], 0, v[138:139]
	s_add_i32 m0, s70, 0xe000
	s_nop 0
	global_load_lds_dwordx4 v[176:177], off
	s_waitcnt vmcnt(8)
	s_waitcnt lgkmcnt(0)
	s_barrier
	s_setprio 1
	s_waitcnt lgkmcnt(0)
	v_mfma_f32_16x16x32_bf16 v[126:129], v[140:143], v[172:175], v[126:129]
	v_mfma_f32_16x16x32_bf16 v[122:125], v[148:151], v[172:175], v[122:125]
	v_mfma_f32_16x16x32_bf16 v[110:113], v[140:143], v[202:205], v[110:113]
	v_mfma_f32_16x16x32_bf16 v[106:109], v[148:151], v[202:205], v[106:109]
	v_mfma_f32_16x16x32_bf16 v[94:97], v[140:143], v[210:213], v[94:97]
	v_mfma_f32_16x16x32_bf16 v[90:93], v[148:151], v[210:213], v[90:93]
	v_mfma_f32_16x16x32_bf16 v[78:81], v[140:143], v[234:237], v[78:81]
	v_mfma_f32_16x16x32_bf16 v[74:77], v[148:151], v[234:237], v[74:77]
	v_mfma_f32_16x16x32_bf16 v[126:129], v[144:147], v[198:201], v[126:129]
	v_mfma_f32_16x16x32_bf16 v[122:125], v[152:155], v[198:201], v[122:125]
	v_mfma_f32_16x16x32_bf16 v[110:113], v[144:147], v[206:209], v[110:113]
	v_mfma_f32_16x16x32_bf16 v[106:109], v[152:155], v[206:209], v[106:109]
	v_mfma_f32_16x16x32_bf16 v[94:97], v[144:147], v[214:217], v[94:97]
	v_mfma_f32_16x16x32_bf16 v[90:93], v[152:155], v[214:217], v[90:93]
	v_mfma_f32_16x16x32_bf16 v[78:81], v[144:147], v[238:241], v[78:81]
	v_mfma_f32_16x16x32_bf16 v[74:77], v[152:155], v[238:241], v[74:77]
	v_mfma_f32_16x16x32_bf16 v[118:121], v[156:159], v[172:175], v[118:121]
	v_mfma_f32_16x16x32_bf16 v[114:117], v[164:167], v[172:175], v[114:117]
	v_mfma_f32_16x16x32_bf16 v[102:105], v[156:159], v[202:205], v[102:105]
	v_mfma_f32_16x16x32_bf16 v[98:101], v[164:167], v[202:205], v[98:101]
	v_mfma_f32_16x16x32_bf16 v[86:89], v[156:159], v[210:213], v[86:89]
	v_mfma_f32_16x16x32_bf16 v[82:85], v[164:167], v[210:213], v[82:85]
	v_mfma_f32_16x16x32_bf16 v[70:73], v[156:159], v[234:237], v[70:73]
	v_mfma_f32_16x16x32_bf16 v[66:69], v[164:167], v[234:237], v[66:69]
	v_mfma_f32_16x16x32_bf16 v[118:121], v[160:163], v[198:201], v[118:121]
	v_mfma_f32_16x16x32_bf16 v[114:117], v[168:171], v[198:201], v[114:117]
	v_mfma_f32_16x16x32_bf16 v[102:105], v[160:163], v[206:209], v[102:105]
	v_mfma_f32_16x16x32_bf16 v[98:101], v[168:171], v[206:209], v[98:101]
	v_mfma_f32_16x16x32_bf16 v[86:89], v[160:163], v[214:217], v[86:89]
	v_mfma_f32_16x16x32_bf16 v[82:85], v[168:171], v[214:217], v[82:85]
	v_mfma_f32_16x16x32_bf16 v[70:73], v[160:163], v[238:241], v[70:73]
	v_mfma_f32_16x16x32_bf16 v[66:69], v[168:171], v[238:241], v[66:69]
	s_setprio 0
	s_barrier
	s_add_i32 s57, s57, s69
	v_lshl_add_u64 v[176:177], s[58:59], 0, v[0:1]
	s_mov_b32 m0, s57
	ds_read_b128 v[172:175], v196 offset:16384
	ds_read_b128 v[198:201], v196 offset:17408
	ds_read_b128 v[202:205], v196 offset:18432
	ds_read_b128 v[206:209], v196 offset:19456
	ds_read_b128 v[210:213], v196 offset:20480
	ds_read_b128 v[214:217], v196 offset:21504
	ds_read_b128 v[234:237], v196 offset:22528
	ds_read_b128 v[238:241], v196 offset:23552
	global_load_lds_dwordx4 v[176:177], off
	s_add_i32 m0, s57, 0x2000
	v_lshl_add_u64 v[222:223], s[58:59], 0, v[134:135]
	s_add_u32 s58, s58, s8
	s_addc_u32 s59, s59, s9
	s_add_i32 s48, s48, s69
	global_load_lds_dwordx4 v[222:223], off
	v_lshl_add_u64 v[232:233], s[58:59], 0, v[0:1]
	s_mov_b32 m0, s48
	v_lshl_add_u64 v[242:243], s[58:59], 0, v[134:135]
	global_load_lds_dwordx4 v[232:233], off
	s_add_i32 m0, s48, 0x2000
	v_lshl_add_u64 v[244:245], s[54:55], 0, v[130:131]
	global_load_lds_dwordx4 v[242:243], off
	s_mov_b32 m0, s70
	v_lshl_add_u64 v[246:247], s[54:55], 0, v[132:133]
	global_load_lds_dwordx4 v[244:245], off
	s_mov_b32 m0, s71
	s_nop 0
	global_load_lds_dwordx4 v[246:247], off
	s_waitcnt vmcnt(8)
	s_waitcnt lgkmcnt(0)
	s_barrier
; #define PG8_STAGE(bufoff, gbase, voff) do { _Pragma("unroll") for (int _i = 0; _i < 2; ++_i) \
;         __builtin_amdgcn_global_load_lds((const unsigned*)((const char*)(gbase) + (voff)[_i]), (PG8_LAS unsigned*)(lds + (bufoff) + ldsw + _i * 8192), 16, 0, 0); } while (0)
; #define PG8_LDA(dst, b, h) do { _Pragma("unroll") for (int m = 0; m < 4; ++m) _Pragma("unroll") for (int k = 0; k < 2; ++k) dst[m][k] = *(const PG8_LAS bf16x8*)(lds + PG8_SA(b, h) + aoff + m * 2048 + k * 1024); } while (0)
; #define PG8_LDB(dst, b, h) do { _Pragma("unroll") for (int n = 0; n < 2; ++n) _Pragma("unroll") for (int k = 0; k < 2; ++k) dst[n][k] = *(const PG8_LAS bf16x8*)(lds + PG8_SB(b, h) + boff + n * 2048 + k * 1024); } while (0)
; #define PG8_MMA(ai, bj, At, Bt) do { __builtin_amdgcn_s_setprio(1); _Pragma("unroll") for (int m = 0; m < 4; ++m) _Pragma("unroll") for (int n = 0; n < 2; ++n) _Pragma("unroll") for (int k = 0; k < 2; ++k) \
;         acc[ai][bj][m][n] = __builtin_amdgcn_mfma_f32_16x16x32_bf16(Bt[n][k], At[m][k], acc[ai][bj][m][n], 0, 0, 0); __builtin_amdgcn_s_setprio(0); } while (0)
; #define PG8_WAIT_V(n) asm volatile("s_waitcnt vmcnt(" #n ")" ::: "memory")
; #define PG8_WAIT_L(n) asm volatile("s_waitcnt lgkmcnt(" #n ")" ::: "memory")
; #define PG8_BAR __builtin_amdgcn_s_barrier()
; #define PG8_SCHED __builtin_amdgcn_sched_barrier(0)
; template <class Epi, class Sched, bool ALIGN_EPI = false, bool SP2 = false>
; __device__ __forceinline__ void gemm_phase(PG8_LAS unsigned char* lds, const Gemm g, const Sched& S, const Epi& E) {
;     ...
;             PG8_WAIT_V(8); PG8_WAIT_L(0); PG8_BAR; PG8_MMA(1, 0, At, B0); PG8_MMA(1, 1, At, B1); PG8_BAR; PG8_SCHED;
;             PG8_LDB(B0, 1, 0); PG8_LDB(B1, 1, 1); PG8_SCHED; PG8_LDA(At, 1, 0); PG8_STAGE(PG8_SA(0, 1), a2 + hstep, voffA);
;             PG8_WAIT_V(8); PG8_WAIT_L(0); PG8_BAR; PG8_MMA(0, 0, At, B0); PG8_MMA(0, 1, At, B1); PG8_BAR; PG8_SCHED;
	s_setprio 1
	s_waitcnt lgkmcnt(0)
	v_mfma_f32_16x16x32_bf16 v[62:65], v[140:143], v[172:175], v[62:65]
	v_mfma_f32_16x16x32_bf16 v[58:61], v[148:151], v[172:175], v[58:61]
	v_mfma_f32_16x16x32_bf16 v[46:49], v[140:143], v[202:205], v[46:49]
	v_mfma_f32_16x16x32_bf16 v[42:45], v[148:151], v[202:205], v[42:45]
	v_mfma_f32_16x16x32_bf16 v[30:33], v[140:143], v[210:213], v[30:33]
	v_mfma_f32_16x16x32_bf16 v[26:29], v[148:151], v[210:213], v[26:29]
	v_mfma_f32_16x16x32_bf16 v[14:17], v[140:143], v[234:237], v[14:17]
	v_mfma_f32_16x16x32_bf16 v[10:13], v[148:151], v[234:237], v[10:13]
	v_mfma_f32_16x16x32_bf16 v[62:65], v[144:147], v[198:201], v[62:65]
	v_mfma_f32_16x16x32_bf16 v[58:61], v[152:155], v[198:201], v[58:61]
	v_mfma_f32_16x16x32_bf16 v[46:49], v[144:147], v[206:209], v[46:49]
	v_mfma_f32_16x16x32_bf16 v[42:45], v[152:155], v[206:209], v[42:45]
	v_mfma_f32_16x16x32_bf16 v[30:33], v[144:147], v[214:217], v[30:33]
	v_mfma_f32_16x16x32_bf16 v[26:29], v[152:155], v[214:217], v[26:29]
	v_mfma_f32_16x16x32_bf16 v[14:17], v[144:147], v[238:241], v[14:17]
	v_mfma_f32_16x16x32_bf16 v[10:13], v[152:155], v[238:241], v[10:13]
	v_mfma_f32_16x16x32_bf16 v[54:57], v[156:159], v[172:175], v[54:57]
	v_mfma_f32_16x16x32_bf16 v[50:53], v[164:167], v[172:175], v[50:53]
	v_mfma_f32_16x16x32_bf16 v[38:41], v[156:159], v[202:205], v[38:41]
	v_mfma_f32_16x16x32_bf16 v[34:37], v[164:167], v[202:205], v[34:37]
	v_mfma_f32_16x16x32_bf16 v[22:25], v[156:159], v[210:213], v[22:25]
	v_mfma_f32_16x16x32_bf16 v[18:21], v[164:167], v[210:213], v[18:21]
	v_mfma_f32_16x16x32_bf16 v[6:9], v[156:159], v[234:237], v[6:9]
	v_mfma_f32_16x16x32_bf16 v[2:5], v[164:167], v[234:237], v[2:5]
	v_mfma_f32_16x16x32_bf16 v[54:57], v[160:163], v[198:201], v[54:57]
	v_mfma_f32_16x16x32_bf16 v[50:53], v[168:171], v[198:201], v[50:53]
	v_mfma_f32_16x16x32_bf16 v[38:41], v[160:163], v[206:209], v[38:41]
	v_mfma_f32_16x16x32_bf16 v[34:37], v[168:171], v[206:209], v[34:37]
	v_mfma_f32_16x16x32_bf16 v[22:25], v[160:163], v[214:217], v[22:25]
	v_mfma_f32_16x16x32_bf16 v[18:21], v[168:171], v[214:217], v[18:21]
	v_mfma_f32_16x16x32_bf16 v[6:9], v[160:163], v[238:241], v[6:9]
	v_mfma_f32_16x16x32_bf16 v[2:5], v[168:171], v[238:241], v[2:5]
	s_setprio 0
	s_barrier
	s_add_i32 s48, 0, 0x18000
	s_add_i32 s57, 0, 0x1c000
	v_add_u32_e32 v152, s48, v195
	v_add_u32_e32 v168, s57, v195
	ds_read_b128 v[140:143], v152
	ds_read_b128 v[144:147], v152 offset:1024
	ds_read_b128 v[148:151], v152 offset:2048
	ds_read_b128 v[152:155], v152 offset:3072
	ds_read_b128 v[156:159], v168
	ds_read_b128 v[160:163], v168 offset:1024
	ds_read_b128 v[164:167], v168 offset:2048
	ds_read_b128 v[168:171], v168 offset:3072
	s_add_u32 s54, s54, s8
	s_addc_u32 s55, s55, s9
	s_mov_b32 m0, s73
	v_lshl_add_u64 v[248:249], s[54:55], 0, v[130:131]
	ds_read_b128 v[172:175], v196 offset:32768
	ds_read_b128 v[198:201], v196 offset:33792
	ds_read_b128 v[202:205], v196 offset:34816
	ds_read_b128 v[206:209], v196 offset:35840
	ds_read_b128 v[210:213], v196 offset:36864
	ds_read_b128 v[214:217], v196 offset:37888
	ds_read_b128 v[234:237], v196 offset:38912
	ds_read_b128 v[238:241], v196 offset:39936
	global_load_lds_dwordx4 v[248:249], off
	v_lshl_add_u64 v[248:249], s[54:55], 0, v[132:133]
	s_mov_b32 m0, s78
	s_nop 0
	global_load_lds_dwordx4 v[248:249], off
	s_waitcnt vmcnt(8)
	s_waitcnt lgkmcnt(0)
	s_barrier
	s_setprio 1
	s_waitcnt lgkmcnt(0)
	v_mfma_f32_16x16x32_bf16 v[126:129], v[140:143], v[172:175], v[126:129]
	v_mfma_f32_16x16x32_bf16 v[122:125], v[148:151], v[172:175], v[122:125]
	v_mfma_f32_16x16x32_bf16 v[110:113], v[140:143], v[202:205], v[110:113]
	v_mfma_f32_16x16x32_bf16 v[106:109], v[148:151], v[202:205], v[106:109]
	v_mfma_f32_16x16x32_bf16 v[94:97], v[140:143], v[210:213], v[94:97]
	v_mfma_f32_16x16x32_bf16 v[90:93], v[148:151], v[210:213], v[90:93]
	v_mfma_f32_16x16x32_bf16 v[78:81], v[140:143], v[234:237], v[78:81]
	v_mfma_f32_16x16x32_bf16 v[74:77], v[148:151], v[234:237], v[74:77]
	v_mfma_f32_16x16x32_bf16 v[126:129], v[144:147], v[198:201], v[126:129]
	v_mfma_f32_16x16x32_bf16 v[122:125], v[152:155], v[198:201], v[122:125]
	v_mfma_f32_16x16x32_bf16 v[110:113], v[144:147], v[206:209], v[110:113]
	v_mfma_f32_16x16x32_bf16 v[106:109], v[152:155], v[206:209], v[106:109]
	v_mfma_f32_16x16x32_bf16 v[94:97], v[144:147], v[214:217], v[94:97]
	v_mfma_f32_16x16x32_bf16 v[90:93], v[152:155], v[214:217], v[90:93]
	v_mfma_f32_16x16x32_bf16 v[78:81], v[144:147], v[238:241], v[78:81]
	v_mfma_f32_16x16x32_bf16 v[74:77], v[152:155], v[238:241], v[74:77]
	v_mfma_f32_16x16x32_bf16 v[118:121], v[156:159], v[172:175], v[118:121]
	v_mfma_f32_16x16x32_bf16 v[114:117], v[164:167], v[172:175], v[114:117]
	v_mfma_f32_16x16x32_bf16 v[102:105], v[156:159], v[202:205], v[102:105]
	v_mfma_f32_16x16x32_bf16 v[98:101], v[164:167], v[202:205], v[98:101]
	v_mfma_f32_16x16x32_bf16 v[86:89], v[156:159], v[210:213], v[86:89]
	v_mfma_f32_16x16x32_bf16 v[82:85], v[164:167], v[210:213], v[82:85]
	v_mfma_f32_16x16x32_bf16 v[70:73], v[156:159], v[234:237], v[70:73]
	v_mfma_f32_16x16x32_bf16 v[66:69], v[164:167], v[234:237], v[66:69]
	v_mfma_f32_16x16x32_bf16 v[118:121], v[160:163], v[198:201], v[118:121]
	v_mfma_f32_16x16x32_bf16 v[114:117], v[168:171], v[198:201], v[114:117]
	v_mfma_f32_16x16x32_bf16 v[102:105], v[160:163], v[206:209], v[102:105]
	v_mfma_f32_16x16x32_bf16 v[98:101], v[168:171], v[206:209], v[98:101]
	v_mfma_f32_16x16x32_bf16 v[86:89], v[160:163], v[214:217], v[86:89]
	v_mfma_f32_16x16x32_bf16 v[82:85], v[168:171], v[214:217], v[82:85]
	v_mfma_f32_16x16x32_bf16 v[70:73], v[160:163], v[238:241], v[70:73]
	v_mfma_f32_16x16x32_bf16 v[66:69], v[168:171], v[238:241], v[66:69]
	s_setprio 0
	s_barrier
; #define PG8_STAGE(bufoff, gbase, voff) do { _Pragma("unroll") for (int _i = 0; _i < 2; ++_i) \
;         __builtin_amdgcn_global_load_lds((const unsigned*)((const char*)(gbase) + (voff)[_i]), (PG8_LAS unsigned*)(lds + (bufoff) + ldsw + _i * 8192), 16, 0, 0); } while (0)
; #define PG8_LDA(dst, b, h) do { _Pragma("unroll") for (int m = 0; m < 4; ++m) _Pragma("unroll") for (int k = 0; k < 2; ++k) dst[m][k] = *(const PG8_LAS bf16x8*)(lds + PG8_SA(b, h) + aoff + m * 2048 + k * 1024); } while (0)
; #define PG8_MMA(ai, bj, At, Bt) do { __builtin_amdgcn_s_setprio(1); _Pragma("unroll") for (int m = 0; m < 4; ++m) _Pragma("unroll") for (int n = 0; n < 2; ++n) _Pragma("unroll") for (int k = 0; k < 2; ++k) \
;         acc[ai][bj][m][n] = __builtin_amdgcn_mfma_f32_16x16x32_bf16(Bt[n][k], At[m][k], acc[ai][bj][m][n], 0, 0, 0); __builtin_amdgcn_s_setprio(0); } while (0)
; #define PG8_WAIT_V(n) asm volatile("s_waitcnt vmcnt(" #n ")" ::: "memory")
; #define PG8_WAIT_L(n) asm volatile("s_waitcnt lgkmcnt(" #n ")" ::: "memory")
; #define PG8_BAR __builtin_amdgcn_s_barrier()
; #define PG8_SCHED __builtin_amdgcn_sched_barrier(0)
; template <class Epi, class Sched, bool ALIGN_EPI = false, bool SP2 = false>
; __device__ __forceinline__ void gemm_phase(PG8_LAS unsigned char* lds, const Gemm g, const Sched& S, const Epi& E) {
;     ...
;         for (int t = 0; t < nt; t += 2) {
;     ...
;             PG8_LDA(At, 1, 1); PG8_STAGE(PG8_SB(1, 0), b3, voffB); PG8_STAGE(PG8_SB(1, 1), b3 + hstep, voffB); PG8_STAGE(PG8_SA(1, 0), a3, voffA);
;             PG8_WAIT_V(8); PG8_WAIT_L(0); PG8_BAR; PG8_MMA(1, 0, At, B0); PG8_MMA(1, 1, At, B1); PG8_BAR; PG8_SCHED;
	s_add_i32 s48, s48, s69
	v_lshl_add_u64 v[176:177], v[176:177], 0, s[52:53]
	s_mov_b32 m0, s48
	ds_read_b128 v[172:175], v196 offset:49152
	ds_read_b128 v[198:201], v196 offset:50176
	ds_read_b128 v[202:205], v196 offset:51200
	ds_read_b128 v[206:209], v196 offset:52224
	ds_read_b128 v[210:213], v196 offset:53248
	ds_read_b128 v[214:217], v196 offset:54272
	ds_read_b128 v[234:237], v196 offset:55296
	ds_read_b128 v[238:241], v196 offset:56320
	global_load_lds_dwordx4 v[176:177], off
	v_lshl_add_u64 v[176:177], v[222:223], 0, s[52:53]
	s_add_i32 m0, s48, 0x2000
	s_add_i32 s48, s57, s69
	global_load_lds_dwordx4 v[176:177], off
	v_lshl_add_u64 v[176:177], v[232:233], 0, s[52:53]
	s_mov_b32 m0, s48
	s_nop 0
	global_load_lds_dwordx4 v[176:177], off
	v_lshl_add_u64 v[176:177], v[242:243], 0, s[52:53]
	s_add_i32 m0, s48, 0x2000
	s_nop 0
	global_load_lds_dwordx4 v[176:177], off
	v_lshl_add_u64 v[176:177], v[244:245], 0, s[52:53]
	s_mov_b32 m0, s79
	s_nop 0
	global_load_lds_dwordx4 v[176:177], off
	v_lshl_add_u64 v[176:177], v[246:247], 0, s[52:53]
	s_mov_b32 m0, s82
	s_nop 0
	global_load_lds_dwordx4 v[176:177], off
	s_waitcnt vmcnt(8)
	s_waitcnt lgkmcnt(0)
	s_barrier
	s_setprio 1
	s_waitcnt lgkmcnt(0)
	v_mfma_f32_16x16x32_bf16 v[62:65], v[140:143], v[172:175], v[62:65]
	v_mfma_f32_16x16x32_bf16 v[58:61], v[148:151], v[172:175], v[58:61]
	v_mfma_f32_16x16x32_bf16 v[46:49], v[140:143], v[202:205], v[46:49]
	v_mfma_f32_16x16x32_bf16 v[42:45], v[148:151], v[202:205], v[42:45]
	v_mfma_f32_16x16x32_bf16 v[30:33], v[140:143], v[210:213], v[30:33]
	v_mfma_f32_16x16x32_bf16 v[26:29], v[148:151], v[210:213], v[26:29]
	v_mfma_f32_16x16x32_bf16 v[14:17], v[140:143], v[234:237], v[14:17]
	v_mfma_f32_16x16x32_bf16 v[10:13], v[148:151], v[234:237], v[10:13]
	v_mfma_f32_16x16x32_bf16 v[62:65], v[144:147], v[198:201], v[62:65]
	v_mfma_f32_16x16x32_bf16 v[58:61], v[152:155], v[198:201], v[58:61]
	v_mfma_f32_16x16x32_bf16 v[46:49], v[144:147], v[206:209], v[46:49]
	v_mfma_f32_16x16x32_bf16 v[42:45], v[152:155], v[206:209], v[42:45]
	v_mfma_f32_16x16x32_bf16 v[30:33], v[144:147], v[214:217], v[30:33]
	v_mfma_f32_16x16x32_bf16 v[26:29], v[152:155], v[214:217], v[26:29]
	v_mfma_f32_16x16x32_bf16 v[14:17], v[144:147], v[238:241], v[14:17]
	v_mfma_f32_16x16x32_bf16 v[10:13], v[152:155], v[238:241], v[10:13]
	v_mfma_f32_16x16x32_bf16 v[54:57], v[156:159], v[172:175], v[54:57]
	v_mfma_f32_16x16x32_bf16 v[50:53], v[164:167], v[172:175], v[50:53]
	v_mfma_f32_16x16x32_bf16 v[38:41], v[156:159], v[202:205], v[38:41]
	v_mfma_f32_16x16x32_bf16 v[34:37], v[164:167], v[202:205], v[34:37]
	v_mfma_f32_16x16x32_bf16 v[22:25], v[156:159], v[210:213], v[22:25]
	v_mfma_f32_16x16x32_bf16 v[18:21], v[164:167], v[210:213], v[18:21]
	v_mfma_f32_16x16x32_bf16 v[6:9], v[156:159], v[234:237], v[6:9]
	v_mfma_f32_16x16x32_bf16 v[2:5], v[164:167], v[234:237], v[2:5]
	v_mfma_f32_16x16x32_bf16 v[54:57], v[160:163], v[198:201], v[54:57]
	v_mfma_f32_16x16x32_bf16 v[50:53], v[168:171], v[198:201], v[50:53]
	v_mfma_f32_16x16x32_bf16 v[38:41], v[160:163], v[206:209], v[38:41]
	v_mfma_f32_16x16x32_bf16 v[34:37], v[168:171], v[206:209], v[34:37]
	v_mfma_f32_16x16x32_bf16 v[22:25], v[160:163], v[214:217], v[22:25]
	v_mfma_f32_16x16x32_bf16 v[18:21], v[168:171], v[214:217], v[18:21]
	v_mfma_f32_16x16x32_bf16 v[6:9], v[160:163], v[238:241], v[6:9]
	v_mfma_f32_16x16x32_bf16 v[2:5], v[168:171], v[238:241], v[2:5]
	s_setprio 0
	s_barrier
	s_add_u32 s6, s6, 0x100
	s_addc_u32 s7, s7, 0
	s_add_u32 s35, s35, 0x100
	s_addc_u32 s45, s45, 0
	s_cmp_ge_i32 s56, s83
	s_mov_b32 s48, s56
	s_cbranch_scc0 .LBB0_1231
	s_mov_b32 s56, 0xc00000
	s_mov_b32 s57, 0xe00000

;     __device__ bool next(int i, Unit& u) const { const int L = i * G + c; if (L >= 33 * 16) return false; const int pnv = L & 15, pm = L >> 4; u.pm = (pnv >> 1) * 33 + pm; u.pn = pnv; return true; }
;     __device__ bool next(int i, Unit& u) const { const int L = i * G + c; if (L >= npn * nsl) return false; u.pm = 32; u.pn = L % npn; u.k0 = (L / npn) * 256; return true; }
; #define PG8_STAGE(bufoff, gbase, voff) do { _Pragma("unroll") for (int _i = 0; _i < 2; ++_i) \
;         __builtin_amdgcn_global_load_lds((const unsigned*)((const char*)(gbase) + (voff)[_i]), (PG8_LAS unsigned*)(lds + (bufoff) + ldsw + _i * 8192), 16, 0, 0); } while (0)
; #define PG8_LDA(dst, b, h) do { _Pragma("unroll") for (int m = 0; m < 4; ++m) _Pragma("unroll") for (int k = 0; k < 2; ++k) dst[m][k] = *(const PG8_LAS bf16x8*)(lds + PG8_SA(b, h) + aoff + m * 2048 + k * 1024); } while (0)
; #define PG8_LDB(dst, b, h) do { _Pragma("unroll") for (int n = 0; n < 2; ++n) _Pragma("unroll") for (int k = 0; k < 2; ++k) dst[n][k] = *(const PG8_LAS bf16x8*)(lds + PG8_SB(b, h) + boff + n * 2048 + k * 1024); } while (0)
; template <class Epi, class Sched, bool ALIGN_EPI = false, bool SP2 = false>
; __device__ __forceinline__ void gemm_phase(PG8_LAS unsigned char* lds, const Gemm g, const Sched& S, const Epi& E) {
;     ...
;         const bool has_next = S.next(ui + 1, nxt);
;         const char* nA = has_next ? (const char*)g.A + (size_t)nxt.pm * tstep + (size_t)nxt.k0 * 2 : cA; const char* nB = has_next ? (const char*)g.Bt + (size_t)nxt.pn * tstep + (size_t)nxt.k0 * 2 : cB;
;         for (int t = 0; t < nt; t += 2) {
;             const bool last = (t == nt - 2);
;             const char* a1 = cA + (size_t)(t + 1) * kstep;
;             const char* a2 = last ? nA : cA + (size_t)(t + 2) * kstep; const char* b2 = last ? nB : cB + (size_t)(t + 2) * kstep;
;             const char* a3 = a2 + kstep; const char* b3 = b2 + kstep;
;             if (last && has_next) S.a_ready(nxt);
;             if constexpr (SP2) {
;             PG8_LDB(B0, 0, 0); PG8_LDB(B1, 0, 1); PG8_SCHED; PG8_LDA(At, 0, 0); PG8_STAGE(PG8_SA(1, 1), a1 + hstep, voffA);
;             PG8_WAIT_V(8); PG8_WAIT_L(0); PG8_BAR; PG8_MMA(0, 0, At, B0); PG8_MMA(0, 1, At, B1); PG8_BAR; PG8_SCHED;
;             PG8_LDA(At, 0, 1); PG8_STAGE(PG8_SB(0, 0), b2, voffB); PG8_STAGE(PG8_SB(0, 1), b2 + hstep, voffB); PG8_STAGE(PG8_SA(0, 0), a2, voffA);
.LBB0_1463:
	s_add_i32 s56, s54, 2
	s_add_u32 s57, s6, 0x80
	s_addc_u32 s55, s7, 0
	s_add_i32 s66, 0, 0x10000
	s_cmp_eq_u32 s24, s54
	s_cselect_b32 s55, s95, s55
	s_cselect_b32 s54, s94, s57
	v_add_u32_e32 v0, s66, v213
	s_cselect_b32 s59, s97, s45
	s_cselect_b32 s58, s96, s35
	s_add_i32 s57, 0, 0x14000
	ds_read_b128 v[82:85], v0
	ds_read_b128 v[86:89], v0 offset:1024
	ds_read_b128 v[94:97], v0 offset:2048
	ds_read_b128 v[154:157], v0 offset:3072
	v_add_u32_e32 v0, s57, v213
	ds_read_b128 v[158:161], v0
	ds_read_b128 v[162:165], v0 offset:1024
	ds_read_b128 v[166:169], v0 offset:2048
	ds_read_b128 v[170:173], v0 offset:3072
	v_lshl_add_u64 v[210:211], s[6:7], 0, v[150:151]
	s_add_i32 m0, s79, 0xc000
	ds_read_b128 v[174:177], v214
	ds_read_b128 v[194:197], v214 offset:1024
	ds_read_b128 v[198:201], v214 offset:2048
	ds_read_b128 v[202:205], v214 offset:3072
	ds_read_b128 v[206:209], v214 offset:4096
	ds_read_b128 v[234:237], v214 offset:5120
	ds_read_b128 v[238:241], v214 offset:6144
	ds_read_b128 v[242:245], v214 offset:7168
	global_load_lds_dwordx4 v[210:211], off
	v_lshl_add_u64 v[210:211], s[6:7], 0, v[152:153]
	s_add_i32 m0, s79, 0xe000
	s_nop 0
	global_load_lds_dwordx4 v[210:211], off
	s_waitcnt vmcnt(8)
	s_waitcnt lgkmcnt(0)
	s_barrier
	s_setprio 1
	s_waitcnt lgkmcnt(0)
	v_mfma_f32_16x16x32_bf16 v[138:141], v[82:85], v[174:177], v[138:141]
	v_mfma_f32_16x16x32_bf16 v[62:65], v[94:97], v[174:177], v[62:65]
	v_mfma_f32_16x16x32_bf16 v[130:133], v[82:85], v[198:201], v[130:133]
	v_mfma_f32_16x16x32_bf16 v[54:57], v[94:97], v[198:201], v[54:57]
	v_mfma_f32_16x16x32_bf16 v[122:125], v[82:85], v[206:209], v[122:125]
	v_mfma_f32_16x16x32_bf16 v[46:49], v[94:97], v[206:209], v[46:49]
	v_mfma_f32_16x16x32_bf16 v[114:117], v[82:85], v[238:241], v[114:117]
	v_mfma_f32_16x16x32_bf16 v[38:41], v[94:97], v[238:241], v[38:41]
	v_mfma_f32_16x16x32_bf16 v[138:141], v[86:89], v[194:197], v[138:141]
	v_mfma_f32_16x16x32_bf16 v[62:65], v[154:157], v[194:197], v[62:65]
	v_mfma_f32_16x16x32_bf16 v[130:133], v[86:89], v[202:205], v[130:133]
	v_mfma_f32_16x16x32_bf16 v[54:57], v[154:157], v[202:205], v[54:57]
	v_mfma_f32_16x16x32_bf16 v[122:125], v[86:89], v[234:237], v[122:125]
	v_mfma_f32_16x16x32_bf16 v[46:49], v[154:157], v[234:237], v[46:49]
	v_mfma_f32_16x16x32_bf16 v[114:117], v[86:89], v[242:245], v[114:117]
	v_mfma_f32_16x16x32_bf16 v[38:41], v[154:157], v[242:245], v[38:41]
	v_mfma_f32_16x16x32_bf16 v[134:137], v[158:161], v[174:177], v[134:137]
	v_mfma_f32_16x16x32_bf16 v[58:61], v[166:169], v[174:177], v[58:61]
	v_mfma_f32_16x16x32_bf16 v[126:129], v[158:161], v[198:201], v[126:129]
	v_mfma_f32_16x16x32_bf16 v[50:53], v[166:169], v[198:201], v[50:53]
	v_mfma_f32_16x16x32_bf16 v[118:121], v[158:161], v[206:209], v[118:121]
	v_mfma_f32_16x16x32_bf16 v[42:45], v[166:169], v[206:209], v[42:45]
	v_mfma_f32_16x16x32_bf16 v[110:113], v[158:161], v[238:241], v[110:113]
	v_mfma_f32_16x16x32_bf16 v[34:37], v[166:169], v[238:241], v[34:37]
	v_mfma_f32_16x16x32_bf16 v[134:137], v[162:165], v[194:197], v[134:137]
	v_mfma_f32_16x16x32_bf16 v[58:61], v[170:173], v[194:197], v[58:61]
	v_mfma_f32_16x16x32_bf16 v[126:129], v[162:165], v[202:205], v[126:129]
	v_mfma_f32_16x16x32_bf16 v[50:53], v[170:173], v[202:205], v[50:53]
	v_mfma_f32_16x16x32_bf16 v[118:121], v[162:165], v[234:237], v[118:121]
	v_mfma_f32_16x16x32_bf16 v[42:45], v[170:173], v[234:237], v[42:45]
	v_mfma_f32_16x16x32_bf16 v[110:113], v[162:165], v[242:245], v[110:113]
	v_mfma_f32_16x16x32_bf16 v[34:37], v[170:173], v[242:245], v[34:37]
	s_setprio 0
	s_barrier
	s_add_i32 s66, s66, s78
	v_lshl_add_u64 v[210:211], s[58:59], 0, v[146:147]
	s_mov_b32 m0, s66
	ds_read_b128 v[174:177], v214 offset:16384
	ds_read_b128 v[194:197], v214 offset:17408
	ds_read_b128 v[198:201], v214 offset:18432
	ds_read_b128 v[202:205], v214 offset:19456
	ds_read_b128 v[206:209], v214 offset:20480
	ds_read_b128 v[234:237], v214 offset:21504
	ds_read_b128 v[238:241], v214 offset:22528
	ds_read_b128 v[242:245], v214 offset:23552
	global_load_lds_dwordx4 v[210:211], off
	s_add_i32 m0, s66, 0x2000
	v_lshl_add_u64 v[216:217], s[58:59], 0, v[142:143]
	s_add_u32 s58, s58, s12
	s_addc_u32 s59, s59, s13
	s_add_i32 s57, s57, s78
	global_load_lds_dwordx4 v[216:217], off
	v_lshl_add_u64 v[222:223], s[58:59], 0, v[146:147]
	s_mov_b32 m0, s57
	v_lshl_add_u64 v[232:233], s[58:59], 0, v[142:143]
	global_load_lds_dwordx4 v[222:223], off
	s_add_i32 m0, s57, 0x2000
	v_lshl_add_u64 v[246:247], s[54:55], 0, v[148:149]
	global_load_lds_dwordx4 v[232:233], off
	s_mov_b32 m0, s79
	v_lshl_add_u64 v[248:249], s[54:55], 0, v[144:145]
	global_load_lds_dwordx4 v[246:247], off
	s_mov_b32 m0, s82
	s_nop 0
	global_load_lds_dwordx4 v[248:249], off
	s_waitcnt vmcnt(8)
	s_waitcnt lgkmcnt(0)
	s_barrier
; #define PG8_STAGE(bufoff, gbase, voff) do { _Pragma("unroll") for (int _i = 0; _i < 2; ++_i) \
;         __builtin_amdgcn_global_load_lds((const unsigned*)((const char*)(gbase) + (voff)[_i]), (PG8_LAS unsigned*)(lds + (bufoff) + ldsw + _i * 8192), 16, 0, 0); } while (0)
; #define PG8_LDA(dst, b, h) do { _Pragma("unroll") for (int m = 0; m < 4; ++m) _Pragma("unroll") for (int k = 0; k < 2; ++k) dst[m][k] = *(const PG8_LAS bf16x8*)(lds + PG8_SA(b, h) + aoff + m * 2048 + k * 1024); } while (0)
; #define PG8_LDB(dst, b, h) do { _Pragma("unroll") for (int n = 0; n < 2; ++n) _Pragma("unroll") for (int k = 0; k < 2; ++k) dst[n][k] = *(const PG8_LAS bf16x8*)(lds + PG8_SB(b, h) + boff + n * 2048 + k * 1024); } while (0)
; #define PG8_MMA(ai, bj, At, Bt) do { __builtin_amdgcn_s_setprio(1); _Pragma("unroll") for (int m = 0; m < 4; ++m) _Pragma("unroll") for (int n = 0; n < 2; ++n) _Pragma("unroll") for (int k = 0; k < 2; ++k) \
;         acc[ai][bj][m][n] = __builtin_amdgcn_mfma_f32_16x16x32_bf16(Bt[n][k], At[m][k], acc[ai][bj][m][n], 0, 0, 0); __builtin_amdgcn_s_setprio(0); } while (0)
; #define PG8_WAIT_V(n) asm volatile("s_waitcnt vmcnt(" #n ")" ::: "memory")
; #define PG8_WAIT_L(n) asm volatile("s_waitcnt lgkmcnt(" #n ")" ::: "memory")
; #define PG8_BAR __builtin_amdgcn_s_barrier()
; #define PG8_SCHED __builtin_amdgcn_sched_barrier(0)
; template <class Epi, class Sched, bool ALIGN_EPI = false, bool SP2 = false>
; __device__ __forceinline__ void gemm_phase(PG8_LAS unsigned char* lds, const Gemm g, const Sched& S, const Epi& E) {
;     ...
;             PG8_WAIT_V(8); PG8_WAIT_L(0); PG8_BAR; PG8_MMA(1, 0, At, B0); PG8_MMA(1, 1, At, B1); PG8_BAR; PG8_SCHED;
;             PG8_LDB(B0, 1, 0); PG8_LDB(B1, 1, 1); PG8_SCHED; PG8_LDA(At, 1, 0); PG8_STAGE(PG8_SA(0, 1), a2 + hstep, voffA);
;             PG8_WAIT_V(8); PG8_WAIT_L(0); PG8_BAR; PG8_MMA(0, 0, At, B0); PG8_MMA(0, 1, At, B1); PG8_BAR; PG8_SCHED;
	s_setprio 1
	s_waitcnt lgkmcnt(0)
	v_mfma_f32_16x16x32_bf16 v[106:109], v[82:85], v[174:177], v[106:109]
	v_mfma_f32_16x16x32_bf16 v[30:33], v[94:97], v[174:177], v[30:33]
	v_mfma_f32_16x16x32_bf16 v[98:101], v[82:85], v[198:201], v[98:101]
	v_mfma_f32_16x16x32_bf16 v[22:25], v[94:97], v[198:201], v[22:25]
	v_mfma_f32_16x16x32_bf16 v[78:81], v[82:85], v[206:209], v[78:81]
	v_mfma_f32_16x16x32_bf16 v[14:17], v[94:97], v[206:209], v[14:17]
	v_mfma_f32_16x16x32_bf16 v[70:73], v[82:85], v[238:241], v[70:73]
	v_mfma_f32_16x16x32_bf16 v[6:9], v[94:97], v[238:241], v[6:9]
	v_mfma_f32_16x16x32_bf16 v[106:109], v[86:89], v[194:197], v[106:109]
	v_mfma_f32_16x16x32_bf16 v[30:33], v[154:157], v[194:197], v[30:33]
	v_mfma_f32_16x16x32_bf16 v[98:101], v[86:89], v[202:205], v[98:101]
	v_mfma_f32_16x16x32_bf16 v[22:25], v[154:157], v[202:205], v[22:25]
	v_mfma_f32_16x16x32_bf16 v[78:81], v[86:89], v[234:237], v[78:81]
	v_mfma_f32_16x16x32_bf16 v[14:17], v[154:157], v[234:237], v[14:17]
	v_mfma_f32_16x16x32_bf16 v[70:73], v[86:89], v[242:245], v[70:73]
	v_mfma_f32_16x16x32_bf16 v[6:9], v[154:157], v[242:245], v[6:9]
	v_mfma_f32_16x16x32_bf16 v[26:29], v[166:169], v[174:177], v[26:29]
	v_mfma_f32_16x16x32_bf16 v[18:21], v[166:169], v[198:201], v[18:21]
	v_mfma_f32_16x16x32_bf16 v[74:77], v[158:161], v[206:209], v[74:77]
	v_mfma_f32_16x16x32_bf16 v[10:13], v[166:169], v[206:209], v[10:13]
	v_mfma_f32_16x16x32_bf16 v[66:69], v[158:161], v[238:241], v[66:69]
	v_mfma_f32_16x16x32_bf16 v[2:5], v[166:169], v[238:241], v[2:5]
	v_mfma_f32_16x16x32_bf16 v[82:85], v[158:161], v[174:177], v[102:105]
	v_mfma_f32_16x16x32_bf16 v[26:29], v[170:173], v[194:197], v[26:29]
	v_mfma_f32_16x16x32_bf16 v[86:89], v[158:161], v[198:201], v[90:93]
	v_mfma_f32_16x16x32_bf16 v[18:21], v[170:173], v[202:205], v[18:21]
	v_mfma_f32_16x16x32_bf16 v[74:77], v[162:165], v[234:237], v[74:77]
	v_mfma_f32_16x16x32_bf16 v[10:13], v[170:173], v[234:237], v[10:13]
	v_mfma_f32_16x16x32_bf16 v[66:69], v[162:165], v[242:245], v[66:69]
	v_mfma_f32_16x16x32_bf16 v[2:5], v[170:173], v[242:245], v[2:5]
	v_mfma_f32_16x16x32_bf16 v[82:85], v[162:165], v[194:197], v[82:85]
	v_mfma_f32_16x16x32_bf16 v[86:89], v[162:165], v[202:205], v[86:89]
	s_setprio 0
	s_barrier
	s_add_i32 s57, 0, 0x18000
	v_add_u32_e32 v0, s57, v213
	s_add_i32 s58, 0, 0x1c000
	ds_read_b128 v[90:93], v0
	ds_read_b128 v[94:97], v0 offset:1024
	ds_read_b128 v[102:105], v0 offset:2048
	ds_read_b128 v[154:157], v0 offset:3072
	v_add_u32_e32 v0, s58, v213
	ds_read_b128 v[158:161], v0
	ds_read_b128 v[162:165], v0 offset:1024
	ds_read_b128 v[166:169], v0 offset:2048
	ds_read_b128 v[170:173], v0 offset:3072
	s_add_u32 s54, s54, s12
	s_addc_u32 s55, s55, s13
	s_mov_b32 m0, s83
	v_lshl_add_u64 v[250:251], s[54:55], 0, v[148:149]
	ds_read_b128 v[174:177], v214 offset:32768
	ds_read_b128 v[194:197], v214 offset:33792
	ds_read_b128 v[198:201], v214 offset:34816
	ds_read_b128 v[202:205], v214 offset:35840
	ds_read_b128 v[206:209], v214 offset:36864
	ds_read_b128 v[234:237], v214 offset:37888
	ds_read_b128 v[238:241], v214 offset:38912
	ds_read_b128 v[242:245], v214 offset:39936
	global_load_lds_dwordx4 v[250:251], off
	v_lshl_add_u64 v[250:251], s[54:55], 0, v[144:145]
	s_mov_b32 m0, s84
	s_nop 0
	global_load_lds_dwordx4 v[250:251], off
	s_waitcnt vmcnt(8)
	s_waitcnt lgkmcnt(0)
	s_barrier
	s_setprio 1
	s_waitcnt lgkmcnt(0)
	v_mfma_f32_16x16x32_bf16 v[138:141], v[90:93], v[174:177], v[138:141]
	v_mfma_f32_16x16x32_bf16 v[62:65], v[102:105], v[174:177], v[62:65]
	v_mfma_f32_16x16x32_bf16 v[130:133], v[90:93], v[198:201], v[130:133]
	v_mfma_f32_16x16x32_bf16 v[54:57], v[102:105], v[198:201], v[54:57]
	v_mfma_f32_16x16x32_bf16 v[122:125], v[90:93], v[206:209], v[122:125]
	v_mfma_f32_16x16x32_bf16 v[46:49], v[102:105], v[206:209], v[46:49]
	v_mfma_f32_16x16x32_bf16 v[114:117], v[90:93], v[238:241], v[114:117]
	v_mfma_f32_16x16x32_bf16 v[38:41], v[102:105], v[238:241], v[38:41]
	v_mfma_f32_16x16x32_bf16 v[138:141], v[94:97], v[194:197], v[138:141]
	v_mfma_f32_16x16x32_bf16 v[62:65], v[154:157], v[194:197], v[62:65]
	v_mfma_f32_16x16x32_bf16 v[130:133], v[94:97], v[202:205], v[130:133]
	v_mfma_f32_16x16x32_bf16 v[54:57], v[154:157], v[202:205], v[54:57]
	v_mfma_f32_16x16x32_bf16 v[122:125], v[94:97], v[234:237], v[122:125]
	v_mfma_f32_16x16x32_bf16 v[46:49], v[154:157], v[234:237], v[46:49]
	v_mfma_f32_16x16x32_bf16 v[114:117], v[94:97], v[242:245], v[114:117]
	v_mfma_f32_16x16x32_bf16 v[38:41], v[154:157], v[242:245], v[38:41]
	v_mfma_f32_16x16x32_bf16 v[134:137], v[158:161], v[174:177], v[134:137]
	v_mfma_f32_16x16x32_bf16 v[58:61], v[166:169], v[174:177], v[58:61]
	v_mfma_f32_16x16x32_bf16 v[126:129], v[158:161], v[198:201], v[126:129]
	v_mfma_f32_16x16x32_bf16 v[50:53], v[166:169], v[198:201], v[50:53]
	v_mfma_f32_16x16x32_bf16 v[118:121], v[158:161], v[206:209], v[118:121]
	v_mfma_f32_16x16x32_bf16 v[42:45], v[166:169], v[206:209], v[42:45]
	v_mfma_f32_16x16x32_bf16 v[110:113], v[158:161], v[238:241], v[110:113]
	v_mfma_f32_16x16x32_bf16 v[34:37], v[166:169], v[238:241], v[34:37]
	v_mfma_f32_16x16x32_bf16 v[134:137], v[162:165], v[194:197], v[134:137]
	v_mfma_f32_16x16x32_bf16 v[58:61], v[170:173], v[194:197], v[58:61]
	v_mfma_f32_16x16x32_bf16 v[126:129], v[162:165], v[202:205], v[126:129]
	v_mfma_f32_16x16x32_bf16 v[50:53], v[170:173], v[202:205], v[50:53]
	v_mfma_f32_16x16x32_bf16 v[118:121], v[162:165], v[234:237], v[118:121]
	v_mfma_f32_16x16x32_bf16 v[42:45], v[170:173], v[234:237], v[42:45]
	v_mfma_f32_16x16x32_bf16 v[110:113], v[162:165], v[242:245], v[110:113]
	v_mfma_f32_16x16x32_bf16 v[34:37], v[170:173], v[242:245], v[34:37]
	s_setprio 0
	s_barrier
; #define PG8_STAGE(bufoff, gbase, voff) do { _Pragma("unroll") for (int _i = 0; _i < 2; ++_i) \
;         __builtin_amdgcn_global_load_lds((const unsigned*)((const char*)(gbase) + (voff)[_i]), (PG8_LAS unsigned*)(lds + (bufoff) + ldsw + _i * 8192), 16, 0, 0); } while (0)
; #define PG8_LDA(dst, b, h) do { _Pragma("unroll") for (int m = 0; m < 4; ++m) _Pragma("unroll") for (int k = 0; k < 2; ++k) dst[m][k] = *(const PG8_LAS bf16x8*)(lds + PG8_SA(b, h) + aoff + m * 2048 + k * 1024); } while (0)
; #define PG8_MMA(ai, bj, At, Bt) do { __builtin_amdgcn_s_setprio(1); _Pragma("unroll") for (int m = 0; m < 4; ++m) _Pragma("unroll") for (int n = 0; n < 2; ++n) _Pragma("unroll") for (int k = 0; k < 2; ++k) \
;         acc[ai][bj][m][n] = __builtin_amdgcn_mfma_f32_16x16x32_bf16(Bt[n][k], At[m][k], acc[ai][bj][m][n], 0, 0, 0); __builtin_amdgcn_s_setprio(0); } while (0)
; #define PG8_WAIT_V(n) asm volatile("s_waitcnt vmcnt(" #n ")" ::: "memory")
; #define PG8_WAIT_L(n) asm volatile("s_waitcnt lgkmcnt(" #n ")" ::: "memory")
; #define PG8_BAR __builtin_amdgcn_s_barrier()
; #define PG8_SCHED __builtin_amdgcn_sched_barrier(0)
; template <class Epi, class Sched, bool ALIGN_EPI = false, bool SP2 = false>
; __device__ __forceinline__ void gemm_phase(PG8_LAS unsigned char* lds, const Gemm g, const Sched& S, const Epi& E) {
;     ...
;         for (int t = 0; t < nt; t += 2) {
;     ...
;             PG8_LDA(At, 1, 1); PG8_STAGE(PG8_SB(1, 0), b3, voffB); PG8_STAGE(PG8_SB(1, 1), b3 + hstep, voffB); PG8_STAGE(PG8_SA(1, 0), a3, voffA);
;             PG8_WAIT_V(8); PG8_WAIT_L(0); PG8_BAR; PG8_MMA(1, 0, At, B0); PG8_MMA(1, 1, At, B1); PG8_BAR; PG8_SCHED;
	s_add_i32 s54, s57, s78
	v_lshl_add_u64 v[210:211], v[210:211], 0, s[52:53]
	s_mov_b32 m0, s54
	ds_read_b128 v[174:177], v214 offset:49152
	ds_read_b128 v[194:197], v214 offset:50176
	ds_read_b128 v[198:201], v214 offset:51200
	ds_read_b128 v[202:205], v214 offset:52224
	ds_read_b128 v[206:209], v214 offset:53248
	ds_read_b128 v[234:237], v214 offset:54272
	ds_read_b128 v[238:241], v214 offset:55296
	ds_read_b128 v[242:245], v214 offset:56320
	global_load_lds_dwordx4 v[210:211], off
	v_lshl_add_u64 v[210:211], v[216:217], 0, s[52:53]
	s_add_i32 m0, s54, 0x2000
	s_add_i32 s54, s58, s78
	global_load_lds_dwordx4 v[210:211], off
	v_lshl_add_u64 v[210:211], v[222:223], 0, s[52:53]
	s_mov_b32 m0, s54
	s_nop 0
	global_load_lds_dwordx4 v[210:211], off
	v_lshl_add_u64 v[210:211], v[232:233], 0, s[52:53]
	s_add_i32 m0, s54, 0x2000
	s_nop 0
	global_load_lds_dwordx4 v[210:211], off
	v_lshl_add_u64 v[210:211], v[246:247], 0, s[52:53]
	s_mov_b32 m0, s85
	s_nop 0
	global_load_lds_dwordx4 v[210:211], off
	v_lshl_add_u64 v[210:211], v[248:249], 0, s[52:53]
	s_mov_b32 m0, s86
	s_nop 0
	global_load_lds_dwordx4 v[210:211], off
	s_waitcnt vmcnt(8)
	s_waitcnt lgkmcnt(0)
	s_barrier
	s_setprio 1
	s_waitcnt lgkmcnt(0)
	v_mfma_f32_16x16x32_bf16 v[106:109], v[90:93], v[174:177], v[106:109]
	v_mfma_f32_16x16x32_bf16 v[30:33], v[102:105], v[174:177], v[30:33]
	v_mfma_f32_16x16x32_bf16 v[98:101], v[90:93], v[198:201], v[98:101]
	v_mfma_f32_16x16x32_bf16 v[22:25], v[102:105], v[198:201], v[22:25]
	v_mfma_f32_16x16x32_bf16 v[78:81], v[90:93], v[206:209], v[78:81]
	v_mfma_f32_16x16x32_bf16 v[14:17], v[102:105], v[206:209], v[14:17]
	v_mfma_f32_16x16x32_bf16 v[70:73], v[90:93], v[238:241], v[70:73]
	v_mfma_f32_16x16x32_bf16 v[6:9], v[102:105], v[238:241], v[6:9]
	v_mfma_f32_16x16x32_bf16 v[106:109], v[94:97], v[194:197], v[106:109]
	v_mfma_f32_16x16x32_bf16 v[30:33], v[154:157], v[194:197], v[30:33]
	v_mfma_f32_16x16x32_bf16 v[98:101], v[94:97], v[202:205], v[98:101]
	v_mfma_f32_16x16x32_bf16 v[22:25], v[154:157], v[202:205], v[22:25]
	v_mfma_f32_16x16x32_bf16 v[78:81], v[94:97], v[234:237], v[78:81]
	v_mfma_f32_16x16x32_bf16 v[14:17], v[154:157], v[234:237], v[14:17]
	v_mfma_f32_16x16x32_bf16 v[70:73], v[94:97], v[242:245], v[70:73]
	v_mfma_f32_16x16x32_bf16 v[6:9], v[154:157], v[242:245], v[6:9]
	v_mfma_f32_16x16x32_bf16 v[82:85], v[158:161], v[174:177], v[82:85]
	v_mfma_f32_16x16x32_bf16 v[102:105], v[162:165], v[194:197], v[82:85]
	v_mfma_f32_16x16x32_bf16 v[26:29], v[166:169], v[174:177], v[26:29]
	v_mfma_f32_16x16x32_bf16 v[82:85], v[158:161], v[198:201], v[86:89]
	v_mfma_f32_16x16x32_bf16 v[18:21], v[166:169], v[198:201], v[18:21]
	v_mfma_f32_16x16x32_bf16 v[74:77], v[158:161], v[206:209], v[74:77]
	v_mfma_f32_16x16x32_bf16 v[10:13], v[166:169], v[206:209], v[10:13]
	v_mfma_f32_16x16x32_bf16 v[66:69], v[158:161], v[238:241], v[66:69]
	v_mfma_f32_16x16x32_bf16 v[2:5], v[166:169], v[238:241], v[2:5]
	v_mfma_f32_16x16x32_bf16 v[26:29], v[170:173], v[194:197], v[26:29]
	v_mfma_f32_16x16x32_bf16 v[90:93], v[162:165], v[202:205], v[82:85]
	v_mfma_f32_16x16x32_bf16 v[18:21], v[170:173], v[202:205], v[18:21]
	v_mfma_f32_16x16x32_bf16 v[74:77], v[162:165], v[234:237], v[74:77]
	v_mfma_f32_16x16x32_bf16 v[10:13], v[170:173], v[234:237], v[10:13]
	v_mfma_f32_16x16x32_bf16 v[66:69], v[162:165], v[242:245], v[66:69]
	v_mfma_f32_16x16x32_bf16 v[2:5], v[170:173], v[242:245], v[2:5]
	s_setprio 0
	s_barrier
	s_add_u32 s6, s6, 0x100
	s_addc_u32 s7, s7, 0
	s_add_u32 s35, s35, 0x100
	s_addc_u32 s45, s45, 0
	s_cmp_ge_i32 s56, s87
	s_mov_b32 s54, s56
	s_cbranch_scc0 .LBB0_1463
	s_mov_b32 s66, 0x700000
	s_mov_b32 s56, 0xc00000
	s_mov_b32 s57, 0xe00000

;     __device__ bool next(int i, Unit& u) const { const int L = i * G + c; if (L >= 33 * 16) return false; const int pnv = L & 15, pm = L >> 4; u.pm = (pnv >> 1) * 33 + pm; u.pn = pnv; return true; }
;     __device__ bool next(int i, Unit& u) const { const int L = i * G + c; if (L >= npn * nsl) return false; u.pm = 32; u.pn = L % npn; u.k0 = (L / npn) * 256; return true; }
; #define PG8_STAGE(bufoff, gbase, voff) do { _Pragma("unroll") for (int _i = 0; _i < 2; ++_i) \
;         __builtin_amdgcn_global_load_lds((const unsigned*)((const char*)(gbase) + (voff)[_i]), (PG8_LAS unsigned*)(lds + (bufoff) + ldsw + _i * 8192), 16, 0, 0); } while (0)
; #define PG8_LDA(dst, b, h) do { _Pragma("unroll") for (int m = 0; m < 4; ++m) _Pragma("unroll") for (int k = 0; k < 2; ++k) dst[m][k] = *(const PG8_LAS bf16x8*)(lds + PG8_SA(b, h) + aoff + m * 2048 + k * 1024); } while (0)
; #define PG8_LDB(dst, b, h) do { _Pragma("unroll") for (int n = 0; n < 2; ++n) _Pragma("unroll") for (int k = 0; k < 2; ++k) dst[n][k] = *(const PG8_LAS bf16x8*)(lds + PG8_SB(b, h) + boff + n * 2048 + k * 1024); } while (0)
; template <class Epi, class Sched, bool ALIGN_EPI = false, bool SP2 = false>
; __device__ __forceinline__ void gemm_phase(PG8_LAS unsigned char* lds, const Gemm g, const Sched& S, const Epi& E) {
;     ...
;         const bool has_next = S.next(ui + 1, nxt);
;         const char* nA = has_next ? (const char*)g.A + (size_t)nxt.pm * tstep + (size_t)nxt.k0 * 2 : cA; const char* nB = has_next ? (const char*)g.Bt + (size_t)nxt.pn * tstep + (size_t)nxt.k0 * 2 : cB;
;         for (int t = 0; t < nt; t += 2) {
;             const bool last = (t == nt - 2);
;             const char* a1 = cA + (size_t)(t + 1) * kstep;
;             const char* a2 = last ? nA : cA + (size_t)(t + 2) * kstep; const char* b2 = last ? nB : cB + (size_t)(t + 2) * kstep;
;             const char* a3 = a2 + kstep; const char* b3 = b2 + kstep;
;             if (last && has_next) S.a_ready(nxt);
;             if constexpr (SP2) {
;             PG8_LDB(B0, 0, 0); PG8_LDB(B1, 0, 1); PG8_SCHED; PG8_LDA(At, 0, 0); PG8_STAGE(PG8_SA(1, 1), a1 + hstep, voffA);
;             PG8_WAIT_V(8); PG8_WAIT_L(0); PG8_BAR; PG8_MMA(0, 0, At, B0); PG8_MMA(0, 1, At, B1); PG8_BAR; PG8_SCHED;
;             PG8_LDA(At, 0, 1); PG8_STAGE(PG8_SB(0, 0), b2, voffB); PG8_STAGE(PG8_SB(0, 1), b2 + hstep, voffB); PG8_STAGE(PG8_SA(0, 0), a2, voffA);
.LBB0_1849:
	s_add_i32 s83, s54, 2
	s_add_u32 s84, s6, 0x80
	s_addc_u32 s55, s7, 0
	s_add_i32 s86, 0, 0x10000
	s_cmp_eq_u32 s73, s54
	s_cselect_b32 s55, s29, s55
	s_cselect_b32 s54, s28, s84
	s_cselect_b32 s85, s31, s59
	s_cselect_b32 s84, s30, s58
	s_add_i32 s87, 0, 0x14000
	v_add_u32_e32 v152, s86, v163
	v_add_u32_e32 v156, s87, v163
	ds_read_b128 v[140:143], v152
	ds_read_b128 v[144:147], v152 offset:1024
	ds_read_b128 v[148:151], v152 offset:2048
	ds_read_b128 v[152:155], v152 offset:3072
	ds_read_b128 v[166:169], v156
	ds_read_b128 v[170:173], v156 offset:1024
	ds_read_b128 v[174:177], v156 offset:2048
	ds_read_b128 v[194:197], v156 offset:3072
	v_lshl_add_u64 v[156:157], s[6:7], 0, v[136:137]
	s_add_i32 m0, s56, 0xc000
	ds_read_b128 v[198:201], v165
	ds_read_b128 v[202:205], v165 offset:1024
	ds_read_b128 v[206:209], v165 offset:2048
	ds_read_b128 v[210:213], v165 offset:3072
	ds_read_b128 v[214:217], v165 offset:4096
	ds_read_b128 v[234:237], v165 offset:5120
	ds_read_b128 v[238:241], v165 offset:6144
	ds_read_b128 v[242:245], v165 offset:7168
	global_load_lds_dwordx4 v[156:157], off
	v_lshl_add_u64 v[156:157], s[6:7], 0, v[138:139]
	s_add_i32 m0, s56, 0xe000
	s_nop 0
	global_load_lds_dwordx4 v[156:157], off
	s_waitcnt vmcnt(8)
	s_waitcnt lgkmcnt(0)
	s_barrier
	s_setprio 1
	s_waitcnt lgkmcnt(0)
	v_mfma_f32_16x16x32_bf16 v[122:125], v[140:143], v[198:201], v[122:125]
	v_mfma_f32_16x16x32_bf16 v[114:117], v[148:151], v[198:201], v[114:117]
	v_mfma_f32_16x16x32_bf16 v[106:109], v[140:143], v[206:209], v[106:109]
	v_mfma_f32_16x16x32_bf16 v[98:101], v[148:151], v[206:209], v[98:101]
	v_mfma_f32_16x16x32_bf16 v[90:93], v[140:143], v[214:217], v[90:93]
	v_mfma_f32_16x16x32_bf16 v[82:85], v[148:151], v[214:217], v[82:85]
	v_mfma_f32_16x16x32_bf16 v[74:77], v[140:143], v[238:241], v[74:77]
	v_mfma_f32_16x16x32_bf16 v[66:69], v[148:151], v[238:241], v[66:69]
	v_mfma_f32_16x16x32_bf16 v[122:125], v[144:147], v[202:205], v[122:125]
	v_mfma_f32_16x16x32_bf16 v[114:117], v[152:155], v[202:205], v[114:117]
	v_mfma_f32_16x16x32_bf16 v[106:109], v[144:147], v[210:213], v[106:109]
	v_mfma_f32_16x16x32_bf16 v[98:101], v[152:155], v[210:213], v[98:101]
	v_mfma_f32_16x16x32_bf16 v[90:93], v[144:147], v[234:237], v[90:93]
	v_mfma_f32_16x16x32_bf16 v[82:85], v[152:155], v[234:237], v[82:85]
	v_mfma_f32_16x16x32_bf16 v[74:77], v[144:147], v[242:245], v[74:77]
	v_mfma_f32_16x16x32_bf16 v[66:69], v[152:155], v[242:245], v[66:69]
	v_mfma_f32_16x16x32_bf16 v[126:129], v[166:169], v[198:201], v[126:129]
	v_mfma_f32_16x16x32_bf16 v[118:121], v[174:177], v[198:201], v[118:121]
	v_mfma_f32_16x16x32_bf16 v[110:113], v[166:169], v[206:209], v[110:113]
	v_mfma_f32_16x16x32_bf16 v[102:105], v[174:177], v[206:209], v[102:105]
	v_mfma_f32_16x16x32_bf16 v[94:97], v[166:169], v[214:217], v[94:97]
	v_mfma_f32_16x16x32_bf16 v[86:89], v[174:177], v[214:217], v[86:89]
	v_mfma_f32_16x16x32_bf16 v[78:81], v[166:169], v[238:241], v[78:81]
	v_mfma_f32_16x16x32_bf16 v[70:73], v[174:177], v[238:241], v[70:73]
	v_mfma_f32_16x16x32_bf16 v[126:129], v[170:173], v[202:205], v[126:129]
	v_mfma_f32_16x16x32_bf16 v[118:121], v[194:197], v[202:205], v[118:121]
	v_mfma_f32_16x16x32_bf16 v[110:113], v[170:173], v[210:213], v[110:113]
	v_mfma_f32_16x16x32_bf16 v[102:105], v[194:197], v[210:213], v[102:105]
	v_mfma_f32_16x16x32_bf16 v[94:97], v[170:173], v[234:237], v[94:97]
	v_mfma_f32_16x16x32_bf16 v[86:89], v[194:197], v[234:237], v[86:89]
	v_mfma_f32_16x16x32_bf16 v[78:81], v[170:173], v[242:245], v[78:81]
	v_mfma_f32_16x16x32_bf16 v[70:73], v[194:197], v[242:245], v[70:73]
	s_setprio 0
	s_barrier
	s_add_i32 s86, s86, s47
	v_lshl_add_u64 v[156:157], s[84:85], 0, v[0:1]
	s_mov_b32 m0, s86
	ds_read_b128 v[198:201], v165 offset:16384
	ds_read_b128 v[202:205], v165 offset:17408
	ds_read_b128 v[206:209], v165 offset:18432
	ds_read_b128 v[210:213], v165 offset:19456
	ds_read_b128 v[214:217], v165 offset:20480
	ds_read_b128 v[234:237], v165 offset:21504
	ds_read_b128 v[238:241], v165 offset:22528
	ds_read_b128 v[242:245], v165 offset:23552
	global_load_lds_dwordx4 v[156:157], off
	s_add_i32 m0, s86, 0x2000
	v_lshl_add_u64 v[222:223], s[84:85], 0, v[134:135]
	s_add_u32 s84, s84, s8
	s_addc_u32 s85, s85, s9
	s_add_i32 s86, s87, s47
	global_load_lds_dwordx4 v[222:223], off
	v_lshl_add_u64 v[232:233], s[84:85], 0, v[0:1]
	s_mov_b32 m0, s86
	v_lshl_add_u64 v[246:247], s[84:85], 0, v[134:135]
	global_load_lds_dwordx4 v[232:233], off
	s_add_i32 m0, s86, 0x2000
	v_lshl_add_u64 v[248:249], s[54:55], 0, v[130:131]
	global_load_lds_dwordx4 v[246:247], off
	s_mov_b32 m0, s56
	v_lshl_add_u64 v[250:251], s[54:55], 0, v[132:133]
	global_load_lds_dwordx4 v[248:249], off
	s_mov_b32 m0, s57
	s_nop 0
	global_load_lds_dwordx4 v[250:251], off
	s_waitcnt vmcnt(8)
	s_waitcnt lgkmcnt(0)
	s_barrier
; #define PG8_STAGE(bufoff, gbase, voff) do { _Pragma("unroll") for (int _i = 0; _i < 2; ++_i) \
;         __builtin_amdgcn_global_load_lds((const unsigned*)((const char*)(gbase) + (voff)[_i]), (PG8_LAS unsigned*)(lds + (bufoff) + ldsw + _i * 8192), 16, 0, 0); } while (0)
; #define PG8_LDA(dst, b, h) do { _Pragma("unroll") for (int m = 0; m < 4; ++m) _Pragma("unroll") for (int k = 0; k < 2; ++k) dst[m][k] = *(const PG8_LAS bf16x8*)(lds + PG8_SA(b, h) + aoff + m * 2048 + k * 1024); } while (0)
; #define PG8_LDB(dst, b, h) do { _Pragma("unroll") for (int n = 0; n < 2; ++n) _Pragma("unroll") for (int k = 0; k < 2; ++k) dst[n][k] = *(const PG8_LAS bf16x8*)(lds + PG8_SB(b, h) + boff + n * 2048 + k * 1024); } while (0)
; #define PG8_MMA(ai, bj, At, Bt) do { __builtin_amdgcn_s_setprio(1); _Pragma("unroll") for (int m = 0; m < 4; ++m) _Pragma("unroll") for (int n = 0; n < 2; ++n) _Pragma("unroll") for (int k = 0; k < 2; ++k) \
;         acc[ai][bj][m][n] = __builtin_amdgcn_mfma_f32_16x16x32_bf16(Bt[n][k], At[m][k], acc[ai][bj][m][n], 0, 0, 0); __builtin_amdgcn_s_setprio(0); } while (0)
; #define PG8_WAIT_V(n) asm volatile("s_waitcnt vmcnt(" #n ")" ::: "memory")
; #define PG8_WAIT_L(n) asm volatile("s_waitcnt lgkmcnt(" #n ")" ::: "memory")
; #define PG8_BAR __builtin_amdgcn_s_barrier()
; #define PG8_SCHED __builtin_amdgcn_sched_barrier(0)
; template <class Epi, class Sched, bool ALIGN_EPI = false, bool SP2 = false>
; __device__ __forceinline__ void gemm_phase(PG8_LAS unsigned char* lds, const Gemm g, const Sched& S, const Epi& E) {
;     ...
;             PG8_WAIT_V(8); PG8_WAIT_L(0); PG8_BAR; PG8_MMA(1, 0, At, B0); PG8_MMA(1, 1, At, B1); PG8_BAR; PG8_SCHED;
;             PG8_LDB(B0, 1, 0); PG8_LDB(B1, 1, 1); PG8_SCHED; PG8_LDA(At, 1, 0); PG8_STAGE(PG8_SA(0, 1), a2 + hstep, voffA);
;             PG8_WAIT_V(8); PG8_WAIT_L(0); PG8_BAR; PG8_MMA(0, 0, At, B0); PG8_MMA(0, 1, At, B1); PG8_BAR; PG8_SCHED;
	s_setprio 1
	s_waitcnt lgkmcnt(0)
	v_mfma_f32_16x16x32_bf16 v[58:61], v[140:143], v[198:201], v[58:61]
	v_mfma_f32_16x16x32_bf16 v[50:53], v[148:151], v[198:201], v[50:53]
	v_mfma_f32_16x16x32_bf16 v[42:45], v[140:143], v[206:209], v[42:45]
	v_mfma_f32_16x16x32_bf16 v[34:37], v[148:151], v[206:209], v[34:37]
	v_mfma_f32_16x16x32_bf16 v[26:29], v[140:143], v[214:217], v[26:29]
	v_mfma_f32_16x16x32_bf16 v[18:21], v[148:151], v[214:217], v[18:21]
	v_mfma_f32_16x16x32_bf16 v[10:13], v[140:143], v[238:241], v[10:13]
	v_mfma_f32_16x16x32_bf16 v[6:9], v[148:151], v[238:241], v[6:9]
	v_mfma_f32_16x16x32_bf16 v[58:61], v[144:147], v[202:205], v[58:61]
	v_mfma_f32_16x16x32_bf16 v[50:53], v[152:155], v[202:205], v[50:53]
	v_mfma_f32_16x16x32_bf16 v[42:45], v[144:147], v[210:213], v[42:45]
	v_mfma_f32_16x16x32_bf16 v[34:37], v[152:155], v[210:213], v[34:37]
	v_mfma_f32_16x16x32_bf16 v[26:29], v[144:147], v[234:237], v[26:29]
	v_mfma_f32_16x16x32_bf16 v[18:21], v[152:155], v[234:237], v[18:21]
	v_mfma_f32_16x16x32_bf16 v[10:13], v[144:147], v[242:245], v[10:13]
	v_mfma_f32_16x16x32_bf16 v[6:9], v[152:155], v[242:245], v[6:9]
	v_mfma_f32_16x16x32_bf16 v[62:65], v[166:169], v[198:201], v[62:65]
	v_mfma_f32_16x16x32_bf16 v[54:57], v[174:177], v[198:201], v[54:57]
	v_mfma_f32_16x16x32_bf16 v[46:49], v[166:169], v[206:209], v[46:49]
	v_mfma_f32_16x16x32_bf16 v[38:41], v[174:177], v[206:209], v[38:41]
	v_mfma_f32_16x16x32_bf16 v[30:33], v[166:169], v[214:217], v[30:33]
	v_mfma_f32_16x16x32_bf16 v[22:25], v[174:177], v[214:217], v[22:25]
	v_mfma_f32_16x16x32_bf16 v[14:17], v[166:169], v[238:241], v[14:17]
	v_mfma_f32_16x16x32_bf16 v[2:5], v[174:177], v[238:241], v[2:5]
	v_mfma_f32_16x16x32_bf16 v[62:65], v[170:173], v[202:205], v[62:65]
	v_mfma_f32_16x16x32_bf16 v[54:57], v[194:197], v[202:205], v[54:57]
	v_mfma_f32_16x16x32_bf16 v[46:49], v[170:173], v[210:213], v[46:49]
	v_mfma_f32_16x16x32_bf16 v[38:41], v[194:197], v[210:213], v[38:41]
	v_mfma_f32_16x16x32_bf16 v[30:33], v[170:173], v[234:237], v[30:33]
	v_mfma_f32_16x16x32_bf16 v[22:25], v[194:197], v[234:237], v[22:25]
	v_mfma_f32_16x16x32_bf16 v[14:17], v[170:173], v[242:245], v[14:17]
	v_mfma_f32_16x16x32_bf16 v[2:5], v[194:197], v[242:245], v[2:5]
	s_setprio 0
	s_barrier
	s_add_i32 s84, 0, 0x18000
	s_add_i32 s85, 0, 0x1c000
	v_add_u32_e32 v152, s84, v163
	v_add_u32_e32 v158, s85, v163
	ds_read_b128 v[140:143], v152
	ds_read_b128 v[144:147], v152 offset:1024
	ds_read_b128 v[148:151], v152 offset:2048
	ds_read_b128 v[152:155], v152 offset:3072
	ds_read_b128 v[166:169], v158
	ds_read_b128 v[170:173], v158 offset:1024
	ds_read_b128 v[174:177], v158 offset:2048
	ds_read_b128 v[194:197], v158 offset:3072
	s_add_u32 s54, s54, s8
	s_addc_u32 s55, s55, s9
	s_mov_b32 m0, s66
	v_lshl_add_u64 v[252:253], s[54:55], 0, v[130:131]
	ds_read_b128 v[198:201], v165 offset:32768
	ds_read_b128 v[202:205], v165 offset:33792
	ds_read_b128 v[206:209], v165 offset:34816
	ds_read_b128 v[210:213], v165 offset:35840
	ds_read_b128 v[214:217], v165 offset:36864
	ds_read_b128 v[234:237], v165 offset:37888
	ds_read_b128 v[238:241], v165 offset:38912
	ds_read_b128 v[242:245], v165 offset:39936
	global_load_lds_dwordx4 v[252:253], off
	v_lshl_add_u64 v[252:253], s[54:55], 0, v[132:133]
	s_mov_b32 m0, s67
	s_nop 0
	global_load_lds_dwordx4 v[252:253], off
	s_waitcnt vmcnt(8)
	s_waitcnt lgkmcnt(0)
	s_barrier
	s_setprio 1
	s_waitcnt lgkmcnt(0)
	v_mfma_f32_16x16x32_bf16 v[122:125], v[140:143], v[198:201], v[122:125]
	v_mfma_f32_16x16x32_bf16 v[114:117], v[148:151], v[198:201], v[114:117]
	v_mfma_f32_16x16x32_bf16 v[106:109], v[140:143], v[206:209], v[106:109]
	v_mfma_f32_16x16x32_bf16 v[98:101], v[148:151], v[206:209], v[98:101]
	v_mfma_f32_16x16x32_bf16 v[90:93], v[140:143], v[214:217], v[90:93]
	v_mfma_f32_16x16x32_bf16 v[82:85], v[148:151], v[214:217], v[82:85]
	v_mfma_f32_16x16x32_bf16 v[74:77], v[140:143], v[238:241], v[74:77]
	v_mfma_f32_16x16x32_bf16 v[66:69], v[148:151], v[238:241], v[66:69]
	v_mfma_f32_16x16x32_bf16 v[122:125], v[144:147], v[202:205], v[122:125]
	v_mfma_f32_16x16x32_bf16 v[114:117], v[152:155], v[202:205], v[114:117]
	v_mfma_f32_16x16x32_bf16 v[106:109], v[144:147], v[210:213], v[106:109]
	v_mfma_f32_16x16x32_bf16 v[98:101], v[152:155], v[210:213], v[98:101]
	v_mfma_f32_16x16x32_bf16 v[90:93], v[144:147], v[234:237], v[90:93]
	v_mfma_f32_16x16x32_bf16 v[82:85], v[152:155], v[234:237], v[82:85]
	v_mfma_f32_16x16x32_bf16 v[74:77], v[144:147], v[242:245], v[74:77]
	v_mfma_f32_16x16x32_bf16 v[66:69], v[152:155], v[242:245], v[66:69]
	v_mfma_f32_16x16x32_bf16 v[126:129], v[166:169], v[198:201], v[126:129]
	v_mfma_f32_16x16x32_bf16 v[118:121], v[174:177], v[198:201], v[118:121]
	v_mfma_f32_16x16x32_bf16 v[110:113], v[166:169], v[206:209], v[110:113]
	v_mfma_f32_16x16x32_bf16 v[102:105], v[174:177], v[206:209], v[102:105]
	v_mfma_f32_16x16x32_bf16 v[94:97], v[166:169], v[214:217], v[94:97]
	v_mfma_f32_16x16x32_bf16 v[86:89], v[174:177], v[214:217], v[86:89]
	v_mfma_f32_16x16x32_bf16 v[78:81], v[166:169], v[238:241], v[78:81]
	v_mfma_f32_16x16x32_bf16 v[70:73], v[174:177], v[238:241], v[70:73]
	v_mfma_f32_16x16x32_bf16 v[126:129], v[170:173], v[202:205], v[126:129]
	v_mfma_f32_16x16x32_bf16 v[118:121], v[194:197], v[202:205], v[118:121]
	v_mfma_f32_16x16x32_bf16 v[110:113], v[170:173], v[210:213], v[110:113]
	v_mfma_f32_16x16x32_bf16 v[102:105], v[194:197], v[210:213], v[102:105]
	v_mfma_f32_16x16x32_bf16 v[94:97], v[170:173], v[234:237], v[94:97]
	v_mfma_f32_16x16x32_bf16 v[86:89], v[194:197], v[234:237], v[86:89]
	v_mfma_f32_16x16x32_bf16 v[78:81], v[170:173], v[242:245], v[78:81]
	v_mfma_f32_16x16x32_bf16 v[70:73], v[194:197], v[242:245], v[70:73]
	s_setprio 0
	s_barrier
; #define PG8_STAGE(bufoff, gbase, voff) do { _Pragma("unroll") for (int _i = 0; _i < 2; ++_i) \
;         __builtin_amdgcn_global_load_lds((const unsigned*)((const char*)(gbase) + (voff)[_i]), (PG8_LAS unsigned*)(lds + (bufoff) + ldsw + _i * 8192), 16, 0, 0); } while (0)
; #define PG8_LDA(dst, b, h) do { _Pragma("unroll") for (int m = 0; m < 4; ++m) _Pragma("unroll") for (int k = 0; k < 2; ++k) dst[m][k] = *(const PG8_LAS bf16x8*)(lds + PG8_SA(b, h) + aoff + m * 2048 + k * 1024); } while (0)
; #define PG8_MMA(ai, bj, At, Bt) do { __builtin_amdgcn_s_setprio(1); _Pragma("unroll") for (int m = 0; m < 4; ++m) _Pragma("unroll") for (int n = 0; n < 2; ++n) _Pragma("unroll") for (int k = 0; k < 2; ++k) \
;         acc[ai][bj][m][n] = __builtin_amdgcn_mfma_f32_16x16x32_bf16(Bt[n][k], At[m][k], acc[ai][bj][m][n], 0, 0, 0); __builtin_amdgcn_s_setprio(0); } while (0)
; #define PG8_WAIT_V(n) asm volatile("s_waitcnt vmcnt(" #n ")" ::: "memory")
; #define PG8_WAIT_L(n) asm volatile("s_waitcnt lgkmcnt(" #n ")" ::: "memory")
; #define PG8_BAR __builtin_amdgcn_s_barrier()
; #define PG8_SCHED __builtin_amdgcn_sched_barrier(0)
; template <class Epi, class Sched, bool ALIGN_EPI = false, bool SP2 = false>
; __device__ __forceinline__ void gemm_phase(PG8_LAS unsigned char* lds, const Gemm g, const Sched& S, const Epi& E) {
;     ...
;         for (int t = 0; t < nt; t += 2) {
;     ...
;             PG8_LDA(At, 1, 1); PG8_STAGE(PG8_SB(1, 0), b3, voffB); PG8_STAGE(PG8_SB(1, 1), b3 + hstep, voffB); PG8_STAGE(PG8_SA(1, 0), a3, voffA);
;             PG8_WAIT_V(8); PG8_WAIT_L(0); PG8_BAR; PG8_MMA(1, 0, At, B0); PG8_MMA(1, 1, At, B1); PG8_BAR; PG8_SCHED;
	s_add_i32 s54, s84, s47
	v_lshl_add_u64 v[156:157], v[156:157], 0, s[52:53]
	s_mov_b32 m0, s54
	ds_read_b128 v[198:201], v165 offset:49152
	ds_read_b128 v[202:205], v165 offset:50176
	ds_read_b128 v[206:209], v165 offset:51200
	ds_read_b128 v[210:213], v165 offset:52224
	ds_read_b128 v[214:217], v165 offset:53248
	ds_read_b128 v[234:237], v165 offset:54272
	ds_read_b128 v[238:241], v165 offset:55296
	ds_read_b128 v[242:245], v165 offset:56320
	global_load_lds_dwordx4 v[156:157], off
	v_lshl_add_u64 v[156:157], v[222:223], 0, s[52:53]
	s_add_i32 m0, s54, 0x2000
	s_add_i32 s54, s85, s47
	global_load_lds_dwordx4 v[156:157], off
	v_lshl_add_u64 v[156:157], v[232:233], 0, s[52:53]
	s_mov_b32 m0, s54
	s_nop 0
	global_load_lds_dwordx4 v[156:157], off
	v_lshl_add_u64 v[156:157], v[246:247], 0, s[52:53]
	s_add_i32 m0, s54, 0x2000
	s_nop 0
	global_load_lds_dwordx4 v[156:157], off
	v_lshl_add_u64 v[156:157], v[248:249], 0, s[52:53]
	s_mov_b32 m0, s68
	s_nop 0
	global_load_lds_dwordx4 v[156:157], off
	v_lshl_add_u64 v[156:157], v[250:251], 0, s[52:53]
	s_mov_b32 m0, s69
	s_nop 0
	global_load_lds_dwordx4 v[156:157], off
	s_waitcnt vmcnt(8)
	s_waitcnt lgkmcnt(0)
	s_barrier
	s_setprio 1
	s_waitcnt lgkmcnt(0)
	v_mfma_f32_16x16x32_bf16 v[58:61], v[140:143], v[198:201], v[58:61]
	v_mfma_f32_16x16x32_bf16 v[50:53], v[148:151], v[198:201], v[50:53]
	v_mfma_f32_16x16x32_bf16 v[42:45], v[140:143], v[206:209], v[42:45]
	v_mfma_f32_16x16x32_bf16 v[34:37], v[148:151], v[206:209], v[34:37]
	v_mfma_f32_16x16x32_bf16 v[26:29], v[140:143], v[214:217], v[26:29]
	v_mfma_f32_16x16x32_bf16 v[18:21], v[148:151], v[214:217], v[18:21]
	v_mfma_f32_16x16x32_bf16 v[10:13], v[140:143], v[238:241], v[10:13]
	v_mfma_f32_16x16x32_bf16 v[6:9], v[148:151], v[238:241], v[6:9]
	v_mfma_f32_16x16x32_bf16 v[58:61], v[144:147], v[202:205], v[58:61]
	v_mfma_f32_16x16x32_bf16 v[50:53], v[152:155], v[202:205], v[50:53]
	v_mfma_f32_16x16x32_bf16 v[42:45], v[144:147], v[210:213], v[42:45]
	v_mfma_f32_16x16x32_bf16 v[34:37], v[152:155], v[210:213], v[34:37]
	v_mfma_f32_16x16x32_bf16 v[26:29], v[144:147], v[234:237], v[26:29]
	v_mfma_f32_16x16x32_bf16 v[18:21], v[152:155], v[234:237], v[18:21]
	v_mfma_f32_16x16x32_bf16 v[10:13], v[144:147], v[242:245], v[10:13]
	v_mfma_f32_16x16x32_bf16 v[6:9], v[152:155], v[242:245], v[6:9]
	v_mfma_f32_16x16x32_bf16 v[62:65], v[166:169], v[198:201], v[62:65]
	v_mfma_f32_16x16x32_bf16 v[54:57], v[174:177], v[198:201], v[54:57]
	v_mfma_f32_16x16x32_bf16 v[46:49], v[166:169], v[206:209], v[46:49]
	v_mfma_f32_16x16x32_bf16 v[38:41], v[174:177], v[206:209], v[38:41]
	v_mfma_f32_16x16x32_bf16 v[30:33], v[166:169], v[214:217], v[30:33]
	v_mfma_f32_16x16x32_bf16 v[22:25], v[174:177], v[214:217], v[22:25]
	v_mfma_f32_16x16x32_bf16 v[14:17], v[166:169], v[238:241], v[14:17]
	v_mfma_f32_16x16x32_bf16 v[2:5], v[174:177], v[238:241], v[2:5]
	v_mfma_f32_16x16x32_bf16 v[62:65], v[170:173], v[202:205], v[62:65]
	v_mfma_f32_16x16x32_bf16 v[54:57], v[194:197], v[202:205], v[54:57]
	v_mfma_f32_16x16x32_bf16 v[46:49], v[170:173], v[210:213], v[46:49]
	v_mfma_f32_16x16x32_bf16 v[38:41], v[194:197], v[210:213], v[38:41]
	v_mfma_f32_16x16x32_bf16 v[30:33], v[170:173], v[234:237], v[30:33]
	v_mfma_f32_16x16x32_bf16 v[22:25], v[194:197], v[234:237], v[22:25]
	v_mfma_f32_16x16x32_bf16 v[14:17], v[170:173], v[242:245], v[14:17]
	v_mfma_f32_16x16x32_bf16 v[2:5], v[194:197], v[242:245], v[2:5]
	s_setprio 0
	s_barrier
	s_add_u32 s6, s6, 0x100
	s_addc_u32 s7, s7, 0
	s_add_u32 s58, s58, 0x100
	s_addc_u32 s59, s59, 0
	s_cmp_ge_i32 s83, s70
	s_mov_b32 s54, s83
	s_cbranch_scc0 .LBB0_1849
